# mid-block s_setprio 0/1 yield pair removed from all MFMA blocks (32 MFMAs back to back)
# baseline (speedup 1.0000x reference)
.LBB0_179:
	ds_read_b128 v[144:147], v153
	ds_read_b128 v[156:159], v153 offset:1024
	ds_read_b128 v[162:165], v153 offset:2048
	ds_read_b128 v[166:169], v153 offset:3072
	ds_read_b128 v[170:173], v154
	ds_read_b128 v[174:177], v154 offset:1024
	ds_read_b128 v[178:181], v154 offset:2048
	ds_read_b128 v[182:185], v154 offset:3072
	s_add_u32 s70, s68, 0xfff80080
	s_addc_u32 s71, s69, -1
	s_cmp_eq_u32 s88, 28
	s_cselect_b32 s73, s1, s71
	s_cselect_b32 s72, s3, s70
	s_cselect_b32 s71, s59, s87
	s_cselect_b32 s70, s61, s86
	v_lshl_add_u64 v[148:149], s[68:69], 0, v[136:137]
	s_add_i32 m0, s29, 0xc000
	ds_read_b128 v[186:189], v155
	ds_read_b128 v[190:193], v155 offset:1024
	ds_read_b128 v[194:197], v155 offset:2048
	ds_read_b128 v[198:201], v155 offset:3072
	ds_read_b128 v[202:205], v155 offset:4096
	ds_read_b128 v[206:209], v155 offset:5120
	ds_read_b128 v[214:217], v155 offset:6144
	ds_read_b128 v[218:221], v155 offset:7168
	global_load_lds_dwordx4 v[148:149], off
	v_lshl_add_u64 v[148:149], s[68:69], 0, v[138:139]
	s_add_i32 m0, s29, 0xe000
	s_nop 0
	global_load_lds_dwordx4 v[148:149], off
	s_waitcnt vmcnt(8)
	s_waitcnt lgkmcnt(0)
	s_setprio 1
	s_barrier
	v_mfma_f32_16x16x32_bf16 v[124:127], v[144:147], v[186:189], v[124:127]
	v_mfma_f32_16x16x32_bf16 v[120:123], v[162:165], v[186:189], v[120:123]
	v_mfma_f32_16x16x32_bf16 v[108:111], v[144:147], v[194:197], v[108:111]
	v_mfma_f32_16x16x32_bf16 v[104:107], v[162:165], v[194:197], v[104:107]
	v_mfma_f32_16x16x32_bf16 v[92:95], v[144:147], v[202:205], v[92:95]
	v_mfma_f32_16x16x32_bf16 v[88:91], v[162:165], v[202:205], v[88:91]
	v_mfma_f32_16x16x32_bf16 v[76:79], v[144:147], v[214:217], v[76:79]
	v_mfma_f32_16x16x32_bf16 v[72:75], v[162:165], v[214:217], v[72:75]
	v_mfma_f32_16x16x32_bf16 v[124:127], v[156:159], v[190:193], v[124:127]
	v_mfma_f32_16x16x32_bf16 v[120:123], v[166:169], v[190:193], v[120:123]
	v_mfma_f32_16x16x32_bf16 v[108:111], v[156:159], v[198:201], v[108:111]
	v_mfma_f32_16x16x32_bf16 v[104:107], v[166:169], v[198:201], v[104:107]
	v_mfma_f32_16x16x32_bf16 v[92:95], v[156:159], v[206:209], v[92:95]
	v_mfma_f32_16x16x32_bf16 v[88:91], v[166:169], v[206:209], v[88:91]
	v_mfma_f32_16x16x32_bf16 v[76:79], v[156:159], v[218:221], v[76:79]
	v_mfma_f32_16x16x32_bf16 v[72:75], v[166:169], v[218:221], v[72:75]
	v_mfma_f32_16x16x32_bf16 v[116:119], v[170:173], v[186:189], v[116:119]
	v_mfma_f32_16x16x32_bf16 v[112:115], v[178:181], v[186:189], v[112:115]
	v_mfma_f32_16x16x32_bf16 v[100:103], v[170:173], v[194:197], v[100:103]
	v_mfma_f32_16x16x32_bf16 v[96:99], v[178:181], v[194:197], v[96:99]
	v_mfma_f32_16x16x32_bf16 v[84:87], v[170:173], v[202:205], v[84:87]
	v_mfma_f32_16x16x32_bf16 v[80:83], v[178:181], v[202:205], v[80:83]
	v_mfma_f32_16x16x32_bf16 v[68:71], v[170:173], v[214:217], v[68:71]
	v_mfma_f32_16x16x32_bf16 v[64:67], v[178:181], v[214:217], v[64:67]
	v_mfma_f32_16x16x32_bf16 v[116:119], v[174:177], v[190:193], v[116:119]
	v_mfma_f32_16x16x32_bf16 v[112:115], v[182:185], v[190:193], v[112:115]
	v_mfma_f32_16x16x32_bf16 v[100:103], v[174:177], v[198:201], v[100:103]
	v_mfma_f32_16x16x32_bf16 v[96:99], v[182:185], v[198:201], v[96:99]
	v_mfma_f32_16x16x32_bf16 v[84:87], v[174:177], v[206:209], v[84:87]
	v_mfma_f32_16x16x32_bf16 v[80:83], v[182:185], v[206:209], v[80:83]
	v_mfma_f32_16x16x32_bf16 v[68:71], v[174:177], v[218:221], v[68:71]
	v_mfma_f32_16x16x32_bf16 v[64:67], v[182:185], v[218:221], v[64:67]
	s_barrier
	s_setprio 0
	s_add_i32 s89, s79, s28
	v_lshl_add_u64 v[148:149], s[70:71], 0, v[132:133]
	s_mov_b32 m0, s89
	ds_read_b128 v[186:189], v155 offset:16384
	ds_read_b128 v[190:193], v155 offset:17408
	ds_read_b128 v[194:197], v155 offset:18432
	ds_read_b128 v[198:201], v155 offset:19456
	ds_read_b128 v[202:205], v155 offset:20480
	ds_read_b128 v[206:209], v155 offset:21504
	ds_read_b128 v[214:217], v155 offset:22528
	ds_read_b128 v[218:221], v155 offset:23552
	global_load_lds_dwordx4 v[148:149], off
	s_add_i32 m0, s89, 0x2000
	s_add_u32 s90, s70, 0x80000
	v_lshl_add_u64 v[210:211], s[70:71], 0, v[128:129]
	s_addc_u32 s91, s71, 0
	s_add_i32 s89, s80, s28
	global_load_lds_dwordx4 v[210:211], off
	v_lshl_add_u64 v[222:223], s[90:91], 0, v[132:133]
	s_mov_b32 m0, s89
	v_lshl_add_u64 v[224:225], s[72:73], 0, v[130:131]
	global_load_lds_dwordx4 v[222:223], off
	v_lshl_add_u64 v[222:223], s[90:91], 0, v[128:129]
	s_add_i32 m0, s89, 0x2000
	s_nop 0
	global_load_lds_dwordx4 v[222:223], off
	v_lshl_add_u64 v[222:223], s[72:73], 0, v[134:135]
	s_mov_b32 m0, s29
	s_nop 0
	global_load_lds_dwordx4 v[222:223], off
	s_mov_b32 m0, s30
	s_nop 0
	global_load_lds_dwordx4 v[224:225], off
	s_waitcnt vmcnt(8)
	s_waitcnt lgkmcnt(0)
	s_setprio 1
	s_barrier
	v_mfma_f32_16x16x32_bf16 v[60:63], v[144:147], v[186:189], v[60:63]
	v_mfma_f32_16x16x32_bf16 v[56:59], v[162:165], v[186:189], v[56:59]
	v_mfma_f32_16x16x32_bf16 v[44:47], v[144:147], v[194:197], v[44:47]
	v_mfma_f32_16x16x32_bf16 v[40:43], v[162:165], v[194:197], v[40:43]
	v_mfma_f32_16x16x32_bf16 v[28:31], v[144:147], v[202:205], v[28:31]
	v_mfma_f32_16x16x32_bf16 v[24:27], v[162:165], v[202:205], v[24:27]
	v_mfma_f32_16x16x32_bf16 v[12:15], v[144:147], v[214:217], v[12:15]
	v_mfma_f32_16x16x32_bf16 v[8:11], v[162:165], v[214:217], v[8:11]
	v_mfma_f32_16x16x32_bf16 v[60:63], v[156:159], v[190:193], v[60:63]
	v_mfma_f32_16x16x32_bf16 v[56:59], v[166:169], v[190:193], v[56:59]
	v_mfma_f32_16x16x32_bf16 v[44:47], v[156:159], v[198:201], v[44:47]
	v_mfma_f32_16x16x32_bf16 v[40:43], v[166:169], v[198:201], v[40:43]
	v_mfma_f32_16x16x32_bf16 v[28:31], v[156:159], v[206:209], v[28:31]
	v_mfma_f32_16x16x32_bf16 v[24:27], v[166:169], v[206:209], v[24:27]
	v_mfma_f32_16x16x32_bf16 v[12:15], v[156:159], v[218:221], v[12:15]
	v_mfma_f32_16x16x32_bf16 v[8:11], v[166:169], v[218:221], v[8:11]
	v_mfma_f32_16x16x32_bf16 v[52:55], v[170:173], v[186:189], v[52:55]
	v_mfma_f32_16x16x32_bf16 v[48:51], v[178:181], v[186:189], v[48:51]
	v_mfma_f32_16x16x32_bf16 v[36:39], v[170:173], v[194:197], v[36:39]
	v_mfma_f32_16x16x32_bf16 v[32:35], v[178:181], v[194:197], v[32:35]
	v_mfma_f32_16x16x32_bf16 v[20:23], v[170:173], v[202:205], v[20:23]
	v_mfma_f32_16x16x32_bf16 v[16:19], v[178:181], v[202:205], v[16:19]
	v_mfma_f32_16x16x32_bf16 v[4:7], v[170:173], v[214:217], v[4:7]
	v_mfma_f32_16x16x32_bf16 v[0:3], v[178:181], v[214:217], v[0:3]
	v_mfma_f32_16x16x32_bf16 v[52:55], v[174:177], v[190:193], v[52:55]
	v_mfma_f32_16x16x32_bf16 v[48:51], v[182:185], v[190:193], v[48:51]
	v_mfma_f32_16x16x32_bf16 v[36:39], v[174:177], v[198:201], v[36:39]
	v_mfma_f32_16x16x32_bf16 v[32:35], v[182:185], v[198:201], v[32:35]
	v_mfma_f32_16x16x32_bf16 v[20:23], v[174:177], v[206:209], v[20:23]
	v_mfma_f32_16x16x32_bf16 v[16:19], v[182:185], v[206:209], v[16:19]
	v_mfma_f32_16x16x32_bf16 v[4:7], v[174:177], v[218:221], v[4:7]
	v_mfma_f32_16x16x32_bf16 v[0:3], v[182:185], v[218:221], v[0:3]
	s_barrier
	s_setprio 0
	s_add_i32 s89, 0, 0x18000
	v_add_u32_e32 v161, s89, v151
	s_add_i32 s90, 0, 0x1c000
	ds_read_b128 v[144:147], v161
	ds_read_b128 v[156:159], v161 offset:1024
	ds_read_b128 v[162:165], v161 offset:2048
	ds_read_b128 v[166:169], v161 offset:3072
	v_add_u32_e32 v161, s90, v151
	ds_read_b128 v[170:173], v161
	ds_read_b128 v[174:177], v161 offset:1024
	ds_read_b128 v[178:181], v161 offset:2048
	ds_read_b128 v[182:185], v161 offset:3072
	s_add_u32 s72, s72, 0x80000
	s_addc_u32 s73, s73, 0
	s_mov_b32 m0, s31
	v_lshl_add_u64 v[226:227], s[72:73], 0, v[134:135]
	ds_read_b128 v[186:189], v155 offset:32768
	ds_read_b128 v[190:193], v155 offset:33792
	ds_read_b128 v[194:197], v155 offset:34816
	ds_read_b128 v[198:201], v155 offset:35840
	ds_read_b128 v[202:205], v155 offset:36864
	ds_read_b128 v[206:209], v155 offset:37888
	ds_read_b128 v[214:217], v155 offset:38912
	ds_read_b128 v[218:221], v155 offset:39936
	global_load_lds_dwordx4 v[226:227], off
	v_lshl_add_u64 v[226:227], s[72:73], 0, v[130:131]
	s_mov_b32 m0, s37
	s_nop 0
	global_load_lds_dwordx4 v[226:227], off
	s_waitcnt vmcnt(8)
	s_waitcnt lgkmcnt(0)
	s_setprio 1
	s_barrier
	v_mfma_f32_16x16x32_bf16 v[124:127], v[144:147], v[186:189], v[124:127]
	v_mfma_f32_16x16x32_bf16 v[120:123], v[162:165], v[186:189], v[120:123]
	v_mfma_f32_16x16x32_bf16 v[108:111], v[144:147], v[194:197], v[108:111]
	v_mfma_f32_16x16x32_bf16 v[104:107], v[162:165], v[194:197], v[104:107]
	v_mfma_f32_16x16x32_bf16 v[92:95], v[144:147], v[202:205], v[92:95]
	v_mfma_f32_16x16x32_bf16 v[88:91], v[162:165], v[202:205], v[88:91]
	v_mfma_f32_16x16x32_bf16 v[76:79], v[144:147], v[214:217], v[76:79]
	v_mfma_f32_16x16x32_bf16 v[72:75], v[162:165], v[214:217], v[72:75]
	v_mfma_f32_16x16x32_bf16 v[124:127], v[156:159], v[190:193], v[124:127]
	v_mfma_f32_16x16x32_bf16 v[120:123], v[166:169], v[190:193], v[120:123]
	v_mfma_f32_16x16x32_bf16 v[108:111], v[156:159], v[198:201], v[108:111]
	v_mfma_f32_16x16x32_bf16 v[104:107], v[166:169], v[198:201], v[104:107]
	v_mfma_f32_16x16x32_bf16 v[92:95], v[156:159], v[206:209], v[92:95]
	v_mfma_f32_16x16x32_bf16 v[88:91], v[166:169], v[206:209], v[88:91]
	v_mfma_f32_16x16x32_bf16 v[76:79], v[156:159], v[218:221], v[76:79]
	v_mfma_f32_16x16x32_bf16 v[72:75], v[166:169], v[218:221], v[72:75]
	v_mfma_f32_16x16x32_bf16 v[116:119], v[170:173], v[186:189], v[116:119]
	v_mfma_f32_16x16x32_bf16 v[112:115], v[178:181], v[186:189], v[112:115]
	v_mfma_f32_16x16x32_bf16 v[100:103], v[170:173], v[194:197], v[100:103]
	v_mfma_f32_16x16x32_bf16 v[96:99], v[178:181], v[194:197], v[96:99]
	v_mfma_f32_16x16x32_bf16 v[84:87], v[170:173], v[202:205], v[84:87]
	v_mfma_f32_16x16x32_bf16 v[80:83], v[178:181], v[202:205], v[80:83]
	v_mfma_f32_16x16x32_bf16 v[68:71], v[170:173], v[214:217], v[68:71]
	v_mfma_f32_16x16x32_bf16 v[64:67], v[178:181], v[214:217], v[64:67]
	v_mfma_f32_16x16x32_bf16 v[116:119], v[174:177], v[190:193], v[116:119]
	v_mfma_f32_16x16x32_bf16 v[112:115], v[182:185], v[190:193], v[112:115]
	v_mfma_f32_16x16x32_bf16 v[100:103], v[174:177], v[198:201], v[100:103]
	v_mfma_f32_16x16x32_bf16 v[96:99], v[182:185], v[198:201], v[96:99]
	v_mfma_f32_16x16x32_bf16 v[84:87], v[174:177], v[206:209], v[84:87]
	v_mfma_f32_16x16x32_bf16 v[80:83], v[182:185], v[206:209], v[80:83]
	v_mfma_f32_16x16x32_bf16 v[68:71], v[174:177], v[218:221], v[68:71]
	v_mfma_f32_16x16x32_bf16 v[64:67], v[182:185], v[218:221], v[64:67]
	s_barrier
	s_setprio 0
	s_add_i32 s72, s89, s28
	v_lshl_add_u64 v[148:149], v[148:149], 0, s[26:27]
	s_mov_b32 m0, s72
	ds_read_b128 v[186:189], v155 offset:49152
	ds_read_b128 v[190:193], v155 offset:50176
	ds_read_b128 v[194:197], v155 offset:51200
	ds_read_b128 v[198:201], v155 offset:52224
	ds_read_b128 v[202:205], v155 offset:53248
	ds_read_b128 v[206:209], v155 offset:54272
	ds_read_b128 v[214:217], v155 offset:55296
	ds_read_b128 v[218:221], v155 offset:56320
	global_load_lds_dwordx4 v[148:149], off
	s_add_i32 m0, s72, 0x2000
	s_add_u32 s70, s70, 0x80080
	v_lshl_add_u64 v[148:149], v[210:211], 0, s[26:27]
	s_addc_u32 s71, s71, 0
	s_add_i32 s72, s90, s28
	global_load_lds_dwordx4 v[148:149], off
	v_lshl_add_u64 v[148:149], s[70:71], 0, v[132:133]
	s_mov_b32 m0, s72
	s_nop 0
	global_load_lds_dwordx4 v[148:149], off
	v_lshl_add_u64 v[148:149], s[70:71], 0, v[128:129]
	s_add_i32 m0, s72, 0x2000
	s_nop 0
	global_load_lds_dwordx4 v[148:149], off
	v_lshl_add_u64 v[148:149], v[222:223], 0, s[26:27]
	s_mov_b32 m0, s76
	s_nop 0
	global_load_lds_dwordx4 v[148:149], off
	v_lshl_add_u64 v[148:149], v[224:225], 0, s[26:27]
	s_mov_b32 m0, s77
	s_nop 0
	global_load_lds_dwordx4 v[148:149], off
	s_waitcnt vmcnt(8)
	s_waitcnt lgkmcnt(0)
	s_setprio 1
	s_barrier
	v_mfma_f32_16x16x32_bf16 v[60:63], v[144:147], v[186:189], v[60:63]
	v_mfma_f32_16x16x32_bf16 v[56:59], v[162:165], v[186:189], v[56:59]
	v_mfma_f32_16x16x32_bf16 v[44:47], v[144:147], v[194:197], v[44:47]
	v_mfma_f32_16x16x32_bf16 v[40:43], v[162:165], v[194:197], v[40:43]
	v_mfma_f32_16x16x32_bf16 v[28:31], v[144:147], v[202:205], v[28:31]
	v_mfma_f32_16x16x32_bf16 v[24:27], v[162:165], v[202:205], v[24:27]
	v_mfma_f32_16x16x32_bf16 v[12:15], v[144:147], v[214:217], v[12:15]
	v_mfma_f32_16x16x32_bf16 v[8:11], v[162:165], v[214:217], v[8:11]
	v_mfma_f32_16x16x32_bf16 v[60:63], v[156:159], v[190:193], v[60:63]
	v_mfma_f32_16x16x32_bf16 v[56:59], v[166:169], v[190:193], v[56:59]
	v_mfma_f32_16x16x32_bf16 v[44:47], v[156:159], v[198:201], v[44:47]
	v_mfma_f32_16x16x32_bf16 v[40:43], v[166:169], v[198:201], v[40:43]
	v_mfma_f32_16x16x32_bf16 v[28:31], v[156:159], v[206:209], v[28:31]
	v_mfma_f32_16x16x32_bf16 v[24:27], v[166:169], v[206:209], v[24:27]
	v_mfma_f32_16x16x32_bf16 v[12:15], v[156:159], v[218:221], v[12:15]
	v_mfma_f32_16x16x32_bf16 v[8:11], v[166:169], v[218:221], v[8:11]
	v_mfma_f32_16x16x32_bf16 v[52:55], v[170:173], v[186:189], v[52:55]
	v_mfma_f32_16x16x32_bf16 v[48:51], v[178:181], v[186:189], v[48:51]
	v_mfma_f32_16x16x32_bf16 v[36:39], v[170:173], v[194:197], v[36:39]
	v_mfma_f32_16x16x32_bf16 v[32:35], v[178:181], v[194:197], v[32:35]
	v_mfma_f32_16x16x32_bf16 v[20:23], v[170:173], v[202:205], v[20:23]
	v_mfma_f32_16x16x32_bf16 v[16:19], v[178:181], v[202:205], v[16:19]
	v_mfma_f32_16x16x32_bf16 v[4:7], v[170:173], v[214:217], v[4:7]
	v_mfma_f32_16x16x32_bf16 v[0:3], v[178:181], v[214:217], v[0:3]
	v_mfma_f32_16x16x32_bf16 v[52:55], v[174:177], v[190:193], v[52:55]
	v_mfma_f32_16x16x32_bf16 v[48:51], v[182:185], v[190:193], v[48:51]
	v_mfma_f32_16x16x32_bf16 v[36:39], v[174:177], v[198:201], v[36:39]
	v_mfma_f32_16x16x32_bf16 v[32:35], v[182:185], v[198:201], v[32:35]
	v_mfma_f32_16x16x32_bf16 v[20:23], v[174:177], v[206:209], v[20:23]
	v_mfma_f32_16x16x32_bf16 v[16:19], v[182:185], v[206:209], v[16:19]
	v_mfma_f32_16x16x32_bf16 v[4:7], v[174:177], v[218:221], v[4:7]
	v_mfma_f32_16x16x32_bf16 v[0:3], v[182:185], v[218:221], v[0:3]
	s_barrier
	s_setprio 0
	s_add_i32 s88, s88, 2
	s_add_u32 s68, s68, 0x100
	s_addc_u32 s69, s69, 0
	s_add_u32 s86, s86, 0x100
	s_addc_u32 s87, s87, 0
	s_cmp_gt_u32 s88, 29
	s_cbranch_scc0 .LBB0_179
	s_and_b64 vcc, exec, s[34:35]
	s_cbranch_vccz .LBB0_182
	s_barrier

.LBB0_208:
	ds_read_b128 v[144:147], v164
	ds_read_b128 v[148:151], v164 offset:1024
	ds_read_b128 v[152:155], v164 offset:2048
	ds_read_b128 v[156:159], v164 offset:3072
	ds_read_b128 v[168:171], v165
	ds_read_b128 v[172:175], v165 offset:1024
	ds_read_b128 v[176:179], v165 offset:2048
	ds_read_b128 v[180:183], v165 offset:3072
	s_add_u32 s70, s68, 0xfff80080
	s_addc_u32 s71, s69, -1
	s_cmp_eq_u32 s67, 28
	s_cselect_b32 s73, s0, s71
	s_cselect_b32 s72, s1, s70
	s_cselect_b32 s71, s3, s65
	s_cselect_b32 s70, s57, s59
	v_lshl_add_u64 v[218:219], s[68:69], 0, v[136:137]
	s_add_i32 m0, s31, 0xc000
	ds_read_b128 v[184:187], v166
	ds_read_b128 v[188:191], v166 offset:1024
	ds_read_b128 v[192:195], v166 offset:2048
	ds_read_b128 v[196:199], v166 offset:3072
	ds_read_b128 v[200:203], v166 offset:4096
	ds_read_b128 v[204:207], v166 offset:5120
	ds_read_b128 v[208:211], v166 offset:6144
	ds_read_b128 v[214:217], v166 offset:7168
	global_load_lds_dwordx4 v[218:219], off
	v_lshl_add_u64 v[218:219], s[68:69], 0, v[138:139]
	s_add_i32 m0, s31, 0xe000
	s_nop 0
	global_load_lds_dwordx4 v[218:219], off
	s_waitcnt vmcnt(8)
	s_waitcnt lgkmcnt(0)
	s_setprio 1
	s_barrier
	v_mfma_f32_16x16x32_bf16 v[124:127], v[144:147], v[184:187], v[124:127]
	v_mfma_f32_16x16x32_bf16 v[120:123], v[152:155], v[184:187], v[120:123]
	v_mfma_f32_16x16x32_bf16 v[108:111], v[144:147], v[192:195], v[108:111]
	v_mfma_f32_16x16x32_bf16 v[104:107], v[152:155], v[192:195], v[104:107]
	v_mfma_f32_16x16x32_bf16 v[92:95], v[144:147], v[200:203], v[92:95]
	v_mfma_f32_16x16x32_bf16 v[88:91], v[152:155], v[200:203], v[88:91]
	v_mfma_f32_16x16x32_bf16 v[76:79], v[144:147], v[208:211], v[76:79]
	v_mfma_f32_16x16x32_bf16 v[72:75], v[152:155], v[208:211], v[72:75]
	v_mfma_f32_16x16x32_bf16 v[124:127], v[148:151], v[188:191], v[124:127]
	v_mfma_f32_16x16x32_bf16 v[120:123], v[156:159], v[188:191], v[120:123]
	v_mfma_f32_16x16x32_bf16 v[108:111], v[148:151], v[196:199], v[108:111]
	v_mfma_f32_16x16x32_bf16 v[104:107], v[156:159], v[196:199], v[104:107]
	v_mfma_f32_16x16x32_bf16 v[92:95], v[148:151], v[204:207], v[92:95]
	v_mfma_f32_16x16x32_bf16 v[88:91], v[156:159], v[204:207], v[88:91]
	v_mfma_f32_16x16x32_bf16 v[76:79], v[148:151], v[214:217], v[76:79]
	v_mfma_f32_16x16x32_bf16 v[72:75], v[156:159], v[214:217], v[72:75]
	v_mfma_f32_16x16x32_bf16 v[116:119], v[168:171], v[184:187], v[116:119]
	v_mfma_f32_16x16x32_bf16 v[112:115], v[176:179], v[184:187], v[112:115]
	v_mfma_f32_16x16x32_bf16 v[100:103], v[168:171], v[192:195], v[100:103]
	v_mfma_f32_16x16x32_bf16 v[96:99], v[176:179], v[192:195], v[96:99]
	v_mfma_f32_16x16x32_bf16 v[84:87], v[168:171], v[200:203], v[84:87]
	v_mfma_f32_16x16x32_bf16 v[80:83], v[176:179], v[200:203], v[80:83]
	v_mfma_f32_16x16x32_bf16 v[68:71], v[168:171], v[208:211], v[68:71]
	v_mfma_f32_16x16x32_bf16 v[64:67], v[176:179], v[208:211], v[64:67]
	v_mfma_f32_16x16x32_bf16 v[116:119], v[172:175], v[188:191], v[116:119]
	v_mfma_f32_16x16x32_bf16 v[112:115], v[180:183], v[188:191], v[112:115]
	v_mfma_f32_16x16x32_bf16 v[100:103], v[172:175], v[196:199], v[100:103]
	v_mfma_f32_16x16x32_bf16 v[96:99], v[180:183], v[196:199], v[96:99]
	v_mfma_f32_16x16x32_bf16 v[84:87], v[172:175], v[204:207], v[84:87]
	v_mfma_f32_16x16x32_bf16 v[80:83], v[180:183], v[204:207], v[80:83]
	v_mfma_f32_16x16x32_bf16 v[68:71], v[172:175], v[214:217], v[68:71]
	v_mfma_f32_16x16x32_bf16 v[64:67], v[180:183], v[214:217], v[64:67]
	s_barrier
	s_setprio 0
	s_add_i32 s90, s84, s30
	v_lshl_add_u64 v[218:219], s[70:71], 0, v[130:131]
	s_mov_b32 m0, s90
	ds_read_b128 v[184:187], v166 offset:16384
	ds_read_b128 v[188:191], v166 offset:17408
	ds_read_b128 v[192:195], v166 offset:18432
	ds_read_b128 v[196:199], v166 offset:19456
	ds_read_b128 v[200:203], v166 offset:20480
	ds_read_b128 v[204:207], v166 offset:21504
	ds_read_b128 v[208:211], v166 offset:22528
	ds_read_b128 v[214:217], v166 offset:23552
	global_load_lds_dwordx4 v[218:219], off
	s_add_i32 m0, s90, 0x2000
	s_add_u32 s90, s70, 0x80000
	v_lshl_add_u64 v[220:221], s[70:71], 0, v[134:135]
	s_addc_u32 s91, s71, 0
	s_add_i32 s92, s85, s30
	global_load_lds_dwordx4 v[220:221], off
	v_lshl_add_u64 v[222:223], s[90:91], 0, v[130:131]
	s_mov_b32 m0, s92
	v_lshl_add_u64 v[224:225], s[72:73], 0, v[132:133]
	global_load_lds_dwordx4 v[222:223], off
	v_lshl_add_u64 v[222:223], s[90:91], 0, v[134:135]
	s_add_i32 m0, s92, 0x2000
	s_nop 0
	global_load_lds_dwordx4 v[222:223], off
	v_lshl_add_u64 v[222:223], s[72:73], 0, v[128:129]
	s_mov_b32 m0, s31
	s_nop 0
	global_load_lds_dwordx4 v[222:223], off
	s_mov_b32 m0, s76
	s_nop 0
	global_load_lds_dwordx4 v[224:225], off
	s_waitcnt vmcnt(8)
	s_waitcnt lgkmcnt(0)
	s_setprio 1
	s_barrier
	v_mfma_f32_16x16x32_bf16 v[60:63], v[144:147], v[184:187], v[60:63]
	v_mfma_f32_16x16x32_bf16 v[56:59], v[152:155], v[184:187], v[56:59]
	v_mfma_f32_16x16x32_bf16 v[44:47], v[144:147], v[192:195], v[44:47]
	v_mfma_f32_16x16x32_bf16 v[40:43], v[152:155], v[192:195], v[40:43]
	v_mfma_f32_16x16x32_bf16 v[28:31], v[144:147], v[200:203], v[28:31]
	v_mfma_f32_16x16x32_bf16 v[24:27], v[152:155], v[200:203], v[24:27]
	v_mfma_f32_16x16x32_bf16 v[12:15], v[144:147], v[208:211], v[12:15]
	v_mfma_f32_16x16x32_bf16 v[8:11], v[152:155], v[208:211], v[8:11]
	v_mfma_f32_16x16x32_bf16 v[60:63], v[148:151], v[188:191], v[60:63]
	v_mfma_f32_16x16x32_bf16 v[56:59], v[156:159], v[188:191], v[56:59]
	v_mfma_f32_16x16x32_bf16 v[44:47], v[148:151], v[196:199], v[44:47]
	v_mfma_f32_16x16x32_bf16 v[40:43], v[156:159], v[196:199], v[40:43]
	v_mfma_f32_16x16x32_bf16 v[28:31], v[148:151], v[204:207], v[28:31]
	v_mfma_f32_16x16x32_bf16 v[24:27], v[156:159], v[204:207], v[24:27]
	v_mfma_f32_16x16x32_bf16 v[12:15], v[148:151], v[214:217], v[12:15]
	v_mfma_f32_16x16x32_bf16 v[8:11], v[156:159], v[214:217], v[8:11]
	v_mfma_f32_16x16x32_bf16 v[52:55], v[168:171], v[184:187], v[52:55]
	v_mfma_f32_16x16x32_bf16 v[48:51], v[176:179], v[184:187], v[48:51]
	v_mfma_f32_16x16x32_bf16 v[36:39], v[168:171], v[192:195], v[36:39]
	v_mfma_f32_16x16x32_bf16 v[32:35], v[176:179], v[192:195], v[32:35]
	v_mfma_f32_16x16x32_bf16 v[20:23], v[168:171], v[200:203], v[20:23]
	v_mfma_f32_16x16x32_bf16 v[16:19], v[176:179], v[200:203], v[16:19]
	v_mfma_f32_16x16x32_bf16 v[4:7], v[168:171], v[208:211], v[4:7]
	v_mfma_f32_16x16x32_bf16 v[0:3], v[176:179], v[208:211], v[0:3]
	v_mfma_f32_16x16x32_bf16 v[52:55], v[172:175], v[188:191], v[52:55]
	v_mfma_f32_16x16x32_bf16 v[48:51], v[180:183], v[188:191], v[48:51]
	v_mfma_f32_16x16x32_bf16 v[36:39], v[172:175], v[196:199], v[36:39]
	v_mfma_f32_16x16x32_bf16 v[32:35], v[180:183], v[196:199], v[32:35]
	v_mfma_f32_16x16x32_bf16 v[20:23], v[172:175], v[204:207], v[20:23]
	v_mfma_f32_16x16x32_bf16 v[16:19], v[180:183], v[204:207], v[16:19]
	v_mfma_f32_16x16x32_bf16 v[4:7], v[172:175], v[214:217], v[4:7]
	v_mfma_f32_16x16x32_bf16 v[0:3], v[180:183], v[214:217], v[0:3]
	s_barrier
	s_setprio 0
	s_add_i32 s90, 0, 0x18000
	s_add_i32 s91, 0, 0x1c000
	v_add_u32_e32 v156, s90, v162
	v_add_u32_e32 v167, s91, v162
	ds_read_b128 v[144:147], v156
	ds_read_b128 v[148:151], v156 offset:1024
	ds_read_b128 v[152:155], v156 offset:2048
	ds_read_b128 v[156:159], v156 offset:3072
	ds_read_b128 v[168:171], v167
	ds_read_b128 v[172:175], v167 offset:1024
	ds_read_b128 v[176:179], v167 offset:2048
	ds_read_b128 v[180:183], v167 offset:3072
	s_add_u32 s72, s72, 0x80000
	s_addc_u32 s73, s73, 0
	s_mov_b32 m0, s77
	v_lshl_add_u64 v[226:227], s[72:73], 0, v[128:129]
	ds_read_b128 v[184:187], v166 offset:32768
	ds_read_b128 v[188:191], v166 offset:33792
	ds_read_b128 v[192:195], v166 offset:34816
	ds_read_b128 v[196:199], v166 offset:35840
	ds_read_b128 v[200:203], v166 offset:36864
	ds_read_b128 v[204:207], v166 offset:37888
	ds_read_b128 v[208:211], v166 offset:38912
	ds_read_b128 v[214:217], v166 offset:39936
	global_load_lds_dwordx4 v[226:227], off
	v_lshl_add_u64 v[226:227], s[72:73], 0, v[132:133]
	s_mov_b32 m0, s78
	s_nop 0
	global_load_lds_dwordx4 v[226:227], off
	s_waitcnt vmcnt(8)
	s_waitcnt lgkmcnt(0)
	s_setprio 1
	s_barrier
	v_mfma_f32_16x16x32_bf16 v[124:127], v[144:147], v[184:187], v[124:127]
	v_mfma_f32_16x16x32_bf16 v[120:123], v[152:155], v[184:187], v[120:123]
	v_mfma_f32_16x16x32_bf16 v[108:111], v[144:147], v[192:195], v[108:111]
	v_mfma_f32_16x16x32_bf16 v[104:107], v[152:155], v[192:195], v[104:107]
	v_mfma_f32_16x16x32_bf16 v[92:95], v[144:147], v[200:203], v[92:95]
	v_mfma_f32_16x16x32_bf16 v[88:91], v[152:155], v[200:203], v[88:91]
	v_mfma_f32_16x16x32_bf16 v[76:79], v[144:147], v[208:211], v[76:79]
	v_mfma_f32_16x16x32_bf16 v[72:75], v[152:155], v[208:211], v[72:75]
	v_mfma_f32_16x16x32_bf16 v[124:127], v[148:151], v[188:191], v[124:127]
	v_mfma_f32_16x16x32_bf16 v[120:123], v[156:159], v[188:191], v[120:123]
	v_mfma_f32_16x16x32_bf16 v[108:111], v[148:151], v[196:199], v[108:111]
	v_mfma_f32_16x16x32_bf16 v[104:107], v[156:159], v[196:199], v[104:107]
	v_mfma_f32_16x16x32_bf16 v[92:95], v[148:151], v[204:207], v[92:95]
	v_mfma_f32_16x16x32_bf16 v[88:91], v[156:159], v[204:207], v[88:91]
	v_mfma_f32_16x16x32_bf16 v[76:79], v[148:151], v[214:217], v[76:79]
	v_mfma_f32_16x16x32_bf16 v[72:75], v[156:159], v[214:217], v[72:75]
	v_mfma_f32_16x16x32_bf16 v[116:119], v[168:171], v[184:187], v[116:119]
	v_mfma_f32_16x16x32_bf16 v[112:115], v[176:179], v[184:187], v[112:115]
	v_mfma_f32_16x16x32_bf16 v[100:103], v[168:171], v[192:195], v[100:103]
	v_mfma_f32_16x16x32_bf16 v[96:99], v[176:179], v[192:195], v[96:99]
	v_mfma_f32_16x16x32_bf16 v[84:87], v[168:171], v[200:203], v[84:87]
	v_mfma_f32_16x16x32_bf16 v[80:83], v[176:179], v[200:203], v[80:83]
	v_mfma_f32_16x16x32_bf16 v[68:71], v[168:171], v[208:211], v[68:71]
	v_mfma_f32_16x16x32_bf16 v[64:67], v[176:179], v[208:211], v[64:67]
	v_mfma_f32_16x16x32_bf16 v[116:119], v[172:175], v[188:191], v[116:119]
	v_mfma_f32_16x16x32_bf16 v[112:115], v[180:183], v[188:191], v[112:115]
	v_mfma_f32_16x16x32_bf16 v[100:103], v[172:175], v[196:199], v[100:103]
	v_mfma_f32_16x16x32_bf16 v[96:99], v[180:183], v[196:199], v[96:99]
	v_mfma_f32_16x16x32_bf16 v[84:87], v[172:175], v[204:207], v[84:87]
	v_mfma_f32_16x16x32_bf16 v[80:83], v[180:183], v[204:207], v[80:83]
	v_mfma_f32_16x16x32_bf16 v[68:71], v[172:175], v[214:217], v[68:71]
	v_mfma_f32_16x16x32_bf16 v[64:67], v[180:183], v[214:217], v[64:67]
	s_barrier
	s_setprio 0
	s_add_i32 s72, s90, s30
	v_lshl_add_u64 v[218:219], v[218:219], 0, s[34:35]
	s_mov_b32 m0, s72
	ds_read_b128 v[184:187], v166 offset:49152
	ds_read_b128 v[188:191], v166 offset:50176
	ds_read_b128 v[192:195], v166 offset:51200
	ds_read_b128 v[196:199], v166 offset:52224
	ds_read_b128 v[200:203], v166 offset:53248
	ds_read_b128 v[204:207], v166 offset:54272
	ds_read_b128 v[208:211], v166 offset:55296
	ds_read_b128 v[214:217], v166 offset:56320
	global_load_lds_dwordx4 v[218:219], off
	s_add_i32 m0, s72, 0x2000
	s_add_u32 s70, s70, 0x80080
	v_lshl_add_u64 v[218:219], v[220:221], 0, s[34:35]
	s_addc_u32 s71, s71, 0
	s_add_i32 s72, s91, s30
	global_load_lds_dwordx4 v[218:219], off
	v_lshl_add_u64 v[218:219], s[70:71], 0, v[130:131]
	s_mov_b32 m0, s72
	s_nop 0
	global_load_lds_dwordx4 v[218:219], off
	v_lshl_add_u64 v[218:219], s[70:71], 0, v[134:135]
	s_add_i32 m0, s72, 0x2000
	s_nop 0
	global_load_lds_dwordx4 v[218:219], off
	v_lshl_add_u64 v[218:219], v[222:223], 0, s[34:35]
	s_mov_b32 m0, s80
	s_nop 0
	global_load_lds_dwordx4 v[218:219], off
	v_lshl_add_u64 v[218:219], v[224:225], 0, s[34:35]
	s_mov_b32 m0, s81
	s_nop 0
	global_load_lds_dwordx4 v[218:219], off
	s_waitcnt vmcnt(8)
	s_waitcnt lgkmcnt(0)
	s_setprio 1
	s_barrier
	v_mfma_f32_16x16x32_bf16 v[60:63], v[144:147], v[184:187], v[60:63]
	v_mfma_f32_16x16x32_bf16 v[56:59], v[152:155], v[184:187], v[56:59]
	v_mfma_f32_16x16x32_bf16 v[44:47], v[144:147], v[192:195], v[44:47]
	v_mfma_f32_16x16x32_bf16 v[40:43], v[152:155], v[192:195], v[40:43]
	v_mfma_f32_16x16x32_bf16 v[28:31], v[144:147], v[200:203], v[28:31]
	v_mfma_f32_16x16x32_bf16 v[24:27], v[152:155], v[200:203], v[24:27]
	v_mfma_f32_16x16x32_bf16 v[12:15], v[144:147], v[208:211], v[12:15]
	v_mfma_f32_16x16x32_bf16 v[8:11], v[152:155], v[208:211], v[8:11]
	v_mfma_f32_16x16x32_bf16 v[60:63], v[148:151], v[188:191], v[60:63]
	v_mfma_f32_16x16x32_bf16 v[56:59], v[156:159], v[188:191], v[56:59]
	v_mfma_f32_16x16x32_bf16 v[44:47], v[148:151], v[196:199], v[44:47]
	v_mfma_f32_16x16x32_bf16 v[40:43], v[156:159], v[196:199], v[40:43]
	v_mfma_f32_16x16x32_bf16 v[28:31], v[148:151], v[204:207], v[28:31]
	v_mfma_f32_16x16x32_bf16 v[24:27], v[156:159], v[204:207], v[24:27]
	v_mfma_f32_16x16x32_bf16 v[12:15], v[148:151], v[214:217], v[12:15]
	v_mfma_f32_16x16x32_bf16 v[8:11], v[156:159], v[214:217], v[8:11]
	v_mfma_f32_16x16x32_bf16 v[52:55], v[168:171], v[184:187], v[52:55]
	v_mfma_f32_16x16x32_bf16 v[48:51], v[176:179], v[184:187], v[48:51]
	v_mfma_f32_16x16x32_bf16 v[36:39], v[168:171], v[192:195], v[36:39]
	v_mfma_f32_16x16x32_bf16 v[32:35], v[176:179], v[192:195], v[32:35]
	v_mfma_f32_16x16x32_bf16 v[20:23], v[168:171], v[200:203], v[20:23]
	v_mfma_f32_16x16x32_bf16 v[16:19], v[176:179], v[200:203], v[16:19]
	v_mfma_f32_16x16x32_bf16 v[4:7], v[168:171], v[208:211], v[4:7]
	v_mfma_f32_16x16x32_bf16 v[0:3], v[176:179], v[208:211], v[0:3]
	v_mfma_f32_16x16x32_bf16 v[52:55], v[172:175], v[188:191], v[52:55]
	v_mfma_f32_16x16x32_bf16 v[48:51], v[180:183], v[188:191], v[48:51]
	v_mfma_f32_16x16x32_bf16 v[36:39], v[172:175], v[196:199], v[36:39]
	v_mfma_f32_16x16x32_bf16 v[32:35], v[180:183], v[196:199], v[32:35]
	v_mfma_f32_16x16x32_bf16 v[20:23], v[172:175], v[204:207], v[20:23]
	v_mfma_f32_16x16x32_bf16 v[16:19], v[180:183], v[204:207], v[16:19]
	v_mfma_f32_16x16x32_bf16 v[4:7], v[172:175], v[214:217], v[4:7]
	v_mfma_f32_16x16x32_bf16 v[0:3], v[180:183], v[214:217], v[0:3]
	s_barrier
	s_setprio 0
	s_add_i32 s67, s67, 2
	s_add_u32 s68, s68, 0x100
	s_addc_u32 s69, s69, 0
	s_add_u32 s59, s59, 0x100
	s_addc_u32 s65, s65, 0
	s_cmp_gt_u32 s67, 29
	s_cbranch_scc0 .LBB0_208
	s_and_b64 vcc, exec, s[36:37]
	s_cbranch_vccz .LBB0_211
	s_barrier

.LBB0_271:
	s_ashr_i32 s63, s62, 31
	s_lshl_b64 s[0:1], s[62:63], 20
	s_add_u32 s66, s49, s0
	s_addc_u32 s67, s82, s1
	s_and_b64 s[0:1], s[4:5], exec
	s_cselect_b32 s0, s67, s75
	s_cselect_b32 s1, s66, s74
	s_ashr_i32 s65, s64, 31
	s_lshl_b64 s[68:69], s[64:65], 20
	s_add_u32 s68, s45, s68
	s_addc_u32 s69, s47, s69
	s_and_b64 s[78:79], s[4:5], exec
	s_cselect_b32 s3, s69, s77
	s_cselect_b32 s63, s68, s76
	s_add_u32 s74, s74, 0x80080
	s_addc_u32 s75, s75, 0
	s_add_u32 s65, s76, 0x100
	s_addc_u32 s71, s77, 0
	s_mov_b32 s90, -2
	s_waitcnt vmcnt(0)
	ds_read_b128 v[146:149], v166
	ds_read_b128 v[150:153], v166 offset:1024
	ds_read_b128 v[154:157], v166 offset:2048
	ds_read_b128 v[170:173], v166 offset:3072
	ds_read_b128 v[174:177], v167
	ds_read_b128 v[178:181], v167 offset:1024
	ds_read_b128 v[182:185], v167 offset:2048
	ds_read_b128 v[186:189], v167 offset:3072
	s_add_u32 s76, s74, 0xfff80080
	s_addc_u32 s77, s75, -1
	s_cmp_eq_u32 s90, 28
	s_cselect_b32 s79, s0, s77
	s_cselect_b32 s78, s1, s76
	s_cselect_b32 s77, s3, s71
	s_cselect_b32 s76, s63, s65
	s_add_i32 m0, s31, 0xc000
	ds_read_b128 v[190:193], v168
	ds_read_b128 v[194:197], v168 offset:1024
	ds_read_b128 v[198:201], v168 offset:2048
	ds_read_b128 v[202:205], v168 offset:3072
	ds_read_b128 v[206:209], v168 offset:4096
	ds_read_b128 v[214:217], v168 offset:5120
	ds_read_b128 v[218:221], v168 offset:6144
	ds_read_b128 v[222:225], v168 offset:7168
	global_load_lds_dwordx4 v138, s[74:75]
	s_add_i32 m0, s31, 0xe000
	s_nop 0
	global_load_lds_dwordx4 v140, s[74:75]
	s_waitcnt vmcnt(8)
	s_waitcnt lgkmcnt(0)
	s_setprio 1
	s_barrier
	v_mfma_f32_16x16x32_bf16 v[124:127], v[146:149], v[190:193], 0
	v_mfma_f32_16x16x32_bf16 v[120:123], v[154:157], v[190:193], 0
	v_mfma_f32_16x16x32_bf16 v[108:111], v[146:149], v[198:201], 0
	v_mfma_f32_16x16x32_bf16 v[104:107], v[154:157], v[198:201], 0
	v_mfma_f32_16x16x32_bf16 v[92:95], v[146:149], v[206:209], 0
	v_mfma_f32_16x16x32_bf16 v[88:91], v[154:157], v[206:209], 0
	v_mfma_f32_16x16x32_bf16 v[76:79], v[146:149], v[218:221], 0
	v_mfma_f32_16x16x32_bf16 v[72:75], v[154:157], v[218:221], 0
	v_mfma_f32_16x16x32_bf16 v[124:127], v[150:153], v[194:197], v[124:127]
	v_mfma_f32_16x16x32_bf16 v[120:123], v[170:173], v[194:197], v[120:123]
	v_mfma_f32_16x16x32_bf16 v[108:111], v[150:153], v[202:205], v[108:111]
	v_mfma_f32_16x16x32_bf16 v[104:107], v[170:173], v[202:205], v[104:107]
	v_mfma_f32_16x16x32_bf16 v[92:95], v[150:153], v[214:217], v[92:95]
	v_mfma_f32_16x16x32_bf16 v[88:91], v[170:173], v[214:217], v[88:91]
	v_mfma_f32_16x16x32_bf16 v[76:79], v[150:153], v[222:225], v[76:79]
	v_mfma_f32_16x16x32_bf16 v[72:75], v[170:173], v[222:225], v[72:75]
	v_mfma_f32_16x16x32_bf16 v[116:119], v[174:177], v[190:193], 0
	v_mfma_f32_16x16x32_bf16 v[112:115], v[182:185], v[190:193], 0
	v_mfma_f32_16x16x32_bf16 v[100:103], v[174:177], v[198:201], 0
	v_mfma_f32_16x16x32_bf16 v[96:99], v[182:185], v[198:201], 0
	v_mfma_f32_16x16x32_bf16 v[84:87], v[174:177], v[206:209], 0
	v_mfma_f32_16x16x32_bf16 v[80:83], v[182:185], v[206:209], 0
	v_mfma_f32_16x16x32_bf16 v[68:71], v[174:177], v[218:221], 0
	v_mfma_f32_16x16x32_bf16 v[64:67], v[182:185], v[218:221], 0
	v_mfma_f32_16x16x32_bf16 v[116:119], v[178:181], v[194:197], v[116:119]
	v_mfma_f32_16x16x32_bf16 v[112:115], v[186:189], v[194:197], v[112:115]
	v_mfma_f32_16x16x32_bf16 v[100:103], v[178:181], v[202:205], v[100:103]
	v_mfma_f32_16x16x32_bf16 v[96:99], v[186:189], v[202:205], v[96:99]
	v_mfma_f32_16x16x32_bf16 v[84:87], v[178:181], v[214:217], v[84:87]
	v_mfma_f32_16x16x32_bf16 v[80:83], v[186:189], v[214:217], v[80:83]
	v_mfma_f32_16x16x32_bf16 v[68:71], v[178:181], v[222:225], v[68:71]
	v_mfma_f32_16x16x32_bf16 v[64:67], v[186:189], v[222:225], v[64:67]
	s_barrier
	s_setprio 0
	s_add_i32 s91, s81, s30
	s_add_u32 s98, s76, s34
	s_addc_u32 s99, s77, s35
	s_mov_b32 m0, s91
	ds_read_b128 v[190:193], v168 offset:16384
	ds_read_b128 v[194:197], v168 offset:17408
	ds_read_b128 v[198:201], v168 offset:18432
	ds_read_b128 v[202:205], v168 offset:19456
	ds_read_b128 v[206:209], v168 offset:20480
	ds_read_b128 v[214:217], v168 offset:21504
	ds_read_b128 v[218:221], v168 offset:22528
	ds_read_b128 v[222:225], v168 offset:23552
	global_load_lds_dwordx4 v130, s[76:77]
	s_add_i32 m0, s91, 0x2000
	s_add_u32 s92, s76, 0x80000
	s_addc_u32 s93, s77, 0
	s_add_i32 s91, s83, s30
	global_load_lds_dwordx4 v134, s[76:77]
	s_mov_b32 m0, s91
	s_add_u32 s100, s78, s34
	s_addc_u32 s101, s79, s35
	global_load_lds_dwordx4 v130, s[92:93]
	s_add_i32 m0, s91, 0x2000
	s_nop 0
	global_load_lds_dwordx4 v134, s[92:93]
	s_mov_b32 m0, s31
	s_nop 0
	global_load_lds_dwordx4 v128, s[78:79]
	s_mov_b32 m0, s51
	s_nop 0
	global_load_lds_dwordx4 v132, s[78:79]
	s_waitcnt vmcnt(8)
	s_waitcnt lgkmcnt(0)
	s_setprio 1
	s_barrier
	v_mfma_f32_16x16x32_bf16 v[60:63], v[146:149], v[190:193], 0
	v_mfma_f32_16x16x32_bf16 v[56:59], v[154:157], v[190:193], 0
	v_mfma_f32_16x16x32_bf16 v[44:47], v[146:149], v[198:201], 0
	v_mfma_f32_16x16x32_bf16 v[40:43], v[154:157], v[198:201], 0
	v_mfma_f32_16x16x32_bf16 v[28:31], v[146:149], v[206:209], 0
	v_mfma_f32_16x16x32_bf16 v[24:27], v[154:157], v[206:209], 0
	v_mfma_f32_16x16x32_bf16 v[12:15], v[146:149], v[218:221], 0
	v_mfma_f32_16x16x32_bf16 v[8:11], v[154:157], v[218:221], 0
	v_mfma_f32_16x16x32_bf16 v[60:63], v[150:153], v[194:197], v[60:63]
	v_mfma_f32_16x16x32_bf16 v[56:59], v[170:173], v[194:197], v[56:59]
	v_mfma_f32_16x16x32_bf16 v[44:47], v[150:153], v[202:205], v[44:47]
	v_mfma_f32_16x16x32_bf16 v[40:43], v[170:173], v[202:205], v[40:43]
	v_mfma_f32_16x16x32_bf16 v[28:31], v[150:153], v[214:217], v[28:31]
	v_mfma_f32_16x16x32_bf16 v[24:27], v[170:173], v[214:217], v[24:27]
	v_mfma_f32_16x16x32_bf16 v[12:15], v[150:153], v[222:225], v[12:15]
	v_mfma_f32_16x16x32_bf16 v[8:11], v[170:173], v[222:225], v[8:11]
	v_mfma_f32_16x16x32_bf16 v[52:55], v[174:177], v[190:193], 0
	v_mfma_f32_16x16x32_bf16 v[48:51], v[182:185], v[190:193], 0
	v_mfma_f32_16x16x32_bf16 v[36:39], v[174:177], v[198:201], 0
	v_mfma_f32_16x16x32_bf16 v[32:35], v[182:185], v[198:201], 0
	v_mfma_f32_16x16x32_bf16 v[20:23], v[174:177], v[206:209], 0
	v_mfma_f32_16x16x32_bf16 v[16:19], v[182:185], v[206:209], 0
	v_mfma_f32_16x16x32_bf16 v[4:7], v[174:177], v[218:221], 0
	v_mfma_f32_16x16x32_bf16 v[0:3], v[182:185], v[218:221], 0
	v_mfma_f32_16x16x32_bf16 v[52:55], v[178:181], v[194:197], v[52:55]
	v_mfma_f32_16x16x32_bf16 v[48:51], v[186:189], v[194:197], v[48:51]
	v_mfma_f32_16x16x32_bf16 v[36:39], v[178:181], v[202:205], v[36:39]
	v_mfma_f32_16x16x32_bf16 v[32:35], v[186:189], v[202:205], v[32:35]
	v_mfma_f32_16x16x32_bf16 v[20:23], v[178:181], v[214:217], v[20:23]
	v_mfma_f32_16x16x32_bf16 v[16:19], v[186:189], v[214:217], v[16:19]
	v_mfma_f32_16x16x32_bf16 v[4:7], v[178:181], v[222:225], v[4:7]
	v_mfma_f32_16x16x32_bf16 v[0:3], v[186:189], v[222:225], v[0:3]
	s_barrier
	s_setprio 0
	s_add_i32 s91, 0, 0x18000
	v_add_u32_e32 v136, s91, v162
	s_add_i32 s92, 0, 0x1c000
	ds_read_b128 v[146:149], v136
	ds_read_b128 v[150:153], v136 offset:1024
	ds_read_b128 v[154:157], v136 offset:2048
	ds_read_b128 v[170:173], v136 offset:3072
	v_add_u32_e32 v136, s92, v162
	ds_read_b128 v[174:177], v136
	ds_read_b128 v[178:181], v136 offset:1024
	ds_read_b128 v[182:185], v136 offset:2048
	ds_read_b128 v[186:189], v136 offset:3072
	s_add_u32 s78, s78, 0x80000
	s_addc_u32 s79, s79, 0
	s_mov_b32 m0, s28
	ds_read_b128 v[190:193], v168 offset:32768
	ds_read_b128 v[194:197], v168 offset:33792
	ds_read_b128 v[198:201], v168 offset:34816
	ds_read_b128 v[202:205], v168 offset:35840
	ds_read_b128 v[206:209], v168 offset:36864
	ds_read_b128 v[214:217], v168 offset:37888
	ds_read_b128 v[218:221], v168 offset:38912
	ds_read_b128 v[222:225], v168 offset:39936
	global_load_lds_dwordx4 v128, s[78:79]
	s_mov_b32 m0, s29
	s_nop 0
	global_load_lds_dwordx4 v132, s[78:79]
	s_waitcnt vmcnt(8)
	s_waitcnt lgkmcnt(0)
	s_setprio 1
	s_barrier
	v_mfma_f32_16x16x32_bf16 v[124:127], v[146:149], v[190:193], v[124:127]
	v_mfma_f32_16x16x32_bf16 v[120:123], v[154:157], v[190:193], v[120:123]
	v_mfma_f32_16x16x32_bf16 v[108:111], v[146:149], v[198:201], v[108:111]
	v_mfma_f32_16x16x32_bf16 v[104:107], v[154:157], v[198:201], v[104:107]
	v_mfma_f32_16x16x32_bf16 v[92:95], v[146:149], v[206:209], v[92:95]
	v_mfma_f32_16x16x32_bf16 v[88:91], v[154:157], v[206:209], v[88:91]
	v_mfma_f32_16x16x32_bf16 v[76:79], v[146:149], v[218:221], v[76:79]
	v_mfma_f32_16x16x32_bf16 v[72:75], v[154:157], v[218:221], v[72:75]
	v_mfma_f32_16x16x32_bf16 v[124:127], v[150:153], v[194:197], v[124:127]
	v_mfma_f32_16x16x32_bf16 v[120:123], v[170:173], v[194:197], v[120:123]
	v_mfma_f32_16x16x32_bf16 v[108:111], v[150:153], v[202:205], v[108:111]
	v_mfma_f32_16x16x32_bf16 v[104:107], v[170:173], v[202:205], v[104:107]
	v_mfma_f32_16x16x32_bf16 v[92:95], v[150:153], v[214:217], v[92:95]
	v_mfma_f32_16x16x32_bf16 v[88:91], v[170:173], v[214:217], v[88:91]
	v_mfma_f32_16x16x32_bf16 v[76:79], v[150:153], v[222:225], v[76:79]
	v_mfma_f32_16x16x32_bf16 v[72:75], v[170:173], v[222:225], v[72:75]
	v_mfma_f32_16x16x32_bf16 v[116:119], v[174:177], v[190:193], v[116:119]
	v_mfma_f32_16x16x32_bf16 v[112:115], v[182:185], v[190:193], v[112:115]
	v_mfma_f32_16x16x32_bf16 v[100:103], v[174:177], v[198:201], v[100:103]
	v_mfma_f32_16x16x32_bf16 v[96:99], v[182:185], v[198:201], v[96:99]
	v_mfma_f32_16x16x32_bf16 v[84:87], v[174:177], v[206:209], v[84:87]
	v_mfma_f32_16x16x32_bf16 v[80:83], v[182:185], v[206:209], v[80:83]
	v_mfma_f32_16x16x32_bf16 v[68:71], v[174:177], v[218:221], v[68:71]
	v_mfma_f32_16x16x32_bf16 v[64:67], v[182:185], v[218:221], v[64:67]
	v_mfma_f32_16x16x32_bf16 v[116:119], v[178:181], v[194:197], v[116:119]
	v_mfma_f32_16x16x32_bf16 v[112:115], v[186:189], v[194:197], v[112:115]
	v_mfma_f32_16x16x32_bf16 v[100:103], v[178:181], v[202:205], v[100:103]
	v_mfma_f32_16x16x32_bf16 v[96:99], v[186:189], v[202:205], v[96:99]
	v_mfma_f32_16x16x32_bf16 v[84:87], v[178:181], v[214:217], v[84:87]
	v_mfma_f32_16x16x32_bf16 v[80:83], v[186:189], v[214:217], v[80:83]
	v_mfma_f32_16x16x32_bf16 v[68:71], v[178:181], v[222:225], v[68:71]
	v_mfma_f32_16x16x32_bf16 v[64:67], v[186:189], v[222:225], v[64:67]
	s_barrier
	s_setprio 0
	s_add_i32 s78, s91, s30
	s_mov_b32 m0, s78
	ds_read_b128 v[190:193], v168 offset:49152
	ds_read_b128 v[194:197], v168 offset:50176
	ds_read_b128 v[198:201], v168 offset:51200
	ds_read_b128 v[202:205], v168 offset:52224
	ds_read_b128 v[206:209], v168 offset:53248
	ds_read_b128 v[214:217], v168 offset:54272
	ds_read_b128 v[218:221], v168 offset:55296
	ds_read_b128 v[222:225], v168 offset:56320
	global_load_lds_dwordx4 v130, s[98:99]
	s_add_i32 m0, s78, 0x2000
	s_add_u32 s76, s76, 0x80080
	s_addc_u32 s77, s77, 0
	s_add_i32 s78, s92, s30
	global_load_lds_dwordx4 v134, s[98:99]
	s_mov_b32 m0, s78
	s_nop 0
	global_load_lds_dwordx4 v130, s[76:77]
	s_add_i32 m0, s78, 0x2000
	s_nop 0
	global_load_lds_dwordx4 v134, s[76:77]
	s_mov_b32 m0, s73
	s_nop 0
	global_load_lds_dwordx4 v128, s[100:101]
	s_mov_b32 m0, s80
	s_nop 0
	global_load_lds_dwordx4 v132, s[100:101]
	s_waitcnt vmcnt(8)
	s_waitcnt lgkmcnt(0)
	s_setprio 1
	s_barrier
	v_mfma_f32_16x16x32_bf16 v[60:63], v[146:149], v[190:193], v[60:63]
	v_mfma_f32_16x16x32_bf16 v[56:59], v[154:157], v[190:193], v[56:59]
	v_mfma_f32_16x16x32_bf16 v[44:47], v[146:149], v[198:201], v[44:47]
	v_mfma_f32_16x16x32_bf16 v[40:43], v[154:157], v[198:201], v[40:43]
	v_mfma_f32_16x16x32_bf16 v[28:31], v[146:149], v[206:209], v[28:31]
	v_mfma_f32_16x16x32_bf16 v[24:27], v[154:157], v[206:209], v[24:27]
	v_mfma_f32_16x16x32_bf16 v[12:15], v[146:149], v[218:221], v[12:15]
	v_mfma_f32_16x16x32_bf16 v[8:11], v[154:157], v[218:221], v[8:11]
	v_mfma_f32_16x16x32_bf16 v[60:63], v[150:153], v[194:197], v[60:63]
	v_mfma_f32_16x16x32_bf16 v[56:59], v[170:173], v[194:197], v[56:59]
	v_mfma_f32_16x16x32_bf16 v[44:47], v[150:153], v[202:205], v[44:47]
	v_mfma_f32_16x16x32_bf16 v[40:43], v[170:173], v[202:205], v[40:43]
	v_mfma_f32_16x16x32_bf16 v[28:31], v[150:153], v[214:217], v[28:31]
	v_mfma_f32_16x16x32_bf16 v[24:27], v[170:173], v[214:217], v[24:27]
	v_mfma_f32_16x16x32_bf16 v[12:15], v[150:153], v[222:225], v[12:15]
	v_mfma_f32_16x16x32_bf16 v[8:11], v[170:173], v[222:225], v[8:11]
	v_mfma_f32_16x16x32_bf16 v[52:55], v[174:177], v[190:193], v[52:55]
	v_mfma_f32_16x16x32_bf16 v[48:51], v[182:185], v[190:193], v[48:51]
	v_mfma_f32_16x16x32_bf16 v[36:39], v[174:177], v[198:201], v[36:39]
	v_mfma_f32_16x16x32_bf16 v[32:35], v[182:185], v[198:201], v[32:35]
	v_mfma_f32_16x16x32_bf16 v[20:23], v[174:177], v[206:209], v[20:23]
	v_mfma_f32_16x16x32_bf16 v[16:19], v[182:185], v[206:209], v[16:19]
	v_mfma_f32_16x16x32_bf16 v[4:7], v[174:177], v[218:221], v[4:7]
	v_mfma_f32_16x16x32_bf16 v[0:3], v[182:185], v[218:221], v[0:3]
	v_mfma_f32_16x16x32_bf16 v[52:55], v[178:181], v[194:197], v[52:55]
	v_mfma_f32_16x16x32_bf16 v[48:51], v[186:189], v[194:197], v[48:51]
	v_mfma_f32_16x16x32_bf16 v[36:39], v[178:181], v[202:205], v[36:39]
	v_mfma_f32_16x16x32_bf16 v[32:35], v[186:189], v[202:205], v[32:35]
	v_mfma_f32_16x16x32_bf16 v[20:23], v[178:181], v[214:217], v[20:23]
	v_mfma_f32_16x16x32_bf16 v[16:19], v[186:189], v[214:217], v[16:19]
	v_mfma_f32_16x16x32_bf16 v[4:7], v[178:181], v[222:225], v[4:7]
	v_mfma_f32_16x16x32_bf16 v[0:3], v[186:189], v[222:225], v[0:3]
	s_barrier
	s_setprio 0
	s_add_i32 s90, s90, 2
	s_add_u32 s74, s74, 0x100
	s_addc_u32 s75, s75, 0
	s_add_u32 s65, s65, 0x100
	s_addc_u32 s71, s71, 0
	s_cmp_gt_u32 s90, 29
.LBB0_272:
	ds_read_b128 v[146:149], v166
	ds_read_b128 v[150:153], v166 offset:1024
	ds_read_b128 v[154:157], v166 offset:2048
	ds_read_b128 v[170:173], v166 offset:3072
	ds_read_b128 v[174:177], v167
	ds_read_b128 v[178:181], v167 offset:1024
	ds_read_b128 v[182:185], v167 offset:2048
	ds_read_b128 v[186:189], v167 offset:3072
	s_add_u32 s76, s74, 0xfff80080
	s_addc_u32 s77, s75, -1
	s_cmp_eq_u32 s90, 28
	s_cselect_b32 s79, s0, s77
	s_cselect_b32 s78, s1, s76
	s_cselect_b32 s77, s3, s71
	s_cselect_b32 s76, s63, s65
	s_add_i32 m0, s31, 0xc000
	ds_read_b128 v[190:193], v168
	ds_read_b128 v[194:197], v168 offset:1024
	ds_read_b128 v[198:201], v168 offset:2048
	ds_read_b128 v[202:205], v168 offset:3072
	ds_read_b128 v[206:209], v168 offset:4096
	ds_read_b128 v[214:217], v168 offset:5120
	ds_read_b128 v[218:221], v168 offset:6144
	ds_read_b128 v[222:225], v168 offset:7168
	global_load_lds_dwordx4 v138, s[74:75]
	s_add_i32 m0, s31, 0xe000
	s_nop 0
	global_load_lds_dwordx4 v140, s[74:75]
	s_waitcnt vmcnt(8)
	s_waitcnt lgkmcnt(0)
	s_setprio 1
	s_barrier
	v_mfma_f32_16x16x32_bf16 v[124:127], v[146:149], v[190:193], v[124:127]
	v_mfma_f32_16x16x32_bf16 v[120:123], v[154:157], v[190:193], v[120:123]
	v_mfma_f32_16x16x32_bf16 v[108:111], v[146:149], v[198:201], v[108:111]
	v_mfma_f32_16x16x32_bf16 v[104:107], v[154:157], v[198:201], v[104:107]
	v_mfma_f32_16x16x32_bf16 v[92:95], v[146:149], v[206:209], v[92:95]
	v_mfma_f32_16x16x32_bf16 v[88:91], v[154:157], v[206:209], v[88:91]
	v_mfma_f32_16x16x32_bf16 v[76:79], v[146:149], v[218:221], v[76:79]
	v_mfma_f32_16x16x32_bf16 v[72:75], v[154:157], v[218:221], v[72:75]
	v_mfma_f32_16x16x32_bf16 v[124:127], v[150:153], v[194:197], v[124:127]
	v_mfma_f32_16x16x32_bf16 v[120:123], v[170:173], v[194:197], v[120:123]
	v_mfma_f32_16x16x32_bf16 v[108:111], v[150:153], v[202:205], v[108:111]
	v_mfma_f32_16x16x32_bf16 v[104:107], v[170:173], v[202:205], v[104:107]
	v_mfma_f32_16x16x32_bf16 v[92:95], v[150:153], v[214:217], v[92:95]
	v_mfma_f32_16x16x32_bf16 v[88:91], v[170:173], v[214:217], v[88:91]
	v_mfma_f32_16x16x32_bf16 v[76:79], v[150:153], v[222:225], v[76:79]
	v_mfma_f32_16x16x32_bf16 v[72:75], v[170:173], v[222:225], v[72:75]
	v_mfma_f32_16x16x32_bf16 v[116:119], v[174:177], v[190:193], v[116:119]
	v_mfma_f32_16x16x32_bf16 v[112:115], v[182:185], v[190:193], v[112:115]
	v_mfma_f32_16x16x32_bf16 v[100:103], v[174:177], v[198:201], v[100:103]
	v_mfma_f32_16x16x32_bf16 v[96:99], v[182:185], v[198:201], v[96:99]
	v_mfma_f32_16x16x32_bf16 v[84:87], v[174:177], v[206:209], v[84:87]
	v_mfma_f32_16x16x32_bf16 v[80:83], v[182:185], v[206:209], v[80:83]
	v_mfma_f32_16x16x32_bf16 v[68:71], v[174:177], v[218:221], v[68:71]
	v_mfma_f32_16x16x32_bf16 v[64:67], v[182:185], v[218:221], v[64:67]
	v_mfma_f32_16x16x32_bf16 v[116:119], v[178:181], v[194:197], v[116:119]
	v_mfma_f32_16x16x32_bf16 v[112:115], v[186:189], v[194:197], v[112:115]
	v_mfma_f32_16x16x32_bf16 v[100:103], v[178:181], v[202:205], v[100:103]
	v_mfma_f32_16x16x32_bf16 v[96:99], v[186:189], v[202:205], v[96:99]
	v_mfma_f32_16x16x32_bf16 v[84:87], v[178:181], v[214:217], v[84:87]
	v_mfma_f32_16x16x32_bf16 v[80:83], v[186:189], v[214:217], v[80:83]
	v_mfma_f32_16x16x32_bf16 v[68:71], v[178:181], v[222:225], v[68:71]
	v_mfma_f32_16x16x32_bf16 v[64:67], v[186:189], v[222:225], v[64:67]
	s_barrier
	s_setprio 0
	s_add_i32 s91, s81, s30
	s_add_u32 s98, s76, s34
	s_addc_u32 s99, s77, s35
	s_mov_b32 m0, s91
	ds_read_b128 v[190:193], v168 offset:16384
	ds_read_b128 v[194:197], v168 offset:17408
	ds_read_b128 v[198:201], v168 offset:18432
	ds_read_b128 v[202:205], v168 offset:19456
	ds_read_b128 v[206:209], v168 offset:20480
	ds_read_b128 v[214:217], v168 offset:21504
	ds_read_b128 v[218:221], v168 offset:22528
	ds_read_b128 v[222:225], v168 offset:23552
	global_load_lds_dwordx4 v130, s[76:77]
	s_add_i32 m0, s91, 0x2000
	s_add_u32 s92, s76, 0x80000
	s_addc_u32 s93, s77, 0
	s_add_i32 s91, s83, s30
	global_load_lds_dwordx4 v134, s[76:77]
	s_mov_b32 m0, s91
	s_add_u32 s100, s78, s34
	s_addc_u32 s101, s79, s35
	global_load_lds_dwordx4 v130, s[92:93]
	s_add_i32 m0, s91, 0x2000
	s_nop 0
	global_load_lds_dwordx4 v134, s[92:93]
	s_mov_b32 m0, s31
	s_nop 0
	global_load_lds_dwordx4 v128, s[78:79]
	s_mov_b32 m0, s51
	s_nop 0
	global_load_lds_dwordx4 v132, s[78:79]
	s_waitcnt vmcnt(8)
	s_waitcnt lgkmcnt(0)
	s_setprio 1
	s_barrier
	v_mfma_f32_16x16x32_bf16 v[60:63], v[146:149], v[190:193], v[60:63]
	v_mfma_f32_16x16x32_bf16 v[56:59], v[154:157], v[190:193], v[56:59]
	v_mfma_f32_16x16x32_bf16 v[44:47], v[146:149], v[198:201], v[44:47]
	v_mfma_f32_16x16x32_bf16 v[40:43], v[154:157], v[198:201], v[40:43]
	v_mfma_f32_16x16x32_bf16 v[28:31], v[146:149], v[206:209], v[28:31]
	v_mfma_f32_16x16x32_bf16 v[24:27], v[154:157], v[206:209], v[24:27]
	v_mfma_f32_16x16x32_bf16 v[12:15], v[146:149], v[218:221], v[12:15]
	v_mfma_f32_16x16x32_bf16 v[8:11], v[154:157], v[218:221], v[8:11]
	v_mfma_f32_16x16x32_bf16 v[60:63], v[150:153], v[194:197], v[60:63]
	v_mfma_f32_16x16x32_bf16 v[56:59], v[170:173], v[194:197], v[56:59]
	v_mfma_f32_16x16x32_bf16 v[44:47], v[150:153], v[202:205], v[44:47]
	v_mfma_f32_16x16x32_bf16 v[40:43], v[170:173], v[202:205], v[40:43]
	v_mfma_f32_16x16x32_bf16 v[28:31], v[150:153], v[214:217], v[28:31]
	v_mfma_f32_16x16x32_bf16 v[24:27], v[170:173], v[214:217], v[24:27]
	v_mfma_f32_16x16x32_bf16 v[12:15], v[150:153], v[222:225], v[12:15]
	v_mfma_f32_16x16x32_bf16 v[8:11], v[170:173], v[222:225], v[8:11]
	v_mfma_f32_16x16x32_bf16 v[52:55], v[174:177], v[190:193], v[52:55]
	v_mfma_f32_16x16x32_bf16 v[48:51], v[182:185], v[190:193], v[48:51]
	v_mfma_f32_16x16x32_bf16 v[36:39], v[174:177], v[198:201], v[36:39]
	v_mfma_f32_16x16x32_bf16 v[32:35], v[182:185], v[198:201], v[32:35]
	v_mfma_f32_16x16x32_bf16 v[20:23], v[174:177], v[206:209], v[20:23]
	v_mfma_f32_16x16x32_bf16 v[16:19], v[182:185], v[206:209], v[16:19]
	v_mfma_f32_16x16x32_bf16 v[4:7], v[174:177], v[218:221], v[4:7]
	v_mfma_f32_16x16x32_bf16 v[0:3], v[182:185], v[218:221], v[0:3]
	v_mfma_f32_16x16x32_bf16 v[52:55], v[178:181], v[194:197], v[52:55]
	v_mfma_f32_16x16x32_bf16 v[48:51], v[186:189], v[194:197], v[48:51]
	v_mfma_f32_16x16x32_bf16 v[36:39], v[178:181], v[202:205], v[36:39]
	v_mfma_f32_16x16x32_bf16 v[32:35], v[186:189], v[202:205], v[32:35]
	v_mfma_f32_16x16x32_bf16 v[20:23], v[178:181], v[214:217], v[20:23]
	v_mfma_f32_16x16x32_bf16 v[16:19], v[186:189], v[214:217], v[16:19]
	v_mfma_f32_16x16x32_bf16 v[4:7], v[178:181], v[222:225], v[4:7]
	v_mfma_f32_16x16x32_bf16 v[0:3], v[186:189], v[222:225], v[0:3]
	s_barrier
	s_setprio 0
	s_add_i32 s91, 0, 0x18000
	v_add_u32_e32 v136, s91, v162
	s_add_i32 s92, 0, 0x1c000
	ds_read_b128 v[146:149], v136
	ds_read_b128 v[150:153], v136 offset:1024
	ds_read_b128 v[154:157], v136 offset:2048
	ds_read_b128 v[170:173], v136 offset:3072
	v_add_u32_e32 v136, s92, v162
	ds_read_b128 v[174:177], v136
	ds_read_b128 v[178:181], v136 offset:1024
	ds_read_b128 v[182:185], v136 offset:2048
	ds_read_b128 v[186:189], v136 offset:3072
	s_add_u32 s78, s78, 0x80000
	s_addc_u32 s79, s79, 0
	s_mov_b32 m0, s28
	ds_read_b128 v[190:193], v168 offset:32768
	ds_read_b128 v[194:197], v168 offset:33792
	ds_read_b128 v[198:201], v168 offset:34816
	ds_read_b128 v[202:205], v168 offset:35840
	ds_read_b128 v[206:209], v168 offset:36864
	ds_read_b128 v[214:217], v168 offset:37888
	ds_read_b128 v[218:221], v168 offset:38912
	ds_read_b128 v[222:225], v168 offset:39936
	global_load_lds_dwordx4 v128, s[78:79]
	s_mov_b32 m0, s29
	s_nop 0
	global_load_lds_dwordx4 v132, s[78:79]
	s_waitcnt vmcnt(8)
	s_waitcnt lgkmcnt(0)
	s_setprio 1
	s_barrier
	v_mfma_f32_16x16x32_bf16 v[124:127], v[146:149], v[190:193], v[124:127]
	v_mfma_f32_16x16x32_bf16 v[120:123], v[154:157], v[190:193], v[120:123]
	v_mfma_f32_16x16x32_bf16 v[108:111], v[146:149], v[198:201], v[108:111]
	v_mfma_f32_16x16x32_bf16 v[104:107], v[154:157], v[198:201], v[104:107]
	v_mfma_f32_16x16x32_bf16 v[92:95], v[146:149], v[206:209], v[92:95]
	v_mfma_f32_16x16x32_bf16 v[88:91], v[154:157], v[206:209], v[88:91]
	v_mfma_f32_16x16x32_bf16 v[76:79], v[146:149], v[218:221], v[76:79]
	v_mfma_f32_16x16x32_bf16 v[72:75], v[154:157], v[218:221], v[72:75]
	v_mfma_f32_16x16x32_bf16 v[124:127], v[150:153], v[194:197], v[124:127]
	v_mfma_f32_16x16x32_bf16 v[120:123], v[170:173], v[194:197], v[120:123]
	v_mfma_f32_16x16x32_bf16 v[108:111], v[150:153], v[202:205], v[108:111]
	v_mfma_f32_16x16x32_bf16 v[104:107], v[170:173], v[202:205], v[104:107]
	v_mfma_f32_16x16x32_bf16 v[92:95], v[150:153], v[214:217], v[92:95]
	v_mfma_f32_16x16x32_bf16 v[88:91], v[170:173], v[214:217], v[88:91]
	v_mfma_f32_16x16x32_bf16 v[76:79], v[150:153], v[222:225], v[76:79]
	v_mfma_f32_16x16x32_bf16 v[72:75], v[170:173], v[222:225], v[72:75]
	v_mfma_f32_16x16x32_bf16 v[116:119], v[174:177], v[190:193], v[116:119]
	v_mfma_f32_16x16x32_bf16 v[112:115], v[182:185], v[190:193], v[112:115]
	v_mfma_f32_16x16x32_bf16 v[100:103], v[174:177], v[198:201], v[100:103]
	v_mfma_f32_16x16x32_bf16 v[96:99], v[182:185], v[198:201], v[96:99]
	v_mfma_f32_16x16x32_bf16 v[84:87], v[174:177], v[206:209], v[84:87]
	v_mfma_f32_16x16x32_bf16 v[80:83], v[182:185], v[206:209], v[80:83]
	v_mfma_f32_16x16x32_bf16 v[68:71], v[174:177], v[218:221], v[68:71]
	v_mfma_f32_16x16x32_bf16 v[64:67], v[182:185], v[218:221], v[64:67]
	v_mfma_f32_16x16x32_bf16 v[116:119], v[178:181], v[194:197], v[116:119]
	v_mfma_f32_16x16x32_bf16 v[112:115], v[186:189], v[194:197], v[112:115]
	v_mfma_f32_16x16x32_bf16 v[100:103], v[178:181], v[202:205], v[100:103]
	v_mfma_f32_16x16x32_bf16 v[96:99], v[186:189], v[202:205], v[96:99]
	v_mfma_f32_16x16x32_bf16 v[84:87], v[178:181], v[214:217], v[84:87]
	v_mfma_f32_16x16x32_bf16 v[80:83], v[186:189], v[214:217], v[80:83]
	v_mfma_f32_16x16x32_bf16 v[68:71], v[178:181], v[222:225], v[68:71]
	v_mfma_f32_16x16x32_bf16 v[64:67], v[186:189], v[222:225], v[64:67]
	s_barrier
	s_setprio 0
	s_add_i32 s78, s91, s30
	s_mov_b32 m0, s78
	ds_read_b128 v[190:193], v168 offset:49152
	ds_read_b128 v[194:197], v168 offset:50176
	ds_read_b128 v[198:201], v168 offset:51200
	ds_read_b128 v[202:205], v168 offset:52224
	ds_read_b128 v[206:209], v168 offset:53248
	ds_read_b128 v[214:217], v168 offset:54272
	ds_read_b128 v[218:221], v168 offset:55296
	ds_read_b128 v[222:225], v168 offset:56320
	global_load_lds_dwordx4 v130, s[98:99]
	s_add_i32 m0, s78, 0x2000
	s_add_u32 s76, s76, 0x80080
	s_addc_u32 s77, s77, 0
	s_add_i32 s78, s92, s30
	global_load_lds_dwordx4 v134, s[98:99]
	s_mov_b32 m0, s78
	s_nop 0
	global_load_lds_dwordx4 v130, s[76:77]
	s_add_i32 m0, s78, 0x2000
	s_nop 0
	global_load_lds_dwordx4 v134, s[76:77]
	s_mov_b32 m0, s73
	s_nop 0
	global_load_lds_dwordx4 v128, s[100:101]
	s_mov_b32 m0, s80
	s_nop 0
	global_load_lds_dwordx4 v132, s[100:101]
	s_waitcnt vmcnt(8)
	s_waitcnt lgkmcnt(0)
	s_setprio 1
	s_barrier
	v_mfma_f32_16x16x32_bf16 v[60:63], v[146:149], v[190:193], v[60:63]
	v_mfma_f32_16x16x32_bf16 v[56:59], v[154:157], v[190:193], v[56:59]
	v_mfma_f32_16x16x32_bf16 v[44:47], v[146:149], v[198:201], v[44:47]
	v_mfma_f32_16x16x32_bf16 v[40:43], v[154:157], v[198:201], v[40:43]
	v_mfma_f32_16x16x32_bf16 v[28:31], v[146:149], v[206:209], v[28:31]
	v_mfma_f32_16x16x32_bf16 v[24:27], v[154:157], v[206:209], v[24:27]
	v_mfma_f32_16x16x32_bf16 v[12:15], v[146:149], v[218:221], v[12:15]
	v_mfma_f32_16x16x32_bf16 v[8:11], v[154:157], v[218:221], v[8:11]
	v_mfma_f32_16x16x32_bf16 v[60:63], v[150:153], v[194:197], v[60:63]
	v_mfma_f32_16x16x32_bf16 v[56:59], v[170:173], v[194:197], v[56:59]
	v_mfma_f32_16x16x32_bf16 v[44:47], v[150:153], v[202:205], v[44:47]
	v_mfma_f32_16x16x32_bf16 v[40:43], v[170:173], v[202:205], v[40:43]
	v_mfma_f32_16x16x32_bf16 v[28:31], v[150:153], v[214:217], v[28:31]
	v_mfma_f32_16x16x32_bf16 v[24:27], v[170:173], v[214:217], v[24:27]
	v_mfma_f32_16x16x32_bf16 v[12:15], v[150:153], v[222:225], v[12:15]
	v_mfma_f32_16x16x32_bf16 v[8:11], v[170:173], v[222:225], v[8:11]
	v_mfma_f32_16x16x32_bf16 v[52:55], v[174:177], v[190:193], v[52:55]
	v_mfma_f32_16x16x32_bf16 v[48:51], v[182:185], v[190:193], v[48:51]
	v_mfma_f32_16x16x32_bf16 v[36:39], v[174:177], v[198:201], v[36:39]
	v_mfma_f32_16x16x32_bf16 v[32:35], v[182:185], v[198:201], v[32:35]
	v_mfma_f32_16x16x32_bf16 v[20:23], v[174:177], v[206:209], v[20:23]
	v_mfma_f32_16x16x32_bf16 v[16:19], v[182:185], v[206:209], v[16:19]
	v_mfma_f32_16x16x32_bf16 v[4:7], v[174:177], v[218:221], v[4:7]
	v_mfma_f32_16x16x32_bf16 v[0:3], v[182:185], v[218:221], v[0:3]
	v_mfma_f32_16x16x32_bf16 v[52:55], v[178:181], v[194:197], v[52:55]
	v_mfma_f32_16x16x32_bf16 v[48:51], v[186:189], v[194:197], v[48:51]
	v_mfma_f32_16x16x32_bf16 v[36:39], v[178:181], v[202:205], v[36:39]
	v_mfma_f32_16x16x32_bf16 v[32:35], v[186:189], v[202:205], v[32:35]
	v_mfma_f32_16x16x32_bf16 v[20:23], v[178:181], v[214:217], v[20:23]
	v_mfma_f32_16x16x32_bf16 v[16:19], v[186:189], v[214:217], v[16:19]
	v_mfma_f32_16x16x32_bf16 v[4:7], v[178:181], v[222:225], v[4:7]
	v_mfma_f32_16x16x32_bf16 v[0:3], v[186:189], v[222:225], v[0:3]
	s_barrier
	s_setprio 0
	s_add_i32 s90, s90, 2
	s_add_u32 s74, s74, 0x100
	s_addc_u32 s75, s75, 0
	s_add_u32 s65, s65, 0x100
	s_addc_u32 s71, s71, 0
	s_cmp_gt_u32 s90, 29
	s_cbranch_scc0 .LBB0_272
	s_and_b64 vcc, exec, s[36:37]
	s_cbranch_vccz .LBB0_275
	s_barrier

.LBB0_542:
	s_ashr_i32 s35, s34, 31
	s_lshl_b64 s[0:1], s[34:35], 20
	s_add_u32 s36, s29, s0
	s_addc_u32 s37, s30, s1
	s_and_b64 s[0:1], s[6:7], exec
	s_cselect_b32 s0, s37, s43
	s_cselect_b32 s1, s36, s42
	s_ashr_i32 s25, s24, 31
	s_lshl_b64 s[38:39], s[24:25], 20
	s_add_u32 s38, s27, s38
	s_addc_u32 s39, s28, s39
	s_and_b64 s[46:47], s[6:7], exec
	s_cselect_b32 s3, s39, s45
	s_cselect_b32 s9, s38, s44
	s_add_u32 s42, s42, 0x80080
	s_addc_u32 s43, s43, 0
	s_add_u32 s25, s44, 0x100
	s_addc_u32 s35, s45, 0
	s_mov_b32 s58, -2
	s_waitcnt lgkmcnt(0)
	s_waitcnt vmcnt(0)
	ds_read_b128 v[128:131], v216
	ds_read_b128 v[132:135], v216 offset:1024
	ds_read_b128 v[136:139], v216 offset:2048
	ds_read_b128 v[140:143], v216 offset:3072
	ds_read_b128 v[144:147], v217
	ds_read_b128 v[148:151], v217 offset:1024
	ds_read_b128 v[152:155], v217 offset:2048
	ds_read_b128 v[156:159], v217 offset:3072
	s_add_u32 s44, s42, 0xfff80080
	s_addc_u32 s45, s43, -1
	s_cmp_eq_u32 s58, 28
	s_cselect_b32 s47, s0, s45
	s_cselect_b32 s46, s1, s44
	s_cselect_b32 s45, s3, s35
	s_cselect_b32 s44, s9, s25
	s_add_i32 m0, s41, 0xc000
	ds_read_b128 v[160:163], v218
	ds_read_b128 v[164:167], v218 offset:1024
	ds_read_b128 v[168:171], v218 offset:2048
	ds_read_b128 v[172:175], v218 offset:3072
	ds_read_b128 v[192:195], v218 offset:4096
	ds_read_b128 v[196:199], v218 offset:5120
	ds_read_b128 v[200:203], v218 offset:6144
	ds_read_b128 v[204:207], v218 offset:7168
	global_load_lds_dwordx4 v184, s[42:43]
	s_add_i32 m0, s41, 0xe000
	s_nop 0
	global_load_lds_dwordx4 v186, s[42:43]
	s_waitcnt vmcnt(8)
	s_waitcnt lgkmcnt(0)
	s_setprio 1
	s_barrier
	v_mfma_f32_16x16x32_bf16 v[124:127], v[128:131], v[160:163], 0
	v_mfma_f32_16x16x32_bf16 v[120:123], v[136:139], v[160:163], 0
	v_mfma_f32_16x16x32_bf16 v[108:111], v[128:131], v[168:171], 0
	v_mfma_f32_16x16x32_bf16 v[104:107], v[136:139], v[168:171], 0
	v_mfma_f32_16x16x32_bf16 v[92:95], v[128:131], v[192:195], 0
	v_mfma_f32_16x16x32_bf16 v[88:91], v[136:139], v[192:195], 0
	v_mfma_f32_16x16x32_bf16 v[76:79], v[128:131], v[200:203], 0
	v_mfma_f32_16x16x32_bf16 v[72:75], v[136:139], v[200:203], 0
	v_mfma_f32_16x16x32_bf16 v[124:127], v[132:135], v[164:167], v[124:127]
	v_mfma_f32_16x16x32_bf16 v[120:123], v[140:143], v[164:167], v[120:123]
	v_mfma_f32_16x16x32_bf16 v[108:111], v[132:135], v[172:175], v[108:111]
	v_mfma_f32_16x16x32_bf16 v[104:107], v[140:143], v[172:175], v[104:107]
	v_mfma_f32_16x16x32_bf16 v[92:95], v[132:135], v[196:199], v[92:95]
	v_mfma_f32_16x16x32_bf16 v[88:91], v[140:143], v[196:199], v[88:91]
	v_mfma_f32_16x16x32_bf16 v[76:79], v[132:135], v[204:207], v[76:79]
	v_mfma_f32_16x16x32_bf16 v[72:75], v[140:143], v[204:207], v[72:75]
	v_mfma_f32_16x16x32_bf16 v[116:119], v[144:147], v[160:163], 0
	v_mfma_f32_16x16x32_bf16 v[112:115], v[152:155], v[160:163], 0
	v_mfma_f32_16x16x32_bf16 v[100:103], v[144:147], v[168:171], 0
	v_mfma_f32_16x16x32_bf16 v[96:99], v[152:155], v[168:171], 0
	v_mfma_f32_16x16x32_bf16 v[84:87], v[144:147], v[192:195], 0
	v_mfma_f32_16x16x32_bf16 v[80:83], v[152:155], v[192:195], 0
	v_mfma_f32_16x16x32_bf16 v[68:71], v[144:147], v[200:203], 0
	v_mfma_f32_16x16x32_bf16 v[64:67], v[152:155], v[200:203], 0
	v_mfma_f32_16x16x32_bf16 v[116:119], v[148:151], v[164:167], v[116:119]
	v_mfma_f32_16x16x32_bf16 v[112:115], v[156:159], v[164:167], v[112:115]
	v_mfma_f32_16x16x32_bf16 v[100:103], v[148:151], v[172:175], v[100:103]
	v_mfma_f32_16x16x32_bf16 v[96:99], v[156:159], v[172:175], v[96:99]
	v_mfma_f32_16x16x32_bf16 v[84:87], v[148:151], v[196:199], v[84:87]
	v_mfma_f32_16x16x32_bf16 v[80:83], v[156:159], v[196:199], v[80:83]
	v_mfma_f32_16x16x32_bf16 v[68:71], v[148:151], v[204:207], v[68:71]
	v_mfma_f32_16x16x32_bf16 v[64:67], v[156:159], v[204:207], v[64:67]
	s_barrier
	s_setprio 0
	s_add_i32 s59, s55, s31
	s_add_u32 s98, s44, s20
	s_addc_u32 s99, s45, s21
	s_mov_b32 m0, s59
	ds_read_b128 v[160:163], v218 offset:16384
	ds_read_b128 v[164:167], v218 offset:17408
	ds_read_b128 v[168:171], v218 offset:18432
	ds_read_b128 v[172:175], v218 offset:19456
	ds_read_b128 v[192:195], v218 offset:20480
	ds_read_b128 v[196:199], v218 offset:21504
	ds_read_b128 v[200:203], v218 offset:22528
	ds_read_b128 v[204:207], v218 offset:23552
	global_load_lds_dwordx4 v178, s[44:45]
	s_add_i32 m0, s59, 0x2000
	s_add_u32 s60, s44, 0x80000
	s_addc_u32 s61, s45, 0
	s_add_i32 s59, s56, s31
	global_load_lds_dwordx4 v182, s[44:45]
	s_mov_b32 m0, s59
	s_add_u32 s100, s46, s20
	s_addc_u32 s101, s47, s21
	global_load_lds_dwordx4 v178, s[60:61]
	s_add_i32 m0, s59, 0x2000
	s_nop 0
	global_load_lds_dwordx4 v182, s[60:61]
	s_mov_b32 m0, s41
	s_nop 0
	global_load_lds_dwordx4 v176, s[46:47]
	s_mov_b32 m0, s48
	s_nop 0
	global_load_lds_dwordx4 v180, s[46:47]
	s_waitcnt vmcnt(8)
	s_waitcnt lgkmcnt(0)
	s_setprio 1
	s_barrier
	v_mfma_f32_16x16x32_bf16 v[60:63], v[128:131], v[160:163], 0
	v_mfma_f32_16x16x32_bf16 v[56:59], v[136:139], v[160:163], 0
	v_mfma_f32_16x16x32_bf16 v[44:47], v[128:131], v[168:171], 0
	v_mfma_f32_16x16x32_bf16 v[40:43], v[136:139], v[168:171], 0
	v_mfma_f32_16x16x32_bf16 v[28:31], v[128:131], v[192:195], 0
	v_mfma_f32_16x16x32_bf16 v[24:27], v[136:139], v[192:195], 0
	v_mfma_f32_16x16x32_bf16 v[12:15], v[128:131], v[200:203], 0
	v_mfma_f32_16x16x32_bf16 v[8:11], v[136:139], v[200:203], 0
	v_mfma_f32_16x16x32_bf16 v[60:63], v[132:135], v[164:167], v[60:63]
	v_mfma_f32_16x16x32_bf16 v[56:59], v[140:143], v[164:167], v[56:59]
	v_mfma_f32_16x16x32_bf16 v[44:47], v[132:135], v[172:175], v[44:47]
	v_mfma_f32_16x16x32_bf16 v[40:43], v[140:143], v[172:175], v[40:43]
	v_mfma_f32_16x16x32_bf16 v[28:31], v[132:135], v[196:199], v[28:31]
	v_mfma_f32_16x16x32_bf16 v[24:27], v[140:143], v[196:199], v[24:27]
	v_mfma_f32_16x16x32_bf16 v[12:15], v[132:135], v[204:207], v[12:15]
	v_mfma_f32_16x16x32_bf16 v[8:11], v[140:143], v[204:207], v[8:11]
	v_mfma_f32_16x16x32_bf16 v[52:55], v[144:147], v[160:163], 0
	v_mfma_f32_16x16x32_bf16 v[48:51], v[152:155], v[160:163], 0
	v_mfma_f32_16x16x32_bf16 v[36:39], v[144:147], v[168:171], 0
	v_mfma_f32_16x16x32_bf16 v[32:35], v[152:155], v[168:171], 0
	v_mfma_f32_16x16x32_bf16 v[20:23], v[144:147], v[192:195], 0
	v_mfma_f32_16x16x32_bf16 v[16:19], v[152:155], v[192:195], 0
	v_mfma_f32_16x16x32_bf16 v[4:7], v[144:147], v[200:203], 0
	v_mfma_f32_16x16x32_bf16 v[0:3], v[152:155], v[200:203], 0
	v_mfma_f32_16x16x32_bf16 v[52:55], v[148:151], v[164:167], v[52:55]
	v_mfma_f32_16x16x32_bf16 v[48:51], v[156:159], v[164:167], v[48:51]
	v_mfma_f32_16x16x32_bf16 v[36:39], v[148:151], v[172:175], v[36:39]
	v_mfma_f32_16x16x32_bf16 v[32:35], v[156:159], v[172:175], v[32:35]
	v_mfma_f32_16x16x32_bf16 v[20:23], v[148:151], v[196:199], v[20:23]
	v_mfma_f32_16x16x32_bf16 v[16:19], v[156:159], v[196:199], v[16:19]
	v_mfma_f32_16x16x32_bf16 v[4:7], v[148:151], v[204:207], v[4:7]
	v_mfma_f32_16x16x32_bf16 v[0:3], v[156:159], v[204:207], v[0:3]
	s_barrier
	s_setprio 0
	s_add_i32 s59, 0, 0x18000
	s_add_i32 s60, 0, 0x1c000
	v_add_u32_e32 v140, s59, v214
	v_add_u32_e32 v156, s60, v214
	ds_read_b128 v[128:131], v140
	ds_read_b128 v[132:135], v140 offset:1024
	ds_read_b128 v[136:139], v140 offset:2048
	ds_read_b128 v[140:143], v140 offset:3072
	ds_read_b128 v[144:147], v156
	ds_read_b128 v[148:151], v156 offset:1024
	ds_read_b128 v[152:155], v156 offset:2048
	ds_read_b128 v[156:159], v156 offset:3072
	s_add_u32 s46, s46, 0x80000
	s_addc_u32 s47, s47, 0
	s_mov_b32 m0, s49
	ds_read_b128 v[160:163], v218 offset:32768
	ds_read_b128 v[164:167], v218 offset:33792
	ds_read_b128 v[168:171], v218 offset:34816
	ds_read_b128 v[172:175], v218 offset:35840
	ds_read_b128 v[192:195], v218 offset:36864
	ds_read_b128 v[196:199], v218 offset:37888
	ds_read_b128 v[200:203], v218 offset:38912
	ds_read_b128 v[204:207], v218 offset:39936
	global_load_lds_dwordx4 v176, s[46:47]
	s_mov_b32 m0, s50
	s_nop 0
	global_load_lds_dwordx4 v180, s[46:47]
	s_waitcnt vmcnt(8)
	s_waitcnt lgkmcnt(0)
	s_setprio 1
	s_barrier
	v_mfma_f32_16x16x32_bf16 v[124:127], v[128:131], v[160:163], v[124:127]
	v_mfma_f32_16x16x32_bf16 v[120:123], v[136:139], v[160:163], v[120:123]
	v_mfma_f32_16x16x32_bf16 v[108:111], v[128:131], v[168:171], v[108:111]
	v_mfma_f32_16x16x32_bf16 v[104:107], v[136:139], v[168:171], v[104:107]
	v_mfma_f32_16x16x32_bf16 v[92:95], v[128:131], v[192:195], v[92:95]
	v_mfma_f32_16x16x32_bf16 v[88:91], v[136:139], v[192:195], v[88:91]
	v_mfma_f32_16x16x32_bf16 v[76:79], v[128:131], v[200:203], v[76:79]
	v_mfma_f32_16x16x32_bf16 v[72:75], v[136:139], v[200:203], v[72:75]
	v_mfma_f32_16x16x32_bf16 v[124:127], v[132:135], v[164:167], v[124:127]
	v_mfma_f32_16x16x32_bf16 v[120:123], v[140:143], v[164:167], v[120:123]
	v_mfma_f32_16x16x32_bf16 v[108:111], v[132:135], v[172:175], v[108:111]
	v_mfma_f32_16x16x32_bf16 v[104:107], v[140:143], v[172:175], v[104:107]
	v_mfma_f32_16x16x32_bf16 v[92:95], v[132:135], v[196:199], v[92:95]
	v_mfma_f32_16x16x32_bf16 v[88:91], v[140:143], v[196:199], v[88:91]
	v_mfma_f32_16x16x32_bf16 v[76:79], v[132:135], v[204:207], v[76:79]
	v_mfma_f32_16x16x32_bf16 v[72:75], v[140:143], v[204:207], v[72:75]
	v_mfma_f32_16x16x32_bf16 v[116:119], v[144:147], v[160:163], v[116:119]
	v_mfma_f32_16x16x32_bf16 v[112:115], v[152:155], v[160:163], v[112:115]
	v_mfma_f32_16x16x32_bf16 v[100:103], v[144:147], v[168:171], v[100:103]
	v_mfma_f32_16x16x32_bf16 v[96:99], v[152:155], v[168:171], v[96:99]
	v_mfma_f32_16x16x32_bf16 v[84:87], v[144:147], v[192:195], v[84:87]
	v_mfma_f32_16x16x32_bf16 v[80:83], v[152:155], v[192:195], v[80:83]
	v_mfma_f32_16x16x32_bf16 v[68:71], v[144:147], v[200:203], v[68:71]
	v_mfma_f32_16x16x32_bf16 v[64:67], v[152:155], v[200:203], v[64:67]
	v_mfma_f32_16x16x32_bf16 v[116:119], v[148:151], v[164:167], v[116:119]
	v_mfma_f32_16x16x32_bf16 v[112:115], v[156:159], v[164:167], v[112:115]
	v_mfma_f32_16x16x32_bf16 v[100:103], v[148:151], v[172:175], v[100:103]
	v_mfma_f32_16x16x32_bf16 v[96:99], v[156:159], v[172:175], v[96:99]
	v_mfma_f32_16x16x32_bf16 v[84:87], v[148:151], v[196:199], v[84:87]
	v_mfma_f32_16x16x32_bf16 v[80:83], v[156:159], v[196:199], v[80:83]
	v_mfma_f32_16x16x32_bf16 v[68:71], v[148:151], v[204:207], v[68:71]
	v_mfma_f32_16x16x32_bf16 v[64:67], v[156:159], v[204:207], v[64:67]
	s_barrier
	s_setprio 0
	s_add_i32 s46, s59, s31
	s_mov_b32 m0, s46
	ds_read_b128 v[160:163], v218 offset:49152
	ds_read_b128 v[164:167], v218 offset:50176
	ds_read_b128 v[168:171], v218 offset:51200
	ds_read_b128 v[172:175], v218 offset:52224
	ds_read_b128 v[192:195], v218 offset:53248
	ds_read_b128 v[196:199], v218 offset:54272
	ds_read_b128 v[200:203], v218 offset:55296
	ds_read_b128 v[204:207], v218 offset:56320
	global_load_lds_dwordx4 v178, s[98:99]
	s_add_i32 m0, s46, 0x2000
	s_add_u32 s44, s44, 0x80080
	s_addc_u32 s45, s45, 0
	s_add_i32 s46, s60, s31
	global_load_lds_dwordx4 v182, s[98:99]
	s_mov_b32 m0, s46
	s_nop 0
	global_load_lds_dwordx4 v178, s[44:45]
	s_add_i32 m0, s46, 0x2000
	s_nop 0
	global_load_lds_dwordx4 v182, s[44:45]
	s_mov_b32 m0, s52
	s_nop 0
	global_load_lds_dwordx4 v176, s[100:101]
	s_mov_b32 m0, s53
	s_nop 0
	global_load_lds_dwordx4 v180, s[100:101]
	s_waitcnt vmcnt(8)
	s_waitcnt lgkmcnt(0)
	s_setprio 1
	s_barrier
	v_mfma_f32_16x16x32_bf16 v[60:63], v[128:131], v[160:163], v[60:63]
	v_mfma_f32_16x16x32_bf16 v[56:59], v[136:139], v[160:163], v[56:59]
	v_mfma_f32_16x16x32_bf16 v[44:47], v[128:131], v[168:171], v[44:47]
	v_mfma_f32_16x16x32_bf16 v[40:43], v[136:139], v[168:171], v[40:43]
	v_mfma_f32_16x16x32_bf16 v[28:31], v[128:131], v[192:195], v[28:31]
	v_mfma_f32_16x16x32_bf16 v[24:27], v[136:139], v[192:195], v[24:27]
	v_mfma_f32_16x16x32_bf16 v[12:15], v[128:131], v[200:203], v[12:15]
	v_mfma_f32_16x16x32_bf16 v[8:11], v[136:139], v[200:203], v[8:11]
	v_mfma_f32_16x16x32_bf16 v[60:63], v[132:135], v[164:167], v[60:63]
	v_mfma_f32_16x16x32_bf16 v[56:59], v[140:143], v[164:167], v[56:59]
	v_mfma_f32_16x16x32_bf16 v[44:47], v[132:135], v[172:175], v[44:47]
	v_mfma_f32_16x16x32_bf16 v[40:43], v[140:143], v[172:175], v[40:43]
	v_mfma_f32_16x16x32_bf16 v[28:31], v[132:135], v[196:199], v[28:31]
	v_mfma_f32_16x16x32_bf16 v[24:27], v[140:143], v[196:199], v[24:27]
	v_mfma_f32_16x16x32_bf16 v[12:15], v[132:135], v[204:207], v[12:15]
	v_mfma_f32_16x16x32_bf16 v[8:11], v[140:143], v[204:207], v[8:11]
	v_mfma_f32_16x16x32_bf16 v[52:55], v[144:147], v[160:163], v[52:55]
	v_mfma_f32_16x16x32_bf16 v[48:51], v[152:155], v[160:163], v[48:51]
	v_mfma_f32_16x16x32_bf16 v[36:39], v[144:147], v[168:171], v[36:39]
	v_mfma_f32_16x16x32_bf16 v[32:35], v[152:155], v[168:171], v[32:35]
	v_mfma_f32_16x16x32_bf16 v[20:23], v[144:147], v[192:195], v[20:23]
	v_mfma_f32_16x16x32_bf16 v[16:19], v[152:155], v[192:195], v[16:19]
	v_mfma_f32_16x16x32_bf16 v[4:7], v[144:147], v[200:203], v[4:7]
	v_mfma_f32_16x16x32_bf16 v[0:3], v[152:155], v[200:203], v[0:3]
	v_mfma_f32_16x16x32_bf16 v[52:55], v[148:151], v[164:167], v[52:55]
	v_mfma_f32_16x16x32_bf16 v[48:51], v[156:159], v[164:167], v[48:51]
	v_mfma_f32_16x16x32_bf16 v[36:39], v[148:151], v[172:175], v[36:39]
	v_mfma_f32_16x16x32_bf16 v[32:35], v[156:159], v[172:175], v[32:35]
	v_mfma_f32_16x16x32_bf16 v[20:23], v[148:151], v[196:199], v[20:23]
	v_mfma_f32_16x16x32_bf16 v[16:19], v[156:159], v[196:199], v[16:19]
	v_mfma_f32_16x16x32_bf16 v[4:7], v[148:151], v[204:207], v[4:7]
	v_mfma_f32_16x16x32_bf16 v[0:3], v[156:159], v[204:207], v[0:3]
	s_barrier
	s_setprio 0
	s_add_i32 s58, s58, 2
	s_add_u32 s42, s42, 0x100
	s_addc_u32 s43, s43, 0
	s_add_u32 s25, s25, 0x100
	s_addc_u32 s35, s35, 0
	s_cmp_gt_u32 s58, 29
.LBB0_543:
	ds_read_b128 v[128:131], v216
	ds_read_b128 v[132:135], v216 offset:1024
	ds_read_b128 v[136:139], v216 offset:2048
	ds_read_b128 v[140:143], v216 offset:3072
	ds_read_b128 v[144:147], v217
	ds_read_b128 v[148:151], v217 offset:1024
	ds_read_b128 v[152:155], v217 offset:2048
	ds_read_b128 v[156:159], v217 offset:3072
	s_add_u32 s44, s42, 0xfff80080
	s_addc_u32 s45, s43, -1
	s_cmp_eq_u32 s58, 28
	s_cselect_b32 s47, s0, s45
	s_cselect_b32 s46, s1, s44
	s_cselect_b32 s45, s3, s35
	s_cselect_b32 s44, s9, s25
	s_add_i32 m0, s41, 0xc000
	ds_read_b128 v[160:163], v218
	ds_read_b128 v[164:167], v218 offset:1024
	ds_read_b128 v[168:171], v218 offset:2048
	ds_read_b128 v[172:175], v218 offset:3072
	ds_read_b128 v[192:195], v218 offset:4096
	ds_read_b128 v[196:199], v218 offset:5120
	ds_read_b128 v[200:203], v218 offset:6144
	ds_read_b128 v[204:207], v218 offset:7168
	global_load_lds_dwordx4 v184, s[42:43]
	s_add_i32 m0, s41, 0xe000
	s_nop 0
	global_load_lds_dwordx4 v186, s[42:43]
	s_waitcnt vmcnt(8)
	s_waitcnt lgkmcnt(0)
	s_setprio 1
	s_barrier
	v_mfma_f32_16x16x32_bf16 v[124:127], v[128:131], v[160:163], v[124:127]
	v_mfma_f32_16x16x32_bf16 v[120:123], v[136:139], v[160:163], v[120:123]
	v_mfma_f32_16x16x32_bf16 v[108:111], v[128:131], v[168:171], v[108:111]
	v_mfma_f32_16x16x32_bf16 v[104:107], v[136:139], v[168:171], v[104:107]
	v_mfma_f32_16x16x32_bf16 v[92:95], v[128:131], v[192:195], v[92:95]
	v_mfma_f32_16x16x32_bf16 v[88:91], v[136:139], v[192:195], v[88:91]
	v_mfma_f32_16x16x32_bf16 v[76:79], v[128:131], v[200:203], v[76:79]
	v_mfma_f32_16x16x32_bf16 v[72:75], v[136:139], v[200:203], v[72:75]
	v_mfma_f32_16x16x32_bf16 v[124:127], v[132:135], v[164:167], v[124:127]
	v_mfma_f32_16x16x32_bf16 v[120:123], v[140:143], v[164:167], v[120:123]
	v_mfma_f32_16x16x32_bf16 v[108:111], v[132:135], v[172:175], v[108:111]
	v_mfma_f32_16x16x32_bf16 v[104:107], v[140:143], v[172:175], v[104:107]
	v_mfma_f32_16x16x32_bf16 v[92:95], v[132:135], v[196:199], v[92:95]
	v_mfma_f32_16x16x32_bf16 v[88:91], v[140:143], v[196:199], v[88:91]
	v_mfma_f32_16x16x32_bf16 v[76:79], v[132:135], v[204:207], v[76:79]
	v_mfma_f32_16x16x32_bf16 v[72:75], v[140:143], v[204:207], v[72:75]
	v_mfma_f32_16x16x32_bf16 v[116:119], v[144:147], v[160:163], v[116:119]
	v_mfma_f32_16x16x32_bf16 v[112:115], v[152:155], v[160:163], v[112:115]
	v_mfma_f32_16x16x32_bf16 v[100:103], v[144:147], v[168:171], v[100:103]
	v_mfma_f32_16x16x32_bf16 v[96:99], v[152:155], v[168:171], v[96:99]
	v_mfma_f32_16x16x32_bf16 v[84:87], v[144:147], v[192:195], v[84:87]
	v_mfma_f32_16x16x32_bf16 v[80:83], v[152:155], v[192:195], v[80:83]
	v_mfma_f32_16x16x32_bf16 v[68:71], v[144:147], v[200:203], v[68:71]
	v_mfma_f32_16x16x32_bf16 v[64:67], v[152:155], v[200:203], v[64:67]
	v_mfma_f32_16x16x32_bf16 v[116:119], v[148:151], v[164:167], v[116:119]
	v_mfma_f32_16x16x32_bf16 v[112:115], v[156:159], v[164:167], v[112:115]
	v_mfma_f32_16x16x32_bf16 v[100:103], v[148:151], v[172:175], v[100:103]
	v_mfma_f32_16x16x32_bf16 v[96:99], v[156:159], v[172:175], v[96:99]
	v_mfma_f32_16x16x32_bf16 v[84:87], v[148:151], v[196:199], v[84:87]
	v_mfma_f32_16x16x32_bf16 v[80:83], v[156:159], v[196:199], v[80:83]
	v_mfma_f32_16x16x32_bf16 v[68:71], v[148:151], v[204:207], v[68:71]
	v_mfma_f32_16x16x32_bf16 v[64:67], v[156:159], v[204:207], v[64:67]
	s_barrier
	s_setprio 0
	s_add_i32 s59, s55, s31
	s_add_u32 s98, s44, s20
	s_addc_u32 s99, s45, s21
	s_mov_b32 m0, s59
	ds_read_b128 v[160:163], v218 offset:16384
	ds_read_b128 v[164:167], v218 offset:17408
	ds_read_b128 v[168:171], v218 offset:18432
	ds_read_b128 v[172:175], v218 offset:19456
	ds_read_b128 v[192:195], v218 offset:20480
	ds_read_b128 v[196:199], v218 offset:21504
	ds_read_b128 v[200:203], v218 offset:22528
	ds_read_b128 v[204:207], v218 offset:23552
	global_load_lds_dwordx4 v178, s[44:45]
	s_add_i32 m0, s59, 0x2000
	s_add_u32 s60, s44, 0x80000
	s_addc_u32 s61, s45, 0
	s_add_i32 s59, s56, s31
	global_load_lds_dwordx4 v182, s[44:45]
	s_mov_b32 m0, s59
	s_add_u32 s100, s46, s20
	s_addc_u32 s101, s47, s21
	global_load_lds_dwordx4 v178, s[60:61]
	s_add_i32 m0, s59, 0x2000
	s_nop 0
	global_load_lds_dwordx4 v182, s[60:61]
	s_mov_b32 m0, s41
	s_nop 0
	global_load_lds_dwordx4 v176, s[46:47]
	s_mov_b32 m0, s48
	s_nop 0
	global_load_lds_dwordx4 v180, s[46:47]
	s_waitcnt vmcnt(8)
	s_waitcnt lgkmcnt(0)
	s_setprio 1
	s_barrier
	v_mfma_f32_16x16x32_bf16 v[60:63], v[128:131], v[160:163], v[60:63]
	v_mfma_f32_16x16x32_bf16 v[56:59], v[136:139], v[160:163], v[56:59]
	v_mfma_f32_16x16x32_bf16 v[44:47], v[128:131], v[168:171], v[44:47]
	v_mfma_f32_16x16x32_bf16 v[40:43], v[136:139], v[168:171], v[40:43]
	v_mfma_f32_16x16x32_bf16 v[28:31], v[128:131], v[192:195], v[28:31]
	v_mfma_f32_16x16x32_bf16 v[24:27], v[136:139], v[192:195], v[24:27]
	v_mfma_f32_16x16x32_bf16 v[12:15], v[128:131], v[200:203], v[12:15]
	v_mfma_f32_16x16x32_bf16 v[8:11], v[136:139], v[200:203], v[8:11]
	v_mfma_f32_16x16x32_bf16 v[60:63], v[132:135], v[164:167], v[60:63]
	v_mfma_f32_16x16x32_bf16 v[56:59], v[140:143], v[164:167], v[56:59]
	v_mfma_f32_16x16x32_bf16 v[44:47], v[132:135], v[172:175], v[44:47]
	v_mfma_f32_16x16x32_bf16 v[40:43], v[140:143], v[172:175], v[40:43]
	v_mfma_f32_16x16x32_bf16 v[28:31], v[132:135], v[196:199], v[28:31]
	v_mfma_f32_16x16x32_bf16 v[24:27], v[140:143], v[196:199], v[24:27]
	v_mfma_f32_16x16x32_bf16 v[12:15], v[132:135], v[204:207], v[12:15]
	v_mfma_f32_16x16x32_bf16 v[8:11], v[140:143], v[204:207], v[8:11]
	v_mfma_f32_16x16x32_bf16 v[52:55], v[144:147], v[160:163], v[52:55]
	v_mfma_f32_16x16x32_bf16 v[48:51], v[152:155], v[160:163], v[48:51]
	v_mfma_f32_16x16x32_bf16 v[36:39], v[144:147], v[168:171], v[36:39]
	v_mfma_f32_16x16x32_bf16 v[32:35], v[152:155], v[168:171], v[32:35]
	v_mfma_f32_16x16x32_bf16 v[20:23], v[144:147], v[192:195], v[20:23]
	v_mfma_f32_16x16x32_bf16 v[16:19], v[152:155], v[192:195], v[16:19]
	v_mfma_f32_16x16x32_bf16 v[4:7], v[144:147], v[200:203], v[4:7]
	v_mfma_f32_16x16x32_bf16 v[0:3], v[152:155], v[200:203], v[0:3]
	v_mfma_f32_16x16x32_bf16 v[52:55], v[148:151], v[164:167], v[52:55]
	v_mfma_f32_16x16x32_bf16 v[48:51], v[156:159], v[164:167], v[48:51]
	v_mfma_f32_16x16x32_bf16 v[36:39], v[148:151], v[172:175], v[36:39]
	v_mfma_f32_16x16x32_bf16 v[32:35], v[156:159], v[172:175], v[32:35]
	v_mfma_f32_16x16x32_bf16 v[20:23], v[148:151], v[196:199], v[20:23]
	v_mfma_f32_16x16x32_bf16 v[16:19], v[156:159], v[196:199], v[16:19]
	v_mfma_f32_16x16x32_bf16 v[4:7], v[148:151], v[204:207], v[4:7]
	v_mfma_f32_16x16x32_bf16 v[0:3], v[156:159], v[204:207], v[0:3]
	s_barrier
	s_setprio 0
	s_add_i32 s59, 0, 0x18000
	s_add_i32 s60, 0, 0x1c000
	v_add_u32_e32 v140, s59, v214
	v_add_u32_e32 v156, s60, v214
	ds_read_b128 v[128:131], v140
	ds_read_b128 v[132:135], v140 offset:1024
	ds_read_b128 v[136:139], v140 offset:2048
	ds_read_b128 v[140:143], v140 offset:3072
	ds_read_b128 v[144:147], v156
	ds_read_b128 v[148:151], v156 offset:1024
	ds_read_b128 v[152:155], v156 offset:2048
	ds_read_b128 v[156:159], v156 offset:3072
	s_add_u32 s46, s46, 0x80000
	s_addc_u32 s47, s47, 0
	s_mov_b32 m0, s49
	ds_read_b128 v[160:163], v218 offset:32768
	ds_read_b128 v[164:167], v218 offset:33792
	ds_read_b128 v[168:171], v218 offset:34816
	ds_read_b128 v[172:175], v218 offset:35840
	ds_read_b128 v[192:195], v218 offset:36864
	ds_read_b128 v[196:199], v218 offset:37888
	ds_read_b128 v[200:203], v218 offset:38912
	ds_read_b128 v[204:207], v218 offset:39936
	global_load_lds_dwordx4 v176, s[46:47]
	s_mov_b32 m0, s50
	s_nop 0
	global_load_lds_dwordx4 v180, s[46:47]
	s_waitcnt vmcnt(8)
	s_waitcnt lgkmcnt(0)
	s_setprio 1
	s_barrier
	v_mfma_f32_16x16x32_bf16 v[124:127], v[128:131], v[160:163], v[124:127]
	v_mfma_f32_16x16x32_bf16 v[120:123], v[136:139], v[160:163], v[120:123]
	v_mfma_f32_16x16x32_bf16 v[108:111], v[128:131], v[168:171], v[108:111]
	v_mfma_f32_16x16x32_bf16 v[104:107], v[136:139], v[168:171], v[104:107]
	v_mfma_f32_16x16x32_bf16 v[92:95], v[128:131], v[192:195], v[92:95]
	v_mfma_f32_16x16x32_bf16 v[88:91], v[136:139], v[192:195], v[88:91]
	v_mfma_f32_16x16x32_bf16 v[76:79], v[128:131], v[200:203], v[76:79]
	v_mfma_f32_16x16x32_bf16 v[72:75], v[136:139], v[200:203], v[72:75]
	v_mfma_f32_16x16x32_bf16 v[124:127], v[132:135], v[164:167], v[124:127]
	v_mfma_f32_16x16x32_bf16 v[120:123], v[140:143], v[164:167], v[120:123]
	v_mfma_f32_16x16x32_bf16 v[108:111], v[132:135], v[172:175], v[108:111]
	v_mfma_f32_16x16x32_bf16 v[104:107], v[140:143], v[172:175], v[104:107]
	v_mfma_f32_16x16x32_bf16 v[92:95], v[132:135], v[196:199], v[92:95]
	v_mfma_f32_16x16x32_bf16 v[88:91], v[140:143], v[196:199], v[88:91]
	v_mfma_f32_16x16x32_bf16 v[76:79], v[132:135], v[204:207], v[76:79]
	v_mfma_f32_16x16x32_bf16 v[72:75], v[140:143], v[204:207], v[72:75]
	v_mfma_f32_16x16x32_bf16 v[116:119], v[144:147], v[160:163], v[116:119]
	v_mfma_f32_16x16x32_bf16 v[112:115], v[152:155], v[160:163], v[112:115]
	v_mfma_f32_16x16x32_bf16 v[100:103], v[144:147], v[168:171], v[100:103]
	v_mfma_f32_16x16x32_bf16 v[96:99], v[152:155], v[168:171], v[96:99]
	v_mfma_f32_16x16x32_bf16 v[84:87], v[144:147], v[192:195], v[84:87]
	v_mfma_f32_16x16x32_bf16 v[80:83], v[152:155], v[192:195], v[80:83]
	v_mfma_f32_16x16x32_bf16 v[68:71], v[144:147], v[200:203], v[68:71]
	v_mfma_f32_16x16x32_bf16 v[64:67], v[152:155], v[200:203], v[64:67]
	v_mfma_f32_16x16x32_bf16 v[116:119], v[148:151], v[164:167], v[116:119]
	v_mfma_f32_16x16x32_bf16 v[112:115], v[156:159], v[164:167], v[112:115]
	v_mfma_f32_16x16x32_bf16 v[100:103], v[148:151], v[172:175], v[100:103]
	v_mfma_f32_16x16x32_bf16 v[96:99], v[156:159], v[172:175], v[96:99]
	v_mfma_f32_16x16x32_bf16 v[84:87], v[148:151], v[196:199], v[84:87]
	v_mfma_f32_16x16x32_bf16 v[80:83], v[156:159], v[196:199], v[80:83]
	v_mfma_f32_16x16x32_bf16 v[68:71], v[148:151], v[204:207], v[68:71]
	v_mfma_f32_16x16x32_bf16 v[64:67], v[156:159], v[204:207], v[64:67]
	s_barrier
	s_setprio 0
	s_add_i32 s46, s59, s31
	s_mov_b32 m0, s46
	ds_read_b128 v[160:163], v218 offset:49152
	ds_read_b128 v[164:167], v218 offset:50176
	ds_read_b128 v[168:171], v218 offset:51200
	ds_read_b128 v[172:175], v218 offset:52224
	ds_read_b128 v[192:195], v218 offset:53248
	ds_read_b128 v[196:199], v218 offset:54272
	ds_read_b128 v[200:203], v218 offset:55296
	ds_read_b128 v[204:207], v218 offset:56320
	global_load_lds_dwordx4 v178, s[98:99]
	s_add_i32 m0, s46, 0x2000
	s_add_u32 s44, s44, 0x80080
	s_addc_u32 s45, s45, 0
	s_add_i32 s46, s60, s31
	global_load_lds_dwordx4 v182, s[98:99]
	s_mov_b32 m0, s46
	s_nop 0
	global_load_lds_dwordx4 v178, s[44:45]
	s_add_i32 m0, s46, 0x2000
	s_nop 0
	global_load_lds_dwordx4 v182, s[44:45]
	s_mov_b32 m0, s52
	s_nop 0
	global_load_lds_dwordx4 v176, s[100:101]
	s_mov_b32 m0, s53
	s_nop 0
	global_load_lds_dwordx4 v180, s[100:101]
	s_waitcnt vmcnt(8)
	s_waitcnt lgkmcnt(0)
	s_setprio 1
	s_barrier
	v_mfma_f32_16x16x32_bf16 v[60:63], v[128:131], v[160:163], v[60:63]
	v_mfma_f32_16x16x32_bf16 v[56:59], v[136:139], v[160:163], v[56:59]
	v_mfma_f32_16x16x32_bf16 v[44:47], v[128:131], v[168:171], v[44:47]
	v_mfma_f32_16x16x32_bf16 v[40:43], v[136:139], v[168:171], v[40:43]
	v_mfma_f32_16x16x32_bf16 v[28:31], v[128:131], v[192:195], v[28:31]
	v_mfma_f32_16x16x32_bf16 v[24:27], v[136:139], v[192:195], v[24:27]
	v_mfma_f32_16x16x32_bf16 v[12:15], v[128:131], v[200:203], v[12:15]
	v_mfma_f32_16x16x32_bf16 v[8:11], v[136:139], v[200:203], v[8:11]
	v_mfma_f32_16x16x32_bf16 v[60:63], v[132:135], v[164:167], v[60:63]
	v_mfma_f32_16x16x32_bf16 v[56:59], v[140:143], v[164:167], v[56:59]
	v_mfma_f32_16x16x32_bf16 v[44:47], v[132:135], v[172:175], v[44:47]
	v_mfma_f32_16x16x32_bf16 v[40:43], v[140:143], v[172:175], v[40:43]
	v_mfma_f32_16x16x32_bf16 v[28:31], v[132:135], v[196:199], v[28:31]
	v_mfma_f32_16x16x32_bf16 v[24:27], v[140:143], v[196:199], v[24:27]
	v_mfma_f32_16x16x32_bf16 v[12:15], v[132:135], v[204:207], v[12:15]
	v_mfma_f32_16x16x32_bf16 v[8:11], v[140:143], v[204:207], v[8:11]
	v_mfma_f32_16x16x32_bf16 v[52:55], v[144:147], v[160:163], v[52:55]
	v_mfma_f32_16x16x32_bf16 v[48:51], v[152:155], v[160:163], v[48:51]
	v_mfma_f32_16x16x32_bf16 v[36:39], v[144:147], v[168:171], v[36:39]
	v_mfma_f32_16x16x32_bf16 v[32:35], v[152:155], v[168:171], v[32:35]
	v_mfma_f32_16x16x32_bf16 v[20:23], v[144:147], v[192:195], v[20:23]
	v_mfma_f32_16x16x32_bf16 v[16:19], v[152:155], v[192:195], v[16:19]
	v_mfma_f32_16x16x32_bf16 v[4:7], v[144:147], v[200:203], v[4:7]
	v_mfma_f32_16x16x32_bf16 v[0:3], v[152:155], v[200:203], v[0:3]
	v_mfma_f32_16x16x32_bf16 v[52:55], v[148:151], v[164:167], v[52:55]
	v_mfma_f32_16x16x32_bf16 v[48:51], v[156:159], v[164:167], v[48:51]
	v_mfma_f32_16x16x32_bf16 v[36:39], v[148:151], v[172:175], v[36:39]
	v_mfma_f32_16x16x32_bf16 v[32:35], v[156:159], v[172:175], v[32:35]
	v_mfma_f32_16x16x32_bf16 v[20:23], v[148:151], v[196:199], v[20:23]
	v_mfma_f32_16x16x32_bf16 v[16:19], v[156:159], v[196:199], v[16:19]
	v_mfma_f32_16x16x32_bf16 v[4:7], v[148:151], v[204:207], v[4:7]
	v_mfma_f32_16x16x32_bf16 v[0:3], v[156:159], v[204:207], v[0:3]
	s_barrier
	s_setprio 0
	s_add_i32 s58, s58, 2
	s_add_u32 s42, s42, 0x100
	s_addc_u32 s43, s43, 0
	s_add_u32 s25, s25, 0x100
	s_addc_u32 s35, s35, 0
	s_cmp_gt_u32 s58, 29
	s_cbranch_scc0 .LBB0_543
	s_and_b64 vcc, exec, s[22:23]
	s_cbranch_vccz .LBB0_546
	s_barrier

.LBB0_635:
	s_ashr_i32 s67, s66, 31
	s_lshl_b64 s[12:13], s[66:67], 20
	s_add_u32 s70, s55, s12
	s_addc_u32 s71, s57, s13
	s_and_b64 s[6:7], s[6:7], exec
	s_cselect_b32 s1, s71, s11
	s_cselect_b32 s3, s70, s10
	s_add_u32 s6, s8, 0x80080
	s_addc_u32 s7, s9, 0
	s_add_u32 s12, s10, 0x100
	s_addc_u32 s13, s11, 0
	s_mov_b32 s15, -2
	s_waitcnt vmcnt(0)
	ds_read_b128 v[148:151], v197
	ds_read_b128 v[170:173], v197 offset:1024
	ds_read_b128 v[174:177], v197 offset:2048
	ds_read_b128 v[178:181], v197 offset:3072
	ds_read_b128 v[182:185], v198
	ds_read_b128 v[186:189], v198 offset:1024
	ds_read_b128 v[202:205], v198 offset:2048
	ds_read_b128 v[206:209], v198 offset:3072
	s_add_u32 s8, s6, 0xfff80080
	s_addc_u32 s9, s7, -1
	s_cmp_eq_u32 s15, 28
	s_cselect_b32 s11, s69, s9
	s_cselect_b32 s10, s68, s8
	s_cselect_b32 s9, s1, s13
	s_cselect_b32 s8, s3, s12
	s_add_i32 m0, s72, 0xc000
	ds_read_b128 v[214:217], v199
	ds_read_b128 v[218:221], v199 offset:1024
	ds_read_b128 v[222:225], v199 offset:2048
	ds_read_b128 v[226:229], v199 offset:3072
	ds_read_b128 v[230:233], v199 offset:4096
	ds_read_b128 v[234:237], v199 offset:5120
	ds_read_b128 v[238:241], v199 offset:6144
	ds_read_b128 v[242:245], v199 offset:7168
	global_load_lds_dwordx4 v162, s[6:7]
	s_add_i32 m0, s72, 0xe000
	s_nop 0
	global_load_lds_dwordx4 v164, s[6:7]
	s_waitcnt vmcnt(8)
	s_waitcnt lgkmcnt(0)
	s_setprio 1
	s_barrier
	v_mfma_f32_16x16x32_bf16 v[112:115], v[148:151], v[214:217], 0
	v_mfma_f32_16x16x32_bf16 v[80:83], v[174:177], v[214:217], 0
	v_mfma_f32_16x16x32_bf16 v[116:119], v[148:151], v[222:225], 0
	v_mfma_f32_16x16x32_bf16 v[88:91], v[174:177], v[222:225], 0
	v_mfma_f32_16x16x32_bf16 v[124:127], v[148:151], v[230:233], 0
	v_mfma_f32_16x16x32_bf16 v[92:95], v[174:177], v[230:233], 0
	v_mfma_f32_16x16x32_bf16 v[120:123], v[148:151], v[238:241], 0
	v_mfma_f32_16x16x32_bf16 v[84:87], v[174:177], v[238:241], 0
	v_mfma_f32_16x16x32_bf16 v[112:115], v[170:173], v[218:221], v[112:115]
	v_mfma_f32_16x16x32_bf16 v[80:83], v[178:181], v[218:221], v[80:83]
	v_mfma_f32_16x16x32_bf16 v[116:119], v[170:173], v[226:229], v[116:119]
	v_mfma_f32_16x16x32_bf16 v[88:91], v[178:181], v[226:229], v[88:91]
	v_mfma_f32_16x16x32_bf16 v[124:127], v[170:173], v[234:237], v[124:127]
	v_mfma_f32_16x16x32_bf16 v[92:95], v[178:181], v[234:237], v[92:95]
	v_mfma_f32_16x16x32_bf16 v[120:123], v[170:173], v[242:245], v[120:123]
	v_mfma_f32_16x16x32_bf16 v[84:87], v[178:181], v[242:245], v[84:87]
	v_mfma_f32_16x16x32_bf16 v[108:111], v[182:185], v[214:217], 0
	v_mfma_f32_16x16x32_bf16 v[76:79], v[202:205], v[214:217], 0
	v_mfma_f32_16x16x32_bf16 v[104:107], v[182:185], v[222:225], 0
	v_mfma_f32_16x16x32_bf16 v[72:75], v[202:205], v[222:225], 0
	v_mfma_f32_16x16x32_bf16 v[100:103], v[182:185], v[230:233], 0
	v_mfma_f32_16x16x32_bf16 v[68:71], v[202:205], v[230:233], 0
	v_mfma_f32_16x16x32_bf16 v[96:99], v[182:185], v[238:241], 0
	v_mfma_f32_16x16x32_bf16 v[64:67], v[202:205], v[238:241], 0
	v_mfma_f32_16x16x32_bf16 v[108:111], v[186:189], v[218:221], v[108:111]
	v_mfma_f32_16x16x32_bf16 v[76:79], v[206:209], v[218:221], v[76:79]
	v_mfma_f32_16x16x32_bf16 v[104:107], v[186:189], v[226:229], v[104:107]
	v_mfma_f32_16x16x32_bf16 v[72:75], v[206:209], v[226:229], v[72:75]
	v_mfma_f32_16x16x32_bf16 v[100:103], v[186:189], v[234:237], v[100:103]
	v_mfma_f32_16x16x32_bf16 v[68:71], v[206:209], v[234:237], v[68:71]
	v_mfma_f32_16x16x32_bf16 v[96:99], v[186:189], v[242:245], v[96:99]
	v_mfma_f32_16x16x32_bf16 v[64:67], v[206:209], v[242:245], v[64:67]
	s_barrier
	s_setprio 0
	s_add_i32 s16, s94, s63
	s_add_u32 s98, s8, s40
	s_addc_u32 s99, s9, s41
	s_mov_b32 m0, s16
	ds_read_b128 v[214:217], v199 offset:16384
	ds_read_b128 v[218:221], v199 offset:17408
	ds_read_b128 v[222:225], v199 offset:18432
	ds_read_b128 v[226:229], v199 offset:19456
	ds_read_b128 v[230:233], v199 offset:20480
	ds_read_b128 v[234:237], v199 offset:21504
	ds_read_b128 v[238:241], v199 offset:22528
	ds_read_b128 v[242:245], v199 offset:23552
	global_load_lds_dwordx4 v154, s[8:9]
	s_add_i32 m0, s16, 0x2000
	s_add_u32 s16, s8, 0x80000
	s_addc_u32 s17, s9, 0
	s_add_i32 s18, s95, s63
	global_load_lds_dwordx4 v158, s[8:9]
	s_mov_b32 m0, s18
	s_add_u32 s100, s10, s40
	s_addc_u32 s101, s11, s41
	global_load_lds_dwordx4 v154, s[16:17]
	s_add_i32 m0, s18, 0x2000
	s_nop 0
	global_load_lds_dwordx4 v158, s[16:17]
	s_mov_b32 m0, s72
	s_nop 0
	global_load_lds_dwordx4 v152, s[10:11]
	s_mov_b32 m0, s73
	s_nop 0
	global_load_lds_dwordx4 v156, s[10:11]
	s_waitcnt vmcnt(8)
	s_waitcnt lgkmcnt(0)
	s_setprio 1
	s_barrier
	v_mfma_f32_16x16x32_bf16 v[48:51], v[148:151], v[214:217], 0
	v_mfma_f32_16x16x32_bf16 v[16:19], v[174:177], v[214:217], 0
	v_mfma_f32_16x16x32_bf16 v[52:55], v[148:151], v[222:225], 0
	v_mfma_f32_16x16x32_bf16 v[24:27], v[174:177], v[222:225], 0
	v_mfma_f32_16x16x32_bf16 v[60:63], v[148:151], v[230:233], 0
	v_mfma_f32_16x16x32_bf16 v[28:31], v[174:177], v[230:233], 0
	v_mfma_f32_16x16x32_bf16 v[56:59], v[148:151], v[238:241], 0
	v_mfma_f32_16x16x32_bf16 v[20:23], v[174:177], v[238:241], 0
	v_mfma_f32_16x16x32_bf16 v[48:51], v[170:173], v[218:221], v[48:51]
	v_mfma_f32_16x16x32_bf16 v[16:19], v[178:181], v[218:221], v[16:19]
	v_mfma_f32_16x16x32_bf16 v[52:55], v[170:173], v[226:229], v[52:55]
	v_mfma_f32_16x16x32_bf16 v[24:27], v[178:181], v[226:229], v[24:27]
	v_mfma_f32_16x16x32_bf16 v[60:63], v[170:173], v[234:237], v[60:63]
	v_mfma_f32_16x16x32_bf16 v[28:31], v[178:181], v[234:237], v[28:31]
	v_mfma_f32_16x16x32_bf16 v[56:59], v[170:173], v[242:245], v[56:59]
	v_mfma_f32_16x16x32_bf16 v[20:23], v[178:181], v[242:245], v[20:23]
	v_mfma_f32_16x16x32_bf16 v[44:47], v[182:185], v[214:217], 0
	v_mfma_f32_16x16x32_bf16 v[12:15], v[202:205], v[214:217], 0
	v_mfma_f32_16x16x32_bf16 v[40:43], v[182:185], v[222:225], 0
	v_mfma_f32_16x16x32_bf16 v[8:11], v[202:205], v[222:225], 0
	v_mfma_f32_16x16x32_bf16 v[36:39], v[182:185], v[230:233], 0
	v_mfma_f32_16x16x32_bf16 v[4:7], v[202:205], v[230:233], 0
	v_mfma_f32_16x16x32_bf16 v[32:35], v[182:185], v[238:241], 0
	v_mfma_f32_16x16x32_bf16 v[0:3], v[202:205], v[238:241], 0
	v_mfma_f32_16x16x32_bf16 v[44:47], v[186:189], v[218:221], v[44:47]
	v_mfma_f32_16x16x32_bf16 v[12:15], v[206:209], v[218:221], v[12:15]
	v_mfma_f32_16x16x32_bf16 v[40:43], v[186:189], v[226:229], v[40:43]
	v_mfma_f32_16x16x32_bf16 v[8:11], v[206:209], v[226:229], v[8:11]
	v_mfma_f32_16x16x32_bf16 v[36:39], v[186:189], v[234:237], v[36:39]
	v_mfma_f32_16x16x32_bf16 v[4:7], v[206:209], v[234:237], v[4:7]
	v_mfma_f32_16x16x32_bf16 v[32:35], v[186:189], v[242:245], v[32:35]
	v_mfma_f32_16x16x32_bf16 v[0:3], v[206:209], v[242:245], v[0:3]
	s_barrier
	s_setprio 0
	s_add_i32 s16, 0, 0x18000
	s_add_i32 s17, 0, 0x1c000
	v_add_u32_e32 v178, s16, v196
	v_add_u32_e32 v201, s17, v196
	ds_read_b128 v[148:151], v178
	ds_read_b128 v[170:173], v178 offset:1024
	ds_read_b128 v[174:177], v178 offset:2048
	ds_read_b128 v[178:181], v178 offset:3072
	ds_read_b128 v[182:185], v201
	ds_read_b128 v[186:189], v201 offset:1024
	ds_read_b128 v[202:205], v201 offset:2048
	ds_read_b128 v[206:209], v201 offset:3072
	s_add_u32 s10, s10, 0x80000
	s_addc_u32 s11, s11, 0
	s_mov_b32 m0, s74
	ds_read_b128 v[214:217], v199 offset:32768
	ds_read_b128 v[218:221], v199 offset:33792
	ds_read_b128 v[222:225], v199 offset:34816
	ds_read_b128 v[226:229], v199 offset:35840
	ds_read_b128 v[230:233], v199 offset:36864
	ds_read_b128 v[234:237], v199 offset:37888
	ds_read_b128 v[238:241], v199 offset:38912
	ds_read_b128 v[242:245], v199 offset:39936
	global_load_lds_dwordx4 v152, s[10:11]
	s_mov_b32 m0, s75
	s_nop 0
	global_load_lds_dwordx4 v156, s[10:11]
	s_waitcnt vmcnt(8)
	s_waitcnt lgkmcnt(0)
	s_setprio 1
	s_barrier
	v_mfma_f32_16x16x32_bf16 v[112:115], v[148:151], v[214:217], v[112:115]
	v_mfma_f32_16x16x32_bf16 v[80:83], v[174:177], v[214:217], v[80:83]
	v_mfma_f32_16x16x32_bf16 v[116:119], v[148:151], v[222:225], v[116:119]
	v_mfma_f32_16x16x32_bf16 v[88:91], v[174:177], v[222:225], v[88:91]
	v_mfma_f32_16x16x32_bf16 v[124:127], v[148:151], v[230:233], v[124:127]
	v_mfma_f32_16x16x32_bf16 v[92:95], v[174:177], v[230:233], v[92:95]
	v_mfma_f32_16x16x32_bf16 v[120:123], v[148:151], v[238:241], v[120:123]
	v_mfma_f32_16x16x32_bf16 v[84:87], v[174:177], v[238:241], v[84:87]
	v_mfma_f32_16x16x32_bf16 v[112:115], v[170:173], v[218:221], v[112:115]
	v_mfma_f32_16x16x32_bf16 v[80:83], v[178:181], v[218:221], v[80:83]
	v_mfma_f32_16x16x32_bf16 v[116:119], v[170:173], v[226:229], v[116:119]
	v_mfma_f32_16x16x32_bf16 v[88:91], v[178:181], v[226:229], v[88:91]
	v_mfma_f32_16x16x32_bf16 v[124:127], v[170:173], v[234:237], v[124:127]
	v_mfma_f32_16x16x32_bf16 v[92:95], v[178:181], v[234:237], v[92:95]
	v_mfma_f32_16x16x32_bf16 v[120:123], v[170:173], v[242:245], v[120:123]
	v_mfma_f32_16x16x32_bf16 v[84:87], v[178:181], v[242:245], v[84:87]
	v_mfma_f32_16x16x32_bf16 v[108:111], v[182:185], v[214:217], v[108:111]
	v_mfma_f32_16x16x32_bf16 v[76:79], v[202:205], v[214:217], v[76:79]
	v_mfma_f32_16x16x32_bf16 v[104:107], v[182:185], v[222:225], v[104:107]
	v_mfma_f32_16x16x32_bf16 v[72:75], v[202:205], v[222:225], v[72:75]
	v_mfma_f32_16x16x32_bf16 v[100:103], v[182:185], v[230:233], v[100:103]
	v_mfma_f32_16x16x32_bf16 v[68:71], v[202:205], v[230:233], v[68:71]
	v_mfma_f32_16x16x32_bf16 v[96:99], v[182:185], v[238:241], v[96:99]
	v_mfma_f32_16x16x32_bf16 v[64:67], v[202:205], v[238:241], v[64:67]
	v_mfma_f32_16x16x32_bf16 v[108:111], v[186:189], v[218:221], v[108:111]
	v_mfma_f32_16x16x32_bf16 v[76:79], v[206:209], v[218:221], v[76:79]
	v_mfma_f32_16x16x32_bf16 v[104:107], v[186:189], v[226:229], v[104:107]
	v_mfma_f32_16x16x32_bf16 v[72:75], v[206:209], v[226:229], v[72:75]
	v_mfma_f32_16x16x32_bf16 v[100:103], v[186:189], v[234:237], v[100:103]
	v_mfma_f32_16x16x32_bf16 v[68:71], v[206:209], v[234:237], v[68:71]
	v_mfma_f32_16x16x32_bf16 v[96:99], v[186:189], v[242:245], v[96:99]
	v_mfma_f32_16x16x32_bf16 v[64:67], v[206:209], v[242:245], v[64:67]
	s_barrier
	s_setprio 0
	s_add_i32 s10, s16, s63
	s_mov_b32 m0, s10
	ds_read_b128 v[214:217], v199 offset:49152
	ds_read_b128 v[218:221], v199 offset:50176
	ds_read_b128 v[222:225], v199 offset:51200
	ds_read_b128 v[226:229], v199 offset:52224
	ds_read_b128 v[230:233], v199 offset:53248
	ds_read_b128 v[234:237], v199 offset:54272
	ds_read_b128 v[238:241], v199 offset:55296
	ds_read_b128 v[242:245], v199 offset:56320
	global_load_lds_dwordx4 v154, s[98:99]
	s_add_i32 m0, s10, 0x2000
	s_add_u32 s8, s8, 0x80080
	s_addc_u32 s9, s9, 0
	s_add_i32 s10, s17, s63
	global_load_lds_dwordx4 v158, s[98:99]
	s_mov_b32 m0, s10
	s_nop 0
	global_load_lds_dwordx4 v154, s[8:9]
	s_add_i32 m0, s10, 0x2000
	s_nop 0
	global_load_lds_dwordx4 v158, s[8:9]
	s_mov_b32 m0, s82
	s_nop 0
	global_load_lds_dwordx4 v152, s[100:101]
	s_mov_b32 m0, s83
	s_nop 0
	global_load_lds_dwordx4 v156, s[100:101]
	s_waitcnt vmcnt(8)
	s_waitcnt lgkmcnt(0)
	s_setprio 1
	s_barrier
	v_mfma_f32_16x16x32_bf16 v[48:51], v[148:151], v[214:217], v[48:51]
	v_mfma_f32_16x16x32_bf16 v[16:19], v[174:177], v[214:217], v[16:19]
	v_mfma_f32_16x16x32_bf16 v[52:55], v[148:151], v[222:225], v[52:55]
	v_mfma_f32_16x16x32_bf16 v[24:27], v[174:177], v[222:225], v[24:27]
	v_mfma_f32_16x16x32_bf16 v[60:63], v[148:151], v[230:233], v[60:63]
	v_mfma_f32_16x16x32_bf16 v[28:31], v[174:177], v[230:233], v[28:31]
	v_mfma_f32_16x16x32_bf16 v[56:59], v[148:151], v[238:241], v[56:59]
	v_mfma_f32_16x16x32_bf16 v[20:23], v[174:177], v[238:241], v[20:23]
	v_mfma_f32_16x16x32_bf16 v[48:51], v[170:173], v[218:221], v[48:51]
	v_mfma_f32_16x16x32_bf16 v[16:19], v[178:181], v[218:221], v[16:19]
	v_mfma_f32_16x16x32_bf16 v[52:55], v[170:173], v[226:229], v[52:55]
	v_mfma_f32_16x16x32_bf16 v[24:27], v[178:181], v[226:229], v[24:27]
	v_mfma_f32_16x16x32_bf16 v[60:63], v[170:173], v[234:237], v[60:63]
	v_mfma_f32_16x16x32_bf16 v[28:31], v[178:181], v[234:237], v[28:31]
	v_mfma_f32_16x16x32_bf16 v[56:59], v[170:173], v[242:245], v[56:59]
	v_mfma_f32_16x16x32_bf16 v[20:23], v[178:181], v[242:245], v[20:23]
	v_mfma_f32_16x16x32_bf16 v[44:47], v[182:185], v[214:217], v[44:47]
	v_mfma_f32_16x16x32_bf16 v[12:15], v[202:205], v[214:217], v[12:15]
	v_mfma_f32_16x16x32_bf16 v[40:43], v[182:185], v[222:225], v[40:43]
	v_mfma_f32_16x16x32_bf16 v[8:11], v[202:205], v[222:225], v[8:11]
	v_mfma_f32_16x16x32_bf16 v[36:39], v[182:185], v[230:233], v[36:39]
	v_mfma_f32_16x16x32_bf16 v[4:7], v[202:205], v[230:233], v[4:7]
	v_mfma_f32_16x16x32_bf16 v[32:35], v[182:185], v[238:241], v[32:35]
	v_mfma_f32_16x16x32_bf16 v[0:3], v[202:205], v[238:241], v[0:3]
	v_mfma_f32_16x16x32_bf16 v[44:47], v[186:189], v[218:221], v[44:47]
	v_mfma_f32_16x16x32_bf16 v[12:15], v[206:209], v[218:221], v[12:15]
	v_mfma_f32_16x16x32_bf16 v[40:43], v[186:189], v[226:229], v[40:43]
	v_mfma_f32_16x16x32_bf16 v[8:11], v[206:209], v[226:229], v[8:11]
	v_mfma_f32_16x16x32_bf16 v[36:39], v[186:189], v[234:237], v[36:39]
	v_mfma_f32_16x16x32_bf16 v[4:7], v[206:209], v[234:237], v[4:7]
	v_mfma_f32_16x16x32_bf16 v[32:35], v[186:189], v[242:245], v[32:35]
	v_mfma_f32_16x16x32_bf16 v[0:3], v[206:209], v[242:245], v[0:3]
	s_barrier
	s_setprio 0
	s_add_i32 s15, s15, 2
	s_add_u32 s6, s6, 0x100
	s_addc_u32 s7, s7, 0
	s_add_u32 s12, s12, 0x100
	s_addc_u32 s13, s13, 0
	s_cmp_gt_u32 s15, 29
.LBB0_636:
	ds_read_b128 v[148:151], v197
	ds_read_b128 v[170:173], v197 offset:1024
	ds_read_b128 v[174:177], v197 offset:2048
	ds_read_b128 v[178:181], v197 offset:3072
	ds_read_b128 v[182:185], v198
	ds_read_b128 v[186:189], v198 offset:1024
	ds_read_b128 v[202:205], v198 offset:2048
	ds_read_b128 v[206:209], v198 offset:3072
	s_add_u32 s8, s6, 0xfff80080
	s_addc_u32 s9, s7, -1
	s_cmp_eq_u32 s15, 28
	s_cselect_b32 s11, s69, s9
	s_cselect_b32 s10, s68, s8
	s_cselect_b32 s9, s1, s13
	s_cselect_b32 s8, s3, s12
	s_add_i32 m0, s72, 0xc000
	ds_read_b128 v[214:217], v199
	ds_read_b128 v[218:221], v199 offset:1024
	ds_read_b128 v[222:225], v199 offset:2048
	ds_read_b128 v[226:229], v199 offset:3072
	ds_read_b128 v[230:233], v199 offset:4096
	ds_read_b128 v[234:237], v199 offset:5120
	ds_read_b128 v[238:241], v199 offset:6144
	ds_read_b128 v[242:245], v199 offset:7168
	global_load_lds_dwordx4 v162, s[6:7]
	s_add_i32 m0, s72, 0xe000
	s_nop 0
	global_load_lds_dwordx4 v164, s[6:7]
	s_waitcnt vmcnt(8)
	s_waitcnt lgkmcnt(0)
	s_setprio 1
	s_barrier
	v_mfma_f32_16x16x32_bf16 v[112:115], v[148:151], v[214:217], v[112:115]
	v_mfma_f32_16x16x32_bf16 v[80:83], v[174:177], v[214:217], v[80:83]
	v_mfma_f32_16x16x32_bf16 v[116:119], v[148:151], v[222:225], v[116:119]
	v_mfma_f32_16x16x32_bf16 v[88:91], v[174:177], v[222:225], v[88:91]
	v_mfma_f32_16x16x32_bf16 v[124:127], v[148:151], v[230:233], v[124:127]
	v_mfma_f32_16x16x32_bf16 v[92:95], v[174:177], v[230:233], v[92:95]
	v_mfma_f32_16x16x32_bf16 v[120:123], v[148:151], v[238:241], v[120:123]
	v_mfma_f32_16x16x32_bf16 v[84:87], v[174:177], v[238:241], v[84:87]
	v_mfma_f32_16x16x32_bf16 v[112:115], v[170:173], v[218:221], v[112:115]
	v_mfma_f32_16x16x32_bf16 v[80:83], v[178:181], v[218:221], v[80:83]
	v_mfma_f32_16x16x32_bf16 v[116:119], v[170:173], v[226:229], v[116:119]
	v_mfma_f32_16x16x32_bf16 v[88:91], v[178:181], v[226:229], v[88:91]
	v_mfma_f32_16x16x32_bf16 v[124:127], v[170:173], v[234:237], v[124:127]
	v_mfma_f32_16x16x32_bf16 v[92:95], v[178:181], v[234:237], v[92:95]
	v_mfma_f32_16x16x32_bf16 v[120:123], v[170:173], v[242:245], v[120:123]
	v_mfma_f32_16x16x32_bf16 v[84:87], v[178:181], v[242:245], v[84:87]
	v_mfma_f32_16x16x32_bf16 v[108:111], v[182:185], v[214:217], v[108:111]
	v_mfma_f32_16x16x32_bf16 v[76:79], v[202:205], v[214:217], v[76:79]
	v_mfma_f32_16x16x32_bf16 v[104:107], v[182:185], v[222:225], v[104:107]
	v_mfma_f32_16x16x32_bf16 v[72:75], v[202:205], v[222:225], v[72:75]
	v_mfma_f32_16x16x32_bf16 v[100:103], v[182:185], v[230:233], v[100:103]
	v_mfma_f32_16x16x32_bf16 v[68:71], v[202:205], v[230:233], v[68:71]
	v_mfma_f32_16x16x32_bf16 v[96:99], v[182:185], v[238:241], v[96:99]
	v_mfma_f32_16x16x32_bf16 v[64:67], v[202:205], v[238:241], v[64:67]
	v_mfma_f32_16x16x32_bf16 v[108:111], v[186:189], v[218:221], v[108:111]
	v_mfma_f32_16x16x32_bf16 v[76:79], v[206:209], v[218:221], v[76:79]
	v_mfma_f32_16x16x32_bf16 v[104:107], v[186:189], v[226:229], v[104:107]
	v_mfma_f32_16x16x32_bf16 v[72:75], v[206:209], v[226:229], v[72:75]
	v_mfma_f32_16x16x32_bf16 v[100:103], v[186:189], v[234:237], v[100:103]
	v_mfma_f32_16x16x32_bf16 v[68:71], v[206:209], v[234:237], v[68:71]
	v_mfma_f32_16x16x32_bf16 v[96:99], v[186:189], v[242:245], v[96:99]
	v_mfma_f32_16x16x32_bf16 v[64:67], v[206:209], v[242:245], v[64:67]
	s_barrier
	s_setprio 0
	s_add_i32 s16, s94, s63
	s_add_u32 s98, s8, s40
	s_addc_u32 s99, s9, s41
	s_mov_b32 m0, s16
	ds_read_b128 v[214:217], v199 offset:16384
	ds_read_b128 v[218:221], v199 offset:17408
	ds_read_b128 v[222:225], v199 offset:18432
	ds_read_b128 v[226:229], v199 offset:19456
	ds_read_b128 v[230:233], v199 offset:20480
	ds_read_b128 v[234:237], v199 offset:21504
	ds_read_b128 v[238:241], v199 offset:22528
	ds_read_b128 v[242:245], v199 offset:23552
	global_load_lds_dwordx4 v154, s[8:9]
	s_add_i32 m0, s16, 0x2000
	s_add_u32 s16, s8, 0x80000
	s_addc_u32 s17, s9, 0
	s_add_i32 s18, s95, s63
	global_load_lds_dwordx4 v158, s[8:9]
	s_mov_b32 m0, s18
	s_add_u32 s100, s10, s40
	s_addc_u32 s101, s11, s41
	global_load_lds_dwordx4 v154, s[16:17]
	s_add_i32 m0, s18, 0x2000
	s_nop 0
	global_load_lds_dwordx4 v158, s[16:17]
	s_mov_b32 m0, s72
	s_nop 0
	global_load_lds_dwordx4 v152, s[10:11]
	s_mov_b32 m0, s73
	s_nop 0
	global_load_lds_dwordx4 v156, s[10:11]
	s_waitcnt vmcnt(8)
	s_waitcnt lgkmcnt(0)
	s_setprio 1
	s_barrier
	v_mfma_f32_16x16x32_bf16 v[48:51], v[148:151], v[214:217], v[48:51]
	v_mfma_f32_16x16x32_bf16 v[16:19], v[174:177], v[214:217], v[16:19]
	v_mfma_f32_16x16x32_bf16 v[52:55], v[148:151], v[222:225], v[52:55]
	v_mfma_f32_16x16x32_bf16 v[24:27], v[174:177], v[222:225], v[24:27]
	v_mfma_f32_16x16x32_bf16 v[60:63], v[148:151], v[230:233], v[60:63]
	v_mfma_f32_16x16x32_bf16 v[28:31], v[174:177], v[230:233], v[28:31]
	v_mfma_f32_16x16x32_bf16 v[56:59], v[148:151], v[238:241], v[56:59]
	v_mfma_f32_16x16x32_bf16 v[20:23], v[174:177], v[238:241], v[20:23]
	v_mfma_f32_16x16x32_bf16 v[48:51], v[170:173], v[218:221], v[48:51]
	v_mfma_f32_16x16x32_bf16 v[16:19], v[178:181], v[218:221], v[16:19]
	v_mfma_f32_16x16x32_bf16 v[52:55], v[170:173], v[226:229], v[52:55]
	v_mfma_f32_16x16x32_bf16 v[24:27], v[178:181], v[226:229], v[24:27]
	v_mfma_f32_16x16x32_bf16 v[60:63], v[170:173], v[234:237], v[60:63]
	v_mfma_f32_16x16x32_bf16 v[28:31], v[178:181], v[234:237], v[28:31]
	v_mfma_f32_16x16x32_bf16 v[56:59], v[170:173], v[242:245], v[56:59]
	v_mfma_f32_16x16x32_bf16 v[20:23], v[178:181], v[242:245], v[20:23]
	v_mfma_f32_16x16x32_bf16 v[44:47], v[182:185], v[214:217], v[44:47]
	v_mfma_f32_16x16x32_bf16 v[12:15], v[202:205], v[214:217], v[12:15]
	v_mfma_f32_16x16x32_bf16 v[40:43], v[182:185], v[222:225], v[40:43]
	v_mfma_f32_16x16x32_bf16 v[8:11], v[202:205], v[222:225], v[8:11]
	v_mfma_f32_16x16x32_bf16 v[36:39], v[182:185], v[230:233], v[36:39]
	v_mfma_f32_16x16x32_bf16 v[4:7], v[202:205], v[230:233], v[4:7]
	v_mfma_f32_16x16x32_bf16 v[32:35], v[182:185], v[238:241], v[32:35]
	v_mfma_f32_16x16x32_bf16 v[0:3], v[202:205], v[238:241], v[0:3]
	v_mfma_f32_16x16x32_bf16 v[44:47], v[186:189], v[218:221], v[44:47]
	v_mfma_f32_16x16x32_bf16 v[12:15], v[206:209], v[218:221], v[12:15]
	v_mfma_f32_16x16x32_bf16 v[40:43], v[186:189], v[226:229], v[40:43]
	v_mfma_f32_16x16x32_bf16 v[8:11], v[206:209], v[226:229], v[8:11]
	v_mfma_f32_16x16x32_bf16 v[36:39], v[186:189], v[234:237], v[36:39]
	v_mfma_f32_16x16x32_bf16 v[4:7], v[206:209], v[234:237], v[4:7]
	v_mfma_f32_16x16x32_bf16 v[32:35], v[186:189], v[242:245], v[32:35]
	v_mfma_f32_16x16x32_bf16 v[0:3], v[206:209], v[242:245], v[0:3]
	s_barrier
	s_setprio 0
	s_add_i32 s16, 0, 0x18000
	s_add_i32 s17, 0, 0x1c000
	v_add_u32_e32 v178, s16, v196
	v_add_u32_e32 v201, s17, v196
	ds_read_b128 v[148:151], v178
	ds_read_b128 v[170:173], v178 offset:1024
	ds_read_b128 v[174:177], v178 offset:2048
	ds_read_b128 v[178:181], v178 offset:3072
	ds_read_b128 v[182:185], v201
	ds_read_b128 v[186:189], v201 offset:1024
	ds_read_b128 v[202:205], v201 offset:2048
	ds_read_b128 v[206:209], v201 offset:3072
	s_add_u32 s10, s10, 0x80000
	s_addc_u32 s11, s11, 0
	s_mov_b32 m0, s74
	ds_read_b128 v[214:217], v199 offset:32768
	ds_read_b128 v[218:221], v199 offset:33792
	ds_read_b128 v[222:225], v199 offset:34816
	ds_read_b128 v[226:229], v199 offset:35840
	ds_read_b128 v[230:233], v199 offset:36864
	ds_read_b128 v[234:237], v199 offset:37888
	ds_read_b128 v[238:241], v199 offset:38912
	ds_read_b128 v[242:245], v199 offset:39936
	global_load_lds_dwordx4 v152, s[10:11]
	s_mov_b32 m0, s75
	s_nop 0
	global_load_lds_dwordx4 v156, s[10:11]
	s_waitcnt vmcnt(8)
	s_waitcnt lgkmcnt(0)
	s_setprio 1
	s_barrier
	v_mfma_f32_16x16x32_bf16 v[112:115], v[148:151], v[214:217], v[112:115]
	v_mfma_f32_16x16x32_bf16 v[80:83], v[174:177], v[214:217], v[80:83]
	v_mfma_f32_16x16x32_bf16 v[116:119], v[148:151], v[222:225], v[116:119]
	v_mfma_f32_16x16x32_bf16 v[88:91], v[174:177], v[222:225], v[88:91]
	v_mfma_f32_16x16x32_bf16 v[124:127], v[148:151], v[230:233], v[124:127]
	v_mfma_f32_16x16x32_bf16 v[92:95], v[174:177], v[230:233], v[92:95]
	v_mfma_f32_16x16x32_bf16 v[120:123], v[148:151], v[238:241], v[120:123]
	v_mfma_f32_16x16x32_bf16 v[84:87], v[174:177], v[238:241], v[84:87]
	v_mfma_f32_16x16x32_bf16 v[112:115], v[170:173], v[218:221], v[112:115]
	v_mfma_f32_16x16x32_bf16 v[80:83], v[178:181], v[218:221], v[80:83]
	v_mfma_f32_16x16x32_bf16 v[116:119], v[170:173], v[226:229], v[116:119]
	v_mfma_f32_16x16x32_bf16 v[88:91], v[178:181], v[226:229], v[88:91]
	v_mfma_f32_16x16x32_bf16 v[124:127], v[170:173], v[234:237], v[124:127]
	v_mfma_f32_16x16x32_bf16 v[92:95], v[178:181], v[234:237], v[92:95]
	v_mfma_f32_16x16x32_bf16 v[120:123], v[170:173], v[242:245], v[120:123]
	v_mfma_f32_16x16x32_bf16 v[84:87], v[178:181], v[242:245], v[84:87]
	v_mfma_f32_16x16x32_bf16 v[108:111], v[182:185], v[214:217], v[108:111]
	v_mfma_f32_16x16x32_bf16 v[76:79], v[202:205], v[214:217], v[76:79]
	v_mfma_f32_16x16x32_bf16 v[104:107], v[182:185], v[222:225], v[104:107]
	v_mfma_f32_16x16x32_bf16 v[72:75], v[202:205], v[222:225], v[72:75]
	v_mfma_f32_16x16x32_bf16 v[100:103], v[182:185], v[230:233], v[100:103]
	v_mfma_f32_16x16x32_bf16 v[68:71], v[202:205], v[230:233], v[68:71]
	v_mfma_f32_16x16x32_bf16 v[96:99], v[182:185], v[238:241], v[96:99]
	v_mfma_f32_16x16x32_bf16 v[64:67], v[202:205], v[238:241], v[64:67]
	v_mfma_f32_16x16x32_bf16 v[108:111], v[186:189], v[218:221], v[108:111]
	v_mfma_f32_16x16x32_bf16 v[76:79], v[206:209], v[218:221], v[76:79]
	v_mfma_f32_16x16x32_bf16 v[104:107], v[186:189], v[226:229], v[104:107]
	v_mfma_f32_16x16x32_bf16 v[72:75], v[206:209], v[226:229], v[72:75]
	v_mfma_f32_16x16x32_bf16 v[100:103], v[186:189], v[234:237], v[100:103]
	v_mfma_f32_16x16x32_bf16 v[68:71], v[206:209], v[234:237], v[68:71]
	v_mfma_f32_16x16x32_bf16 v[96:99], v[186:189], v[242:245], v[96:99]
	v_mfma_f32_16x16x32_bf16 v[64:67], v[206:209], v[242:245], v[64:67]
	s_barrier
	s_setprio 0
	s_add_i32 s10, s16, s63
	s_mov_b32 m0, s10
	ds_read_b128 v[214:217], v199 offset:49152
	ds_read_b128 v[218:221], v199 offset:50176
	ds_read_b128 v[222:225], v199 offset:51200
	ds_read_b128 v[226:229], v199 offset:52224
	ds_read_b128 v[230:233], v199 offset:53248
	ds_read_b128 v[234:237], v199 offset:54272
	ds_read_b128 v[238:241], v199 offset:55296
	ds_read_b128 v[242:245], v199 offset:56320
	global_load_lds_dwordx4 v154, s[98:99]
	s_add_i32 m0, s10, 0x2000
	s_add_u32 s8, s8, 0x80080
	s_addc_u32 s9, s9, 0
	s_add_i32 s10, s17, s63
	global_load_lds_dwordx4 v158, s[98:99]
	s_mov_b32 m0, s10
	s_nop 0
	global_load_lds_dwordx4 v154, s[8:9]
	s_add_i32 m0, s10, 0x2000
	s_nop 0
	global_load_lds_dwordx4 v158, s[8:9]
	s_mov_b32 m0, s82
	s_nop 0
	global_load_lds_dwordx4 v152, s[100:101]
	s_mov_b32 m0, s83
	s_nop 0
	global_load_lds_dwordx4 v156, s[100:101]
	s_waitcnt vmcnt(8)
	s_waitcnt lgkmcnt(0)
	s_setprio 1
	s_barrier
	v_mfma_f32_16x16x32_bf16 v[48:51], v[148:151], v[214:217], v[48:51]
	v_mfma_f32_16x16x32_bf16 v[16:19], v[174:177], v[214:217], v[16:19]
	v_mfma_f32_16x16x32_bf16 v[52:55], v[148:151], v[222:225], v[52:55]
	v_mfma_f32_16x16x32_bf16 v[24:27], v[174:177], v[222:225], v[24:27]
	v_mfma_f32_16x16x32_bf16 v[60:63], v[148:151], v[230:233], v[60:63]
	v_mfma_f32_16x16x32_bf16 v[28:31], v[174:177], v[230:233], v[28:31]
	v_mfma_f32_16x16x32_bf16 v[56:59], v[148:151], v[238:241], v[56:59]
	v_mfma_f32_16x16x32_bf16 v[20:23], v[174:177], v[238:241], v[20:23]
	v_mfma_f32_16x16x32_bf16 v[48:51], v[170:173], v[218:221], v[48:51]
	v_mfma_f32_16x16x32_bf16 v[16:19], v[178:181], v[218:221], v[16:19]
	v_mfma_f32_16x16x32_bf16 v[52:55], v[170:173], v[226:229], v[52:55]
	v_mfma_f32_16x16x32_bf16 v[24:27], v[178:181], v[226:229], v[24:27]
	v_mfma_f32_16x16x32_bf16 v[60:63], v[170:173], v[234:237], v[60:63]
	v_mfma_f32_16x16x32_bf16 v[28:31], v[178:181], v[234:237], v[28:31]
	v_mfma_f32_16x16x32_bf16 v[56:59], v[170:173], v[242:245], v[56:59]
	v_mfma_f32_16x16x32_bf16 v[20:23], v[178:181], v[242:245], v[20:23]
	v_mfma_f32_16x16x32_bf16 v[44:47], v[182:185], v[214:217], v[44:47]
	v_mfma_f32_16x16x32_bf16 v[12:15], v[202:205], v[214:217], v[12:15]
	v_mfma_f32_16x16x32_bf16 v[40:43], v[182:185], v[222:225], v[40:43]
	v_mfma_f32_16x16x32_bf16 v[8:11], v[202:205], v[222:225], v[8:11]
	v_mfma_f32_16x16x32_bf16 v[36:39], v[182:185], v[230:233], v[36:39]
	v_mfma_f32_16x16x32_bf16 v[4:7], v[202:205], v[230:233], v[4:7]
	v_mfma_f32_16x16x32_bf16 v[32:35], v[182:185], v[238:241], v[32:35]
	v_mfma_f32_16x16x32_bf16 v[0:3], v[202:205], v[238:241], v[0:3]
	v_mfma_f32_16x16x32_bf16 v[44:47], v[186:189], v[218:221], v[44:47]
	v_mfma_f32_16x16x32_bf16 v[12:15], v[206:209], v[218:221], v[12:15]
	v_mfma_f32_16x16x32_bf16 v[40:43], v[186:189], v[226:229], v[40:43]
	v_mfma_f32_16x16x32_bf16 v[8:11], v[206:209], v[226:229], v[8:11]
	v_mfma_f32_16x16x32_bf16 v[36:39], v[186:189], v[234:237], v[36:39]
	v_mfma_f32_16x16x32_bf16 v[4:7], v[206:209], v[234:237], v[4:7]
	v_mfma_f32_16x16x32_bf16 v[32:35], v[186:189], v[242:245], v[32:35]
	v_mfma_f32_16x16x32_bf16 v[0:3], v[206:209], v[242:245], v[0:3]
	s_barrier
	s_setprio 0
	s_add_i32 s15, s15, 2
	s_add_u32 s6, s6, 0x100
	s_addc_u32 s7, s7, 0
	s_add_u32 s12, s12, 0x100
	s_addc_u32 s13, s13, 0
	s_cmp_gt_u32 s15, 29
	s_cbranch_scc0 .LBB0_636
	s_and_b64 vcc, exec, s[42:43]
	s_cbranch_vccz .LBB0_639
	s_barrier

.LBB0_843:
	ds_read_b128 v[128:131], v184
	ds_read_b128 v[132:135], v184 offset:1024
	ds_read_b128 v[136:139], v184 offset:2048
	ds_read_b128 v[140:143], v184 offset:3072
	ds_read_b128 v[144:147], v185
	ds_read_b128 v[148:151], v185 offset:1024
	ds_read_b128 v[168:171], v185 offset:2048
	ds_read_b128 v[172:175], v185 offset:3072
	s_add_u32 s34, s30, 0x100
	s_addc_u32 s35, s31, 0
	s_cmpk_eq_i32 s59, 0x52
	s_cselect_b32 s39, s7, s35
	s_cselect_b32 s38, s6, s34
	s_cselect_b32 s37, s27, s58
	s_cselect_b32 s36, s26, s3
	v_lshl_add_u64 v[218:219], s[30:31], 0, v[160:161]
	s_add_i32 m0, s45, 0xc000
	ds_read_b128 v[176:179], v186
	ds_read_b128 v[188:191], v186 offset:1024
	ds_read_b128 v[192:195], v186 offset:2048
	ds_read_b128 v[196:199], v186 offset:3072
	ds_read_b128 v[200:203], v186 offset:4096
	ds_read_b128 v[204:207], v186 offset:5120
	ds_read_b128 v[208:211], v186 offset:6144
	ds_read_b128 v[214:217], v186 offset:7168
	global_load_lds_dwordx4 v[218:219], off
	v_lshl_add_u64 v[218:219], s[30:31], 0, v[162:163]
	s_add_i32 m0, s45, 0xe000
	s_nop 0
	global_load_lds_dwordx4 v[218:219], off
	s_waitcnt vmcnt(8)
	s_waitcnt lgkmcnt(0)
	s_setprio 1
	s_barrier
	v_mfma_f32_16x16x32_bf16 v[124:127], v[128:131], v[176:179], v[124:127]
	v_mfma_f32_16x16x32_bf16 v[120:123], v[136:139], v[176:179], v[120:123]
	v_mfma_f32_16x16x32_bf16 v[108:111], v[128:131], v[192:195], v[108:111]
	v_mfma_f32_16x16x32_bf16 v[104:107], v[136:139], v[192:195], v[104:107]
	v_mfma_f32_16x16x32_bf16 v[92:95], v[128:131], v[200:203], v[92:95]
	v_mfma_f32_16x16x32_bf16 v[88:91], v[136:139], v[200:203], v[88:91]
	v_mfma_f32_16x16x32_bf16 v[76:79], v[128:131], v[208:211], v[76:79]
	v_mfma_f32_16x16x32_bf16 v[72:75], v[136:139], v[208:211], v[72:75]
	v_mfma_f32_16x16x32_bf16 v[124:127], v[132:135], v[188:191], v[124:127]
	v_mfma_f32_16x16x32_bf16 v[120:123], v[140:143], v[188:191], v[120:123]
	v_mfma_f32_16x16x32_bf16 v[108:111], v[132:135], v[196:199], v[108:111]
	v_mfma_f32_16x16x32_bf16 v[104:107], v[140:143], v[196:199], v[104:107]
	v_mfma_f32_16x16x32_bf16 v[92:95], v[132:135], v[204:207], v[92:95]
	v_mfma_f32_16x16x32_bf16 v[88:91], v[140:143], v[204:207], v[88:91]
	v_mfma_f32_16x16x32_bf16 v[76:79], v[132:135], v[214:217], v[76:79]
	v_mfma_f32_16x16x32_bf16 v[72:75], v[140:143], v[214:217], v[72:75]
	v_mfma_f32_16x16x32_bf16 v[116:119], v[144:147], v[176:179], v[116:119]
	v_mfma_f32_16x16x32_bf16 v[112:115], v[168:171], v[176:179], v[112:115]
	v_mfma_f32_16x16x32_bf16 v[100:103], v[144:147], v[192:195], v[100:103]
	v_mfma_f32_16x16x32_bf16 v[96:99], v[168:171], v[192:195], v[96:99]
	v_mfma_f32_16x16x32_bf16 v[84:87], v[144:147], v[200:203], v[84:87]
	v_mfma_f32_16x16x32_bf16 v[80:83], v[168:171], v[200:203], v[80:83]
	v_mfma_f32_16x16x32_bf16 v[68:71], v[144:147], v[208:211], v[68:71]
	v_mfma_f32_16x16x32_bf16 v[64:67], v[168:171], v[208:211], v[64:67]
	v_mfma_f32_16x16x32_bf16 v[116:119], v[148:151], v[188:191], v[116:119]
	v_mfma_f32_16x16x32_bf16 v[112:115], v[172:175], v[188:191], v[112:115]
	v_mfma_f32_16x16x32_bf16 v[100:103], v[148:151], v[196:199], v[100:103]
	v_mfma_f32_16x16x32_bf16 v[96:99], v[172:175], v[196:199], v[96:99]
	v_mfma_f32_16x16x32_bf16 v[84:87], v[148:151], v[204:207], v[84:87]
	v_mfma_f32_16x16x32_bf16 v[80:83], v[172:175], v[204:207], v[80:83]
	v_mfma_f32_16x16x32_bf16 v[68:71], v[148:151], v[214:217], v[68:71]
	v_mfma_f32_16x16x32_bf16 v[64:67], v[172:175], v[214:217], v[64:67]
	s_barrier
	s_setprio 0
	s_add_i32 s30, s54, s44
	v_lshl_add_u64 v[218:219], s[36:37], 0, v[154:155]
	s_mov_b32 m0, s30
	ds_read_b128 v[176:179], v186 offset:16384
	ds_read_b128 v[188:191], v186 offset:17408
	ds_read_b128 v[192:195], v186 offset:18432
	ds_read_b128 v[196:199], v186 offset:19456
	ds_read_b128 v[200:203], v186 offset:20480
	ds_read_b128 v[204:207], v186 offset:21504
	ds_read_b128 v[208:211], v186 offset:22528
	ds_read_b128 v[214:217], v186 offset:23552
	global_load_lds_dwordx4 v[218:219], off
	s_add_i32 m0, s30, 0x2000
	s_add_u32 s30, s36, 0x158000
	v_lshl_add_u64 v[220:221], s[36:37], 0, v[158:159]
	s_addc_u32 s31, s37, 0
	s_add_i32 s60, s55, s44
	global_load_lds_dwordx4 v[220:221], off
	v_lshl_add_u64 v[222:223], s[30:31], 0, v[154:155]
	s_mov_b32 m0, s60
	v_lshl_add_u64 v[224:225], s[38:39], 0, v[156:157]
	global_load_lds_dwordx4 v[222:223], off
	v_lshl_add_u64 v[222:223], s[30:31], 0, v[158:159]
	s_add_i32 m0, s60, 0x2000
	s_nop 0
	global_load_lds_dwordx4 v[222:223], off
	v_lshl_add_u64 v[222:223], s[38:39], 0, v[152:153]
	s_mov_b32 m0, s45
	s_nop 0
	global_load_lds_dwordx4 v[222:223], off
	s_mov_b32 m0, s46
	s_nop 0
	global_load_lds_dwordx4 v[224:225], off
	s_waitcnt vmcnt(8)
	s_waitcnt lgkmcnt(0)
	s_setprio 1
	s_barrier
	v_mfma_f32_16x16x32_bf16 v[60:63], v[128:131], v[176:179], v[60:63]
	v_mfma_f32_16x16x32_bf16 v[56:59], v[136:139], v[176:179], v[56:59]
	v_mfma_f32_16x16x32_bf16 v[44:47], v[128:131], v[192:195], v[44:47]
	v_mfma_f32_16x16x32_bf16 v[40:43], v[136:139], v[192:195], v[40:43]
	v_mfma_f32_16x16x32_bf16 v[28:31], v[128:131], v[200:203], v[28:31]
	v_mfma_f32_16x16x32_bf16 v[24:27], v[136:139], v[200:203], v[24:27]
	v_mfma_f32_16x16x32_bf16 v[12:15], v[128:131], v[208:211], v[12:15]
	v_mfma_f32_16x16x32_bf16 v[8:11], v[136:139], v[208:211], v[8:11]
	v_mfma_f32_16x16x32_bf16 v[60:63], v[132:135], v[188:191], v[60:63]
	v_mfma_f32_16x16x32_bf16 v[56:59], v[140:143], v[188:191], v[56:59]
	v_mfma_f32_16x16x32_bf16 v[44:47], v[132:135], v[196:199], v[44:47]
	v_mfma_f32_16x16x32_bf16 v[40:43], v[140:143], v[196:199], v[40:43]
	v_mfma_f32_16x16x32_bf16 v[28:31], v[132:135], v[204:207], v[28:31]
	v_mfma_f32_16x16x32_bf16 v[24:27], v[140:143], v[204:207], v[24:27]
	v_mfma_f32_16x16x32_bf16 v[12:15], v[132:135], v[214:217], v[12:15]
	v_mfma_f32_16x16x32_bf16 v[8:11], v[140:143], v[214:217], v[8:11]
	v_mfma_f32_16x16x32_bf16 v[52:55], v[144:147], v[176:179], v[52:55]
	v_mfma_f32_16x16x32_bf16 v[48:51], v[168:171], v[176:179], v[48:51]
	v_mfma_f32_16x16x32_bf16 v[36:39], v[144:147], v[192:195], v[36:39]
	v_mfma_f32_16x16x32_bf16 v[32:35], v[168:171], v[192:195], v[32:35]
	v_mfma_f32_16x16x32_bf16 v[20:23], v[144:147], v[200:203], v[20:23]
	v_mfma_f32_16x16x32_bf16 v[16:19], v[168:171], v[200:203], v[16:19]
	v_mfma_f32_16x16x32_bf16 v[4:7], v[144:147], v[208:211], v[4:7]
	v_mfma_f32_16x16x32_bf16 v[0:3], v[168:171], v[208:211], v[0:3]
	v_mfma_f32_16x16x32_bf16 v[52:55], v[148:151], v[188:191], v[52:55]
	v_mfma_f32_16x16x32_bf16 v[48:51], v[172:175], v[188:191], v[48:51]
	v_mfma_f32_16x16x32_bf16 v[36:39], v[148:151], v[196:199], v[36:39]
	v_mfma_f32_16x16x32_bf16 v[32:35], v[172:175], v[196:199], v[32:35]
	v_mfma_f32_16x16x32_bf16 v[20:23], v[148:151], v[204:207], v[20:23]
	v_mfma_f32_16x16x32_bf16 v[16:19], v[172:175], v[204:207], v[16:19]
	v_mfma_f32_16x16x32_bf16 v[4:7], v[148:151], v[214:217], v[4:7]
	v_mfma_f32_16x16x32_bf16 v[0:3], v[172:175], v[214:217], v[0:3]
	s_barrier
	s_setprio 0
	s_add_i32 s60, 0, 0x18000
	s_add_i32 s61, 0, 0x1c000
	v_add_u32_e32 v140, s60, v182
	v_add_u32_e32 v172, s61, v182
	ds_read_b128 v[128:131], v140
	ds_read_b128 v[132:135], v140 offset:1024
	ds_read_b128 v[136:139], v140 offset:2048
	ds_read_b128 v[140:143], v140 offset:3072
	ds_read_b128 v[144:147], v172
	ds_read_b128 v[148:151], v172 offset:1024
	ds_read_b128 v[168:171], v172 offset:2048
	ds_read_b128 v[172:175], v172 offset:3072
	s_add_u32 s30, s38, 0x158000
	s_addc_u32 s31, s39, 0
	s_mov_b32 m0, s47
	v_lshl_add_u64 v[226:227], s[30:31], 0, v[152:153]
	ds_read_b128 v[176:179], v186 offset:32768
	ds_read_b128 v[188:191], v186 offset:33792
	ds_read_b128 v[192:195], v186 offset:34816
	ds_read_b128 v[196:199], v186 offset:35840
	ds_read_b128 v[200:203], v186 offset:36864
	ds_read_b128 v[204:207], v186 offset:37888
	ds_read_b128 v[208:211], v186 offset:38912
	ds_read_b128 v[214:217], v186 offset:39936
	global_load_lds_dwordx4 v[226:227], off
	v_lshl_add_u64 v[226:227], s[30:31], 0, v[156:157]
	s_mov_b32 m0, s48
	s_nop 0
	global_load_lds_dwordx4 v[226:227], off
	s_waitcnt vmcnt(8)
	s_waitcnt lgkmcnt(0)
	s_setprio 1
	s_barrier
	v_mfma_f32_16x16x32_bf16 v[124:127], v[128:131], v[176:179], v[124:127]
	v_mfma_f32_16x16x32_bf16 v[120:123], v[136:139], v[176:179], v[120:123]
	v_mfma_f32_16x16x32_bf16 v[108:111], v[128:131], v[192:195], v[108:111]
	v_mfma_f32_16x16x32_bf16 v[104:107], v[136:139], v[192:195], v[104:107]
	v_mfma_f32_16x16x32_bf16 v[92:95], v[128:131], v[200:203], v[92:95]
	v_mfma_f32_16x16x32_bf16 v[88:91], v[136:139], v[200:203], v[88:91]
	v_mfma_f32_16x16x32_bf16 v[76:79], v[128:131], v[208:211], v[76:79]
	v_mfma_f32_16x16x32_bf16 v[72:75], v[136:139], v[208:211], v[72:75]
	v_mfma_f32_16x16x32_bf16 v[124:127], v[132:135], v[188:191], v[124:127]
	v_mfma_f32_16x16x32_bf16 v[120:123], v[140:143], v[188:191], v[120:123]
	v_mfma_f32_16x16x32_bf16 v[108:111], v[132:135], v[196:199], v[108:111]
	v_mfma_f32_16x16x32_bf16 v[104:107], v[140:143], v[196:199], v[104:107]
	v_mfma_f32_16x16x32_bf16 v[92:95], v[132:135], v[204:207], v[92:95]
	v_mfma_f32_16x16x32_bf16 v[88:91], v[140:143], v[204:207], v[88:91]
	v_mfma_f32_16x16x32_bf16 v[76:79], v[132:135], v[214:217], v[76:79]
	v_mfma_f32_16x16x32_bf16 v[72:75], v[140:143], v[214:217], v[72:75]
	v_mfma_f32_16x16x32_bf16 v[116:119], v[144:147], v[176:179], v[116:119]
	v_mfma_f32_16x16x32_bf16 v[112:115], v[168:171], v[176:179], v[112:115]
	v_mfma_f32_16x16x32_bf16 v[100:103], v[144:147], v[192:195], v[100:103]
	v_mfma_f32_16x16x32_bf16 v[96:99], v[168:171], v[192:195], v[96:99]
	v_mfma_f32_16x16x32_bf16 v[84:87], v[144:147], v[200:203], v[84:87]
	v_mfma_f32_16x16x32_bf16 v[80:83], v[168:171], v[200:203], v[80:83]
	v_mfma_f32_16x16x32_bf16 v[68:71], v[144:147], v[208:211], v[68:71]
	v_mfma_f32_16x16x32_bf16 v[64:67], v[168:171], v[208:211], v[64:67]
	v_mfma_f32_16x16x32_bf16 v[116:119], v[148:151], v[188:191], v[116:119]
	v_mfma_f32_16x16x32_bf16 v[112:115], v[172:175], v[188:191], v[112:115]
	v_mfma_f32_16x16x32_bf16 v[100:103], v[148:151], v[196:199], v[100:103]
	v_mfma_f32_16x16x32_bf16 v[96:99], v[172:175], v[196:199], v[96:99]
	v_mfma_f32_16x16x32_bf16 v[84:87], v[148:151], v[204:207], v[84:87]
	v_mfma_f32_16x16x32_bf16 v[80:83], v[172:175], v[204:207], v[80:83]
	v_mfma_f32_16x16x32_bf16 v[68:71], v[148:151], v[214:217], v[68:71]
	v_mfma_f32_16x16x32_bf16 v[64:67], v[172:175], v[214:217], v[64:67]
	s_barrier
	s_setprio 0
	s_add_i32 s30, s60, s44
	v_lshl_add_u64 v[218:219], v[218:219], 0, s[20:21]
	s_mov_b32 m0, s30
	ds_read_b128 v[176:179], v186 offset:49152
	ds_read_b128 v[188:191], v186 offset:50176
	ds_read_b128 v[192:195], v186 offset:51200
	ds_read_b128 v[196:199], v186 offset:52224
	ds_read_b128 v[200:203], v186 offset:53248
	ds_read_b128 v[204:207], v186 offset:54272
	ds_read_b128 v[208:211], v186 offset:55296
	ds_read_b128 v[214:217], v186 offset:56320
	global_load_lds_dwordx4 v[218:219], off
	s_add_i32 m0, s30, 0x2000
	s_add_u32 s30, s36, 0x158080
	v_lshl_add_u64 v[218:219], v[220:221], 0, s[20:21]
	s_addc_u32 s31, s37, 0
	s_add_i32 s36, s61, s44
	global_load_lds_dwordx4 v[218:219], off
	v_lshl_add_u64 v[218:219], s[30:31], 0, v[154:155]
	s_mov_b32 m0, s36
	s_nop 0
	global_load_lds_dwordx4 v[218:219], off
	v_lshl_add_u64 v[218:219], s[30:31], 0, v[158:159]
	s_add_i32 m0, s36, 0x2000
	s_nop 0
	global_load_lds_dwordx4 v[218:219], off
	v_lshl_add_u64 v[218:219], v[222:223], 0, s[20:21]
	s_mov_b32 m0, s51
	s_nop 0
	global_load_lds_dwordx4 v[218:219], off
	v_lshl_add_u64 v[218:219], v[224:225], 0, s[20:21]
	s_mov_b32 m0, s52
	s_nop 0
	global_load_lds_dwordx4 v[218:219], off
	s_waitcnt vmcnt(8)
	s_waitcnt lgkmcnt(0)
	s_setprio 1
	s_barrier
	v_mfma_f32_16x16x32_bf16 v[60:63], v[128:131], v[176:179], v[60:63]
	v_mfma_f32_16x16x32_bf16 v[56:59], v[136:139], v[176:179], v[56:59]
	v_mfma_f32_16x16x32_bf16 v[44:47], v[128:131], v[192:195], v[44:47]
	v_mfma_f32_16x16x32_bf16 v[40:43], v[136:139], v[192:195], v[40:43]
	v_mfma_f32_16x16x32_bf16 v[28:31], v[128:131], v[200:203], v[28:31]
	v_mfma_f32_16x16x32_bf16 v[24:27], v[136:139], v[200:203], v[24:27]
	v_mfma_f32_16x16x32_bf16 v[12:15], v[128:131], v[208:211], v[12:15]
	v_mfma_f32_16x16x32_bf16 v[8:11], v[136:139], v[208:211], v[8:11]
	v_mfma_f32_16x16x32_bf16 v[60:63], v[132:135], v[188:191], v[60:63]
	v_mfma_f32_16x16x32_bf16 v[56:59], v[140:143], v[188:191], v[56:59]
	v_mfma_f32_16x16x32_bf16 v[44:47], v[132:135], v[196:199], v[44:47]
	v_mfma_f32_16x16x32_bf16 v[40:43], v[140:143], v[196:199], v[40:43]
	v_mfma_f32_16x16x32_bf16 v[28:31], v[132:135], v[204:207], v[28:31]
	v_mfma_f32_16x16x32_bf16 v[24:27], v[140:143], v[204:207], v[24:27]
	v_mfma_f32_16x16x32_bf16 v[12:15], v[132:135], v[214:217], v[12:15]
	v_mfma_f32_16x16x32_bf16 v[8:11], v[140:143], v[214:217], v[8:11]
	v_mfma_f32_16x16x32_bf16 v[52:55], v[144:147], v[176:179], v[52:55]
	v_mfma_f32_16x16x32_bf16 v[48:51], v[168:171], v[176:179], v[48:51]
	v_mfma_f32_16x16x32_bf16 v[36:39], v[144:147], v[192:195], v[36:39]
	v_mfma_f32_16x16x32_bf16 v[32:35], v[168:171], v[192:195], v[32:35]
	v_mfma_f32_16x16x32_bf16 v[20:23], v[144:147], v[200:203], v[20:23]
	v_mfma_f32_16x16x32_bf16 v[16:19], v[168:171], v[200:203], v[16:19]
	v_mfma_f32_16x16x32_bf16 v[4:7], v[144:147], v[208:211], v[4:7]
	v_mfma_f32_16x16x32_bf16 v[0:3], v[168:171], v[208:211], v[0:3]
	v_mfma_f32_16x16x32_bf16 v[52:55], v[148:151], v[188:191], v[52:55]
	v_mfma_f32_16x16x32_bf16 v[48:51], v[172:175], v[188:191], v[48:51]
	v_mfma_f32_16x16x32_bf16 v[36:39], v[148:151], v[196:199], v[36:39]
	v_mfma_f32_16x16x32_bf16 v[32:35], v[172:175], v[196:199], v[32:35]
	v_mfma_f32_16x16x32_bf16 v[20:23], v[148:151], v[204:207], v[20:23]
	v_mfma_f32_16x16x32_bf16 v[16:19], v[172:175], v[204:207], v[16:19]
	v_mfma_f32_16x16x32_bf16 v[4:7], v[148:151], v[214:217], v[4:7]
	v_mfma_f32_16x16x32_bf16 v[0:3], v[172:175], v[214:217], v[0:3]
	s_barrier
	s_setprio 0
	s_add_i32 s59, s59, 2
	s_add_u32 s3, s3, 0x100
	s_addc_u32 s58, s58, 0
	s_cmpk_gt_u32 s59, 0x53
	s_mov_b64 s[30:31], s[34:35]
	s_cbranch_scc0 .LBB0_843
	s_and_b64 vcc, exec, s[24:25]
	s_cbranch_vccz .LBB0_846
	s_barrier

.LBB0_875:
	s_mov_b32 s1, -2
	s_mov_b64 s[4:5], s[22:23]
	ds_read_b128 v[128:131], v188
	ds_read_b128 v[132:135], v188 offset:1024
	ds_read_b128 v[136:139], v188 offset:2048
	ds_read_b128 v[140:143], v188 offset:3072
	ds_read_b128 v[144:147], v189
	ds_read_b128 v[148:151], v189 offset:1024
	ds_read_b128 v[166:169], v189 offset:2048
	ds_read_b128 v[170:173], v189 offset:3072
	s_add_u32 s40, s38, 0x100
	s_addc_u32 s41, s39, 0
	s_cmpk_eq_i32 s1, 0x52
	s_cselect_b32 s45, s37, s41
	s_cselect_b32 s44, s36, s40
	s_cselect_b32 s43, s17, s5
	s_cselect_b32 s42, s16, s4
	s_add_i32 m0, s48, 0xc000
	ds_read_b128 v[174:177], v190
	ds_read_b128 v[178:181], v190 offset:1024
	ds_read_b128 v[194:197], v190 offset:2048
	ds_read_b128 v[198:201], v190 offset:3072
	ds_read_b128 v[202:205], v190 offset:4096
	ds_read_b128 v[206:209], v190 offset:5120
	ds_read_b128 v[210:213], v190 offset:6144
	ds_read_b128 v[214:217], v190 offset:7168
	global_load_lds_dwordx4 v160, s[38:39]
	s_add_i32 m0, s48, 0xe000
	s_nop 0
	global_load_lds_dwordx4 v162, s[38:39]
	s_waitcnt vmcnt(8)
	s_waitcnt lgkmcnt(0)
	s_setprio 1
	s_barrier
	v_mfma_f32_16x16x32_bf16 v[124:127], v[128:131], v[174:177], 0
	v_mfma_f32_16x16x32_bf16 v[120:123], v[136:139], v[174:177], 0
	v_mfma_f32_16x16x32_bf16 v[108:111], v[128:131], v[194:197], 0
	v_mfma_f32_16x16x32_bf16 v[104:107], v[136:139], v[194:197], 0
	v_mfma_f32_16x16x32_bf16 v[92:95], v[128:131], v[202:205], 0
	v_mfma_f32_16x16x32_bf16 v[88:91], v[136:139], v[202:205], 0
	v_mfma_f32_16x16x32_bf16 v[76:79], v[128:131], v[210:213], 0
	v_mfma_f32_16x16x32_bf16 v[72:75], v[136:139], v[210:213], 0
	v_mfma_f32_16x16x32_bf16 v[124:127], v[132:135], v[178:181], v[124:127]
	v_mfma_f32_16x16x32_bf16 v[120:123], v[140:143], v[178:181], v[120:123]
	v_mfma_f32_16x16x32_bf16 v[108:111], v[132:135], v[198:201], v[108:111]
	v_mfma_f32_16x16x32_bf16 v[104:107], v[140:143], v[198:201], v[104:107]
	v_mfma_f32_16x16x32_bf16 v[92:95], v[132:135], v[206:209], v[92:95]
	v_mfma_f32_16x16x32_bf16 v[88:91], v[140:143], v[206:209], v[88:91]
	v_mfma_f32_16x16x32_bf16 v[76:79], v[132:135], v[214:217], v[76:79]
	v_mfma_f32_16x16x32_bf16 v[72:75], v[140:143], v[214:217], v[72:75]
	v_mfma_f32_16x16x32_bf16 v[116:119], v[144:147], v[174:177], 0
	v_mfma_f32_16x16x32_bf16 v[112:115], v[166:169], v[174:177], 0
	v_mfma_f32_16x16x32_bf16 v[100:103], v[144:147], v[194:197], 0
	v_mfma_f32_16x16x32_bf16 v[96:99], v[166:169], v[194:197], 0
	v_mfma_f32_16x16x32_bf16 v[84:87], v[144:147], v[202:205], 0
	v_mfma_f32_16x16x32_bf16 v[80:83], v[166:169], v[202:205], 0
	v_mfma_f32_16x16x32_bf16 v[68:71], v[144:147], v[210:213], 0
	v_mfma_f32_16x16x32_bf16 v[64:67], v[166:169], v[210:213], 0
	v_mfma_f32_16x16x32_bf16 v[116:119], v[148:151], v[178:181], v[116:119]
	v_mfma_f32_16x16x32_bf16 v[112:115], v[170:173], v[178:181], v[112:115]
	v_mfma_f32_16x16x32_bf16 v[100:103], v[148:151], v[198:201], v[100:103]
	v_mfma_f32_16x16x32_bf16 v[96:99], v[170:173], v[198:201], v[96:99]
	v_mfma_f32_16x16x32_bf16 v[84:87], v[148:151], v[206:209], v[84:87]
	v_mfma_f32_16x16x32_bf16 v[80:83], v[170:173], v[206:209], v[80:83]
	v_mfma_f32_16x16x32_bf16 v[68:71], v[148:151], v[214:217], v[68:71]
	v_mfma_f32_16x16x32_bf16 v[64:67], v[170:173], v[214:217], v[64:67]
	s_barrier
	s_setprio 0
	s_add_i32 s3, s70, s33
	s_add_u32 s98, s42, s24
	s_addc_u32 s99, s43, s25
	s_mov_b32 m0, s3
	ds_read_b128 v[174:177], v190 offset:16384
	ds_read_b128 v[178:181], v190 offset:17408
	ds_read_b128 v[194:197], v190 offset:18432
	ds_read_b128 v[198:201], v190 offset:19456
	ds_read_b128 v[202:205], v190 offset:20480
	ds_read_b128 v[206:209], v190 offset:21504
	ds_read_b128 v[210:213], v190 offset:22528
	ds_read_b128 v[214:217], v190 offset:23552
	global_load_lds_dwordx4 v154, s[42:43]
	s_add_i32 m0, s3, 0x2000
	s_add_u32 s38, s42, 0x158000
	s_addc_u32 s39, s43, 0
	s_add_i32 s3, s71, s33
	global_load_lds_dwordx4 v158, s[42:43]
	s_mov_b32 m0, s3
	s_add_u32 s100, s44, s24
	s_addc_u32 s101, s45, s25
	global_load_lds_dwordx4 v154, s[38:39]
	s_add_i32 m0, s3, 0x2000
	s_nop 0
	global_load_lds_dwordx4 v158, s[38:39]
	s_mov_b32 m0, s48
	s_nop 0
	global_load_lds_dwordx4 v152, s[44:45]
	s_mov_b32 m0, s49
	s_nop 0
	global_load_lds_dwordx4 v156, s[44:45]
	s_waitcnt vmcnt(8)
	s_waitcnt lgkmcnt(0)
	s_setprio 1
	s_barrier
	v_mfma_f32_16x16x32_bf16 v[60:63], v[128:131], v[174:177], 0
	v_mfma_f32_16x16x32_bf16 v[56:59], v[136:139], v[174:177], 0
	v_mfma_f32_16x16x32_bf16 v[44:47], v[128:131], v[194:197], 0
	v_mfma_f32_16x16x32_bf16 v[40:43], v[136:139], v[194:197], 0
	v_mfma_f32_16x16x32_bf16 v[28:31], v[128:131], v[202:205], 0
	v_mfma_f32_16x16x32_bf16 v[24:27], v[136:139], v[202:205], 0
	v_mfma_f32_16x16x32_bf16 v[12:15], v[128:131], v[210:213], 0
	v_mfma_f32_16x16x32_bf16 v[8:11], v[136:139], v[210:213], 0
	v_mfma_f32_16x16x32_bf16 v[60:63], v[132:135], v[178:181], v[60:63]
	v_mfma_f32_16x16x32_bf16 v[56:59], v[140:143], v[178:181], v[56:59]
	v_mfma_f32_16x16x32_bf16 v[44:47], v[132:135], v[198:201], v[44:47]
	v_mfma_f32_16x16x32_bf16 v[40:43], v[140:143], v[198:201], v[40:43]
	v_mfma_f32_16x16x32_bf16 v[28:31], v[132:135], v[206:209], v[28:31]
	v_mfma_f32_16x16x32_bf16 v[24:27], v[140:143], v[206:209], v[24:27]
	v_mfma_f32_16x16x32_bf16 v[12:15], v[132:135], v[214:217], v[12:15]
	v_mfma_f32_16x16x32_bf16 v[8:11], v[140:143], v[214:217], v[8:11]
	v_mfma_f32_16x16x32_bf16 v[52:55], v[144:147], v[174:177], 0
	v_mfma_f32_16x16x32_bf16 v[48:51], v[166:169], v[174:177], 0
	v_mfma_f32_16x16x32_bf16 v[36:39], v[144:147], v[194:197], 0
	v_mfma_f32_16x16x32_bf16 v[32:35], v[166:169], v[194:197], 0
	v_mfma_f32_16x16x32_bf16 v[20:23], v[144:147], v[202:205], 0
	v_mfma_f32_16x16x32_bf16 v[16:19], v[166:169], v[202:205], 0
	v_mfma_f32_16x16x32_bf16 v[4:7], v[144:147], v[210:213], 0
	v_mfma_f32_16x16x32_bf16 v[0:3], v[166:169], v[210:213], 0
	v_mfma_f32_16x16x32_bf16 v[52:55], v[148:151], v[178:181], v[52:55]
	v_mfma_f32_16x16x32_bf16 v[48:51], v[170:173], v[178:181], v[48:51]
	v_mfma_f32_16x16x32_bf16 v[36:39], v[148:151], v[198:201], v[36:39]
	v_mfma_f32_16x16x32_bf16 v[32:35], v[170:173], v[198:201], v[32:35]
	v_mfma_f32_16x16x32_bf16 v[20:23], v[148:151], v[206:209], v[20:23]
	v_mfma_f32_16x16x32_bf16 v[16:19], v[170:173], v[206:209], v[16:19]
	v_mfma_f32_16x16x32_bf16 v[4:7], v[148:151], v[214:217], v[4:7]
	v_mfma_f32_16x16x32_bf16 v[0:3], v[170:173], v[214:217], v[0:3]
	s_barrier
	s_setprio 0
	s_add_i32 s3, 0, 0x18000
	s_add_i32 s73, 0, 0x1c000
	v_add_u32_e32 v140, s3, v187
	v_add_u32_e32 v170, s73, v187
	ds_read_b128 v[128:131], v140
	ds_read_b128 v[132:135], v140 offset:1024
	ds_read_b128 v[136:139], v140 offset:2048
	ds_read_b128 v[140:143], v140 offset:3072
	ds_read_b128 v[144:147], v170
	ds_read_b128 v[148:151], v170 offset:1024
	ds_read_b128 v[166:169], v170 offset:2048
	ds_read_b128 v[170:173], v170 offset:3072
	s_add_u32 s38, s44, 0x158000
	s_addc_u32 s39, s45, 0
	s_mov_b32 m0, s51
	ds_read_b128 v[174:177], v190 offset:32768
	ds_read_b128 v[178:181], v190 offset:33792
	ds_read_b128 v[194:197], v190 offset:34816
	ds_read_b128 v[198:201], v190 offset:35840
	ds_read_b128 v[202:205], v190 offset:36864
	ds_read_b128 v[206:209], v190 offset:37888
	ds_read_b128 v[210:213], v190 offset:38912
	ds_read_b128 v[214:217], v190 offset:39936
	global_load_lds_dwordx4 v152, s[38:39]
	s_mov_b32 m0, s52
	s_nop 0
	global_load_lds_dwordx4 v156, s[38:39]
	s_waitcnt vmcnt(8)
	s_waitcnt lgkmcnt(0)
	s_setprio 1
	s_barrier
	v_mfma_f32_16x16x32_bf16 v[124:127], v[128:131], v[174:177], v[124:127]
	v_mfma_f32_16x16x32_bf16 v[120:123], v[136:139], v[174:177], v[120:123]
	v_mfma_f32_16x16x32_bf16 v[108:111], v[128:131], v[194:197], v[108:111]
	v_mfma_f32_16x16x32_bf16 v[104:107], v[136:139], v[194:197], v[104:107]
	v_mfma_f32_16x16x32_bf16 v[92:95], v[128:131], v[202:205], v[92:95]
	v_mfma_f32_16x16x32_bf16 v[88:91], v[136:139], v[202:205], v[88:91]
	v_mfma_f32_16x16x32_bf16 v[76:79], v[128:131], v[210:213], v[76:79]
	v_mfma_f32_16x16x32_bf16 v[72:75], v[136:139], v[210:213], v[72:75]
	v_mfma_f32_16x16x32_bf16 v[124:127], v[132:135], v[178:181], v[124:127]
	v_mfma_f32_16x16x32_bf16 v[120:123], v[140:143], v[178:181], v[120:123]
	v_mfma_f32_16x16x32_bf16 v[108:111], v[132:135], v[198:201], v[108:111]
	v_mfma_f32_16x16x32_bf16 v[104:107], v[140:143], v[198:201], v[104:107]
	v_mfma_f32_16x16x32_bf16 v[92:95], v[132:135], v[206:209], v[92:95]
	v_mfma_f32_16x16x32_bf16 v[88:91], v[140:143], v[206:209], v[88:91]
	v_mfma_f32_16x16x32_bf16 v[76:79], v[132:135], v[214:217], v[76:79]
	v_mfma_f32_16x16x32_bf16 v[72:75], v[140:143], v[214:217], v[72:75]
	v_mfma_f32_16x16x32_bf16 v[116:119], v[144:147], v[174:177], v[116:119]
	v_mfma_f32_16x16x32_bf16 v[112:115], v[166:169], v[174:177], v[112:115]
	v_mfma_f32_16x16x32_bf16 v[100:103], v[144:147], v[194:197], v[100:103]
	v_mfma_f32_16x16x32_bf16 v[96:99], v[166:169], v[194:197], v[96:99]
	v_mfma_f32_16x16x32_bf16 v[84:87], v[144:147], v[202:205], v[84:87]
	v_mfma_f32_16x16x32_bf16 v[80:83], v[166:169], v[202:205], v[80:83]
	v_mfma_f32_16x16x32_bf16 v[68:71], v[144:147], v[210:213], v[68:71]
	v_mfma_f32_16x16x32_bf16 v[64:67], v[166:169], v[210:213], v[64:67]
	v_mfma_f32_16x16x32_bf16 v[116:119], v[148:151], v[178:181], v[116:119]
	v_mfma_f32_16x16x32_bf16 v[112:115], v[170:173], v[178:181], v[112:115]
	v_mfma_f32_16x16x32_bf16 v[100:103], v[148:151], v[198:201], v[100:103]
	v_mfma_f32_16x16x32_bf16 v[96:99], v[170:173], v[198:201], v[96:99]
	v_mfma_f32_16x16x32_bf16 v[84:87], v[148:151], v[206:209], v[84:87]
	v_mfma_f32_16x16x32_bf16 v[80:83], v[170:173], v[206:209], v[80:83]
	v_mfma_f32_16x16x32_bf16 v[68:71], v[148:151], v[214:217], v[68:71]
	v_mfma_f32_16x16x32_bf16 v[64:67], v[170:173], v[214:217], v[64:67]
	s_barrier
	s_setprio 0
	s_add_i32 s3, s3, s33
	s_mov_b32 m0, s3
	ds_read_b128 v[174:177], v190 offset:49152
	ds_read_b128 v[178:181], v190 offset:50176
	ds_read_b128 v[194:197], v190 offset:51200
	ds_read_b128 v[198:201], v190 offset:52224
	ds_read_b128 v[202:205], v190 offset:53248
	ds_read_b128 v[206:209], v190 offset:54272
	ds_read_b128 v[210:213], v190 offset:55296
	ds_read_b128 v[214:217], v190 offset:56320
	global_load_lds_dwordx4 v154, s[98:99]
	s_add_i32 m0, s3, 0x2000
	s_add_u32 s38, s42, 0x158080
	s_addc_u32 s39, s43, 0
	s_add_i32 s3, s73, s33
	global_load_lds_dwordx4 v158, s[98:99]
	s_mov_b32 m0, s3
	s_nop 0
	global_load_lds_dwordx4 v154, s[38:39]
	s_add_i32 m0, s3, 0x2000
	s_nop 0
	global_load_lds_dwordx4 v158, s[38:39]
	s_mov_b32 m0, s56
	s_nop 0
	global_load_lds_dwordx4 v152, s[100:101]
	s_mov_b32 m0, s57
	s_nop 0
	global_load_lds_dwordx4 v156, s[100:101]
	s_waitcnt vmcnt(8)
	s_waitcnt lgkmcnt(0)
	s_setprio 1
	s_barrier
	v_mfma_f32_16x16x32_bf16 v[60:63], v[128:131], v[174:177], v[60:63]
	v_mfma_f32_16x16x32_bf16 v[56:59], v[136:139], v[174:177], v[56:59]
	v_mfma_f32_16x16x32_bf16 v[44:47], v[128:131], v[194:197], v[44:47]
	v_mfma_f32_16x16x32_bf16 v[40:43], v[136:139], v[194:197], v[40:43]
	v_mfma_f32_16x16x32_bf16 v[28:31], v[128:131], v[202:205], v[28:31]
	v_mfma_f32_16x16x32_bf16 v[24:27], v[136:139], v[202:205], v[24:27]
	v_mfma_f32_16x16x32_bf16 v[12:15], v[128:131], v[210:213], v[12:15]
	v_mfma_f32_16x16x32_bf16 v[8:11], v[136:139], v[210:213], v[8:11]
	v_mfma_f32_16x16x32_bf16 v[60:63], v[132:135], v[178:181], v[60:63]
	v_mfma_f32_16x16x32_bf16 v[56:59], v[140:143], v[178:181], v[56:59]
	v_mfma_f32_16x16x32_bf16 v[44:47], v[132:135], v[198:201], v[44:47]
	v_mfma_f32_16x16x32_bf16 v[40:43], v[140:143], v[198:201], v[40:43]
	v_mfma_f32_16x16x32_bf16 v[28:31], v[132:135], v[206:209], v[28:31]
	v_mfma_f32_16x16x32_bf16 v[24:27], v[140:143], v[206:209], v[24:27]
	v_mfma_f32_16x16x32_bf16 v[12:15], v[132:135], v[214:217], v[12:15]
	v_mfma_f32_16x16x32_bf16 v[8:11], v[140:143], v[214:217], v[8:11]
	v_mfma_f32_16x16x32_bf16 v[52:55], v[144:147], v[174:177], v[52:55]
	v_mfma_f32_16x16x32_bf16 v[48:51], v[166:169], v[174:177], v[48:51]
	v_mfma_f32_16x16x32_bf16 v[36:39], v[144:147], v[194:197], v[36:39]
	v_mfma_f32_16x16x32_bf16 v[32:35], v[166:169], v[194:197], v[32:35]
	v_mfma_f32_16x16x32_bf16 v[20:23], v[144:147], v[202:205], v[20:23]
	v_mfma_f32_16x16x32_bf16 v[16:19], v[166:169], v[202:205], v[16:19]
	v_mfma_f32_16x16x32_bf16 v[4:7], v[144:147], v[210:213], v[4:7]
	v_mfma_f32_16x16x32_bf16 v[0:3], v[166:169], v[210:213], v[0:3]
	v_mfma_f32_16x16x32_bf16 v[52:55], v[148:151], v[178:181], v[52:55]
	v_mfma_f32_16x16x32_bf16 v[48:51], v[170:173], v[178:181], v[48:51]
	v_mfma_f32_16x16x32_bf16 v[36:39], v[148:151], v[198:201], v[36:39]
	v_mfma_f32_16x16x32_bf16 v[32:35], v[170:173], v[198:201], v[32:35]
	v_mfma_f32_16x16x32_bf16 v[20:23], v[148:151], v[206:209], v[20:23]
	v_mfma_f32_16x16x32_bf16 v[16:19], v[170:173], v[206:209], v[16:19]
	v_mfma_f32_16x16x32_bf16 v[4:7], v[148:151], v[214:217], v[4:7]
	v_mfma_f32_16x16x32_bf16 v[0:3], v[170:173], v[214:217], v[0:3]
	s_barrier
	s_setprio 0
	s_add_i32 s1, s1, 2
	s_add_u32 s4, s4, 0x100
	s_addc_u32 s5, s5, 0
	s_cmpk_gt_u32 s1, 0x53
	s_mov_b64 s[38:39], s[40:41]
.LBB0_876:
	ds_read_b128 v[128:131], v188
	ds_read_b128 v[132:135], v188 offset:1024
	ds_read_b128 v[136:139], v188 offset:2048
	ds_read_b128 v[140:143], v188 offset:3072
	ds_read_b128 v[144:147], v189
	ds_read_b128 v[148:151], v189 offset:1024
	ds_read_b128 v[166:169], v189 offset:2048
	ds_read_b128 v[170:173], v189 offset:3072
	s_add_u32 s40, s38, 0x100
	s_addc_u32 s41, s39, 0
	s_cmpk_eq_i32 s1, 0x52
	s_cselect_b32 s45, s37, s41
	s_cselect_b32 s44, s36, s40
	s_cselect_b32 s43, s17, s5
	s_cselect_b32 s42, s16, s4
	s_add_i32 m0, s48, 0xc000
	ds_read_b128 v[174:177], v190
	ds_read_b128 v[178:181], v190 offset:1024
	ds_read_b128 v[194:197], v190 offset:2048
	ds_read_b128 v[198:201], v190 offset:3072
	ds_read_b128 v[202:205], v190 offset:4096
	ds_read_b128 v[206:209], v190 offset:5120
	ds_read_b128 v[210:213], v190 offset:6144
	ds_read_b128 v[214:217], v190 offset:7168
	global_load_lds_dwordx4 v160, s[38:39]
	s_add_i32 m0, s48, 0xe000
	s_nop 0
	global_load_lds_dwordx4 v162, s[38:39]
	s_waitcnt vmcnt(8)
	s_waitcnt lgkmcnt(0)
	s_setprio 1
	s_barrier
	v_mfma_f32_16x16x32_bf16 v[124:127], v[128:131], v[174:177], v[124:127]
	v_mfma_f32_16x16x32_bf16 v[120:123], v[136:139], v[174:177], v[120:123]
	v_mfma_f32_16x16x32_bf16 v[108:111], v[128:131], v[194:197], v[108:111]
	v_mfma_f32_16x16x32_bf16 v[104:107], v[136:139], v[194:197], v[104:107]
	v_mfma_f32_16x16x32_bf16 v[92:95], v[128:131], v[202:205], v[92:95]
	v_mfma_f32_16x16x32_bf16 v[88:91], v[136:139], v[202:205], v[88:91]
	v_mfma_f32_16x16x32_bf16 v[76:79], v[128:131], v[210:213], v[76:79]
	v_mfma_f32_16x16x32_bf16 v[72:75], v[136:139], v[210:213], v[72:75]
	v_mfma_f32_16x16x32_bf16 v[124:127], v[132:135], v[178:181], v[124:127]
	v_mfma_f32_16x16x32_bf16 v[120:123], v[140:143], v[178:181], v[120:123]
	v_mfma_f32_16x16x32_bf16 v[108:111], v[132:135], v[198:201], v[108:111]
	v_mfma_f32_16x16x32_bf16 v[104:107], v[140:143], v[198:201], v[104:107]
	v_mfma_f32_16x16x32_bf16 v[92:95], v[132:135], v[206:209], v[92:95]
	v_mfma_f32_16x16x32_bf16 v[88:91], v[140:143], v[206:209], v[88:91]
	v_mfma_f32_16x16x32_bf16 v[76:79], v[132:135], v[214:217], v[76:79]
	v_mfma_f32_16x16x32_bf16 v[72:75], v[140:143], v[214:217], v[72:75]
	v_mfma_f32_16x16x32_bf16 v[116:119], v[144:147], v[174:177], v[116:119]
	v_mfma_f32_16x16x32_bf16 v[112:115], v[166:169], v[174:177], v[112:115]
	v_mfma_f32_16x16x32_bf16 v[100:103], v[144:147], v[194:197], v[100:103]
	v_mfma_f32_16x16x32_bf16 v[96:99], v[166:169], v[194:197], v[96:99]
	v_mfma_f32_16x16x32_bf16 v[84:87], v[144:147], v[202:205], v[84:87]
	v_mfma_f32_16x16x32_bf16 v[80:83], v[166:169], v[202:205], v[80:83]
	v_mfma_f32_16x16x32_bf16 v[68:71], v[144:147], v[210:213], v[68:71]
	v_mfma_f32_16x16x32_bf16 v[64:67], v[166:169], v[210:213], v[64:67]
	v_mfma_f32_16x16x32_bf16 v[116:119], v[148:151], v[178:181], v[116:119]
	v_mfma_f32_16x16x32_bf16 v[112:115], v[170:173], v[178:181], v[112:115]
	v_mfma_f32_16x16x32_bf16 v[100:103], v[148:151], v[198:201], v[100:103]
	v_mfma_f32_16x16x32_bf16 v[96:99], v[170:173], v[198:201], v[96:99]
	v_mfma_f32_16x16x32_bf16 v[84:87], v[148:151], v[206:209], v[84:87]
	v_mfma_f32_16x16x32_bf16 v[80:83], v[170:173], v[206:209], v[80:83]
	v_mfma_f32_16x16x32_bf16 v[68:71], v[148:151], v[214:217], v[68:71]
	v_mfma_f32_16x16x32_bf16 v[64:67], v[170:173], v[214:217], v[64:67]
	s_barrier
	s_setprio 0
	s_add_i32 s3, s70, s33
	s_add_u32 s98, s42, s24
	s_addc_u32 s99, s43, s25
	s_mov_b32 m0, s3
	ds_read_b128 v[174:177], v190 offset:16384
	ds_read_b128 v[178:181], v190 offset:17408
	ds_read_b128 v[194:197], v190 offset:18432
	ds_read_b128 v[198:201], v190 offset:19456
	ds_read_b128 v[202:205], v190 offset:20480
	ds_read_b128 v[206:209], v190 offset:21504
	ds_read_b128 v[210:213], v190 offset:22528
	ds_read_b128 v[214:217], v190 offset:23552
	global_load_lds_dwordx4 v154, s[42:43]
	s_add_i32 m0, s3, 0x2000
	s_add_u32 s38, s42, 0x158000
	s_addc_u32 s39, s43, 0
	s_add_i32 s3, s71, s33
	global_load_lds_dwordx4 v158, s[42:43]
	s_mov_b32 m0, s3
	s_add_u32 s100, s44, s24
	s_addc_u32 s101, s45, s25
	global_load_lds_dwordx4 v154, s[38:39]
	s_add_i32 m0, s3, 0x2000
	s_nop 0
	global_load_lds_dwordx4 v158, s[38:39]
	s_mov_b32 m0, s48
	s_nop 0
	global_load_lds_dwordx4 v152, s[44:45]
	s_mov_b32 m0, s49
	s_nop 0
	global_load_lds_dwordx4 v156, s[44:45]
	s_waitcnt vmcnt(8)
	s_waitcnt lgkmcnt(0)
	s_setprio 1
	s_barrier
	v_mfma_f32_16x16x32_bf16 v[60:63], v[128:131], v[174:177], v[60:63]
	v_mfma_f32_16x16x32_bf16 v[56:59], v[136:139], v[174:177], v[56:59]
	v_mfma_f32_16x16x32_bf16 v[44:47], v[128:131], v[194:197], v[44:47]
	v_mfma_f32_16x16x32_bf16 v[40:43], v[136:139], v[194:197], v[40:43]
	v_mfma_f32_16x16x32_bf16 v[28:31], v[128:131], v[202:205], v[28:31]
	v_mfma_f32_16x16x32_bf16 v[24:27], v[136:139], v[202:205], v[24:27]
	v_mfma_f32_16x16x32_bf16 v[12:15], v[128:131], v[210:213], v[12:15]
	v_mfma_f32_16x16x32_bf16 v[8:11], v[136:139], v[210:213], v[8:11]
	v_mfma_f32_16x16x32_bf16 v[60:63], v[132:135], v[178:181], v[60:63]
	v_mfma_f32_16x16x32_bf16 v[56:59], v[140:143], v[178:181], v[56:59]
	v_mfma_f32_16x16x32_bf16 v[44:47], v[132:135], v[198:201], v[44:47]
	v_mfma_f32_16x16x32_bf16 v[40:43], v[140:143], v[198:201], v[40:43]
	v_mfma_f32_16x16x32_bf16 v[28:31], v[132:135], v[206:209], v[28:31]
	v_mfma_f32_16x16x32_bf16 v[24:27], v[140:143], v[206:209], v[24:27]
	v_mfma_f32_16x16x32_bf16 v[12:15], v[132:135], v[214:217], v[12:15]
	v_mfma_f32_16x16x32_bf16 v[8:11], v[140:143], v[214:217], v[8:11]
	v_mfma_f32_16x16x32_bf16 v[52:55], v[144:147], v[174:177], v[52:55]
	v_mfma_f32_16x16x32_bf16 v[48:51], v[166:169], v[174:177], v[48:51]
	v_mfma_f32_16x16x32_bf16 v[36:39], v[144:147], v[194:197], v[36:39]
	v_mfma_f32_16x16x32_bf16 v[32:35], v[166:169], v[194:197], v[32:35]
	v_mfma_f32_16x16x32_bf16 v[20:23], v[144:147], v[202:205], v[20:23]
	v_mfma_f32_16x16x32_bf16 v[16:19], v[166:169], v[202:205], v[16:19]
	v_mfma_f32_16x16x32_bf16 v[4:7], v[144:147], v[210:213], v[4:7]
	v_mfma_f32_16x16x32_bf16 v[0:3], v[166:169], v[210:213], v[0:3]
	v_mfma_f32_16x16x32_bf16 v[52:55], v[148:151], v[178:181], v[52:55]
	v_mfma_f32_16x16x32_bf16 v[48:51], v[170:173], v[178:181], v[48:51]
	v_mfma_f32_16x16x32_bf16 v[36:39], v[148:151], v[198:201], v[36:39]
	v_mfma_f32_16x16x32_bf16 v[32:35], v[170:173], v[198:201], v[32:35]
	v_mfma_f32_16x16x32_bf16 v[20:23], v[148:151], v[206:209], v[20:23]
	v_mfma_f32_16x16x32_bf16 v[16:19], v[170:173], v[206:209], v[16:19]
	v_mfma_f32_16x16x32_bf16 v[4:7], v[148:151], v[214:217], v[4:7]
	v_mfma_f32_16x16x32_bf16 v[0:3], v[170:173], v[214:217], v[0:3]
	s_barrier
	s_setprio 0
	s_add_i32 s3, 0, 0x18000
	s_add_i32 s73, 0, 0x1c000
	v_add_u32_e32 v140, s3, v187
	v_add_u32_e32 v170, s73, v187
	ds_read_b128 v[128:131], v140
	ds_read_b128 v[132:135], v140 offset:1024
	ds_read_b128 v[136:139], v140 offset:2048
	ds_read_b128 v[140:143], v140 offset:3072
	ds_read_b128 v[144:147], v170
	ds_read_b128 v[148:151], v170 offset:1024
	ds_read_b128 v[166:169], v170 offset:2048
	ds_read_b128 v[170:173], v170 offset:3072
	s_add_u32 s38, s44, 0x158000
	s_addc_u32 s39, s45, 0
	s_mov_b32 m0, s51
	ds_read_b128 v[174:177], v190 offset:32768
	ds_read_b128 v[178:181], v190 offset:33792
	ds_read_b128 v[194:197], v190 offset:34816
	ds_read_b128 v[198:201], v190 offset:35840
	ds_read_b128 v[202:205], v190 offset:36864
	ds_read_b128 v[206:209], v190 offset:37888
	ds_read_b128 v[210:213], v190 offset:38912
	ds_read_b128 v[214:217], v190 offset:39936
	global_load_lds_dwordx4 v152, s[38:39]
	s_mov_b32 m0, s52
	s_nop 0
	global_load_lds_dwordx4 v156, s[38:39]
	s_waitcnt vmcnt(8)
	s_waitcnt lgkmcnt(0)
	s_setprio 1
	s_barrier
	v_mfma_f32_16x16x32_bf16 v[124:127], v[128:131], v[174:177], v[124:127]
	v_mfma_f32_16x16x32_bf16 v[120:123], v[136:139], v[174:177], v[120:123]
	v_mfma_f32_16x16x32_bf16 v[108:111], v[128:131], v[194:197], v[108:111]
	v_mfma_f32_16x16x32_bf16 v[104:107], v[136:139], v[194:197], v[104:107]
	v_mfma_f32_16x16x32_bf16 v[92:95], v[128:131], v[202:205], v[92:95]
	v_mfma_f32_16x16x32_bf16 v[88:91], v[136:139], v[202:205], v[88:91]
	v_mfma_f32_16x16x32_bf16 v[76:79], v[128:131], v[210:213], v[76:79]
	v_mfma_f32_16x16x32_bf16 v[72:75], v[136:139], v[210:213], v[72:75]
	v_mfma_f32_16x16x32_bf16 v[124:127], v[132:135], v[178:181], v[124:127]
	v_mfma_f32_16x16x32_bf16 v[120:123], v[140:143], v[178:181], v[120:123]
	v_mfma_f32_16x16x32_bf16 v[108:111], v[132:135], v[198:201], v[108:111]
	v_mfma_f32_16x16x32_bf16 v[104:107], v[140:143], v[198:201], v[104:107]
	v_mfma_f32_16x16x32_bf16 v[92:95], v[132:135], v[206:209], v[92:95]
	v_mfma_f32_16x16x32_bf16 v[88:91], v[140:143], v[206:209], v[88:91]
	v_mfma_f32_16x16x32_bf16 v[76:79], v[132:135], v[214:217], v[76:79]
	v_mfma_f32_16x16x32_bf16 v[72:75], v[140:143], v[214:217], v[72:75]
	v_mfma_f32_16x16x32_bf16 v[116:119], v[144:147], v[174:177], v[116:119]
	v_mfma_f32_16x16x32_bf16 v[112:115], v[166:169], v[174:177], v[112:115]
	v_mfma_f32_16x16x32_bf16 v[100:103], v[144:147], v[194:197], v[100:103]
	v_mfma_f32_16x16x32_bf16 v[96:99], v[166:169], v[194:197], v[96:99]
	v_mfma_f32_16x16x32_bf16 v[84:87], v[144:147], v[202:205], v[84:87]
	v_mfma_f32_16x16x32_bf16 v[80:83], v[166:169], v[202:205], v[80:83]
	v_mfma_f32_16x16x32_bf16 v[68:71], v[144:147], v[210:213], v[68:71]
	v_mfma_f32_16x16x32_bf16 v[64:67], v[166:169], v[210:213], v[64:67]
	v_mfma_f32_16x16x32_bf16 v[116:119], v[148:151], v[178:181], v[116:119]
	v_mfma_f32_16x16x32_bf16 v[112:115], v[170:173], v[178:181], v[112:115]
	v_mfma_f32_16x16x32_bf16 v[100:103], v[148:151], v[198:201], v[100:103]
	v_mfma_f32_16x16x32_bf16 v[96:99], v[170:173], v[198:201], v[96:99]
	v_mfma_f32_16x16x32_bf16 v[84:87], v[148:151], v[206:209], v[84:87]
	v_mfma_f32_16x16x32_bf16 v[80:83], v[170:173], v[206:209], v[80:83]
	v_mfma_f32_16x16x32_bf16 v[68:71], v[148:151], v[214:217], v[68:71]
	v_mfma_f32_16x16x32_bf16 v[64:67], v[170:173], v[214:217], v[64:67]
	s_barrier
	s_setprio 0
	s_add_i32 s3, s3, s33
	s_mov_b32 m0, s3
	ds_read_b128 v[174:177], v190 offset:49152
	ds_read_b128 v[178:181], v190 offset:50176
	ds_read_b128 v[194:197], v190 offset:51200
	ds_read_b128 v[198:201], v190 offset:52224
	ds_read_b128 v[202:205], v190 offset:53248
	ds_read_b128 v[206:209], v190 offset:54272
	ds_read_b128 v[210:213], v190 offset:55296
	ds_read_b128 v[214:217], v190 offset:56320
	global_load_lds_dwordx4 v154, s[98:99]
	s_add_i32 m0, s3, 0x2000
	s_add_u32 s38, s42, 0x158080
	s_addc_u32 s39, s43, 0
	s_add_i32 s3, s73, s33
	global_load_lds_dwordx4 v158, s[98:99]
	s_mov_b32 m0, s3
	s_nop 0
	global_load_lds_dwordx4 v154, s[38:39]
	s_add_i32 m0, s3, 0x2000
	s_nop 0
	global_load_lds_dwordx4 v158, s[38:39]
	s_mov_b32 m0, s56
	s_nop 0
	global_load_lds_dwordx4 v152, s[100:101]
	s_mov_b32 m0, s57
	s_nop 0
	global_load_lds_dwordx4 v156, s[100:101]
	s_waitcnt vmcnt(8)
	s_waitcnt lgkmcnt(0)
	s_setprio 1
	s_barrier
	v_mfma_f32_16x16x32_bf16 v[60:63], v[128:131], v[174:177], v[60:63]
	v_mfma_f32_16x16x32_bf16 v[56:59], v[136:139], v[174:177], v[56:59]
	v_mfma_f32_16x16x32_bf16 v[44:47], v[128:131], v[194:197], v[44:47]
	v_mfma_f32_16x16x32_bf16 v[40:43], v[136:139], v[194:197], v[40:43]
	v_mfma_f32_16x16x32_bf16 v[28:31], v[128:131], v[202:205], v[28:31]
	v_mfma_f32_16x16x32_bf16 v[24:27], v[136:139], v[202:205], v[24:27]
	v_mfma_f32_16x16x32_bf16 v[12:15], v[128:131], v[210:213], v[12:15]
	v_mfma_f32_16x16x32_bf16 v[8:11], v[136:139], v[210:213], v[8:11]
	v_mfma_f32_16x16x32_bf16 v[60:63], v[132:135], v[178:181], v[60:63]
	v_mfma_f32_16x16x32_bf16 v[56:59], v[140:143], v[178:181], v[56:59]
	v_mfma_f32_16x16x32_bf16 v[44:47], v[132:135], v[198:201], v[44:47]
	v_mfma_f32_16x16x32_bf16 v[40:43], v[140:143], v[198:201], v[40:43]
	v_mfma_f32_16x16x32_bf16 v[28:31], v[132:135], v[206:209], v[28:31]
	v_mfma_f32_16x16x32_bf16 v[24:27], v[140:143], v[206:209], v[24:27]
	v_mfma_f32_16x16x32_bf16 v[12:15], v[132:135], v[214:217], v[12:15]
	v_mfma_f32_16x16x32_bf16 v[8:11], v[140:143], v[214:217], v[8:11]
	v_mfma_f32_16x16x32_bf16 v[52:55], v[144:147], v[174:177], v[52:55]
	v_mfma_f32_16x16x32_bf16 v[48:51], v[166:169], v[174:177], v[48:51]
	v_mfma_f32_16x16x32_bf16 v[36:39], v[144:147], v[194:197], v[36:39]
	v_mfma_f32_16x16x32_bf16 v[32:35], v[166:169], v[194:197], v[32:35]
	v_mfma_f32_16x16x32_bf16 v[20:23], v[144:147], v[202:205], v[20:23]
	v_mfma_f32_16x16x32_bf16 v[16:19], v[166:169], v[202:205], v[16:19]
	v_mfma_f32_16x16x32_bf16 v[4:7], v[144:147], v[210:213], v[4:7]
	v_mfma_f32_16x16x32_bf16 v[0:3], v[166:169], v[210:213], v[0:3]
	v_mfma_f32_16x16x32_bf16 v[52:55], v[148:151], v[178:181], v[52:55]
	v_mfma_f32_16x16x32_bf16 v[48:51], v[170:173], v[178:181], v[48:51]
	v_mfma_f32_16x16x32_bf16 v[36:39], v[148:151], v[198:201], v[36:39]
	v_mfma_f32_16x16x32_bf16 v[32:35], v[170:173], v[198:201], v[32:35]
	v_mfma_f32_16x16x32_bf16 v[20:23], v[148:151], v[206:209], v[20:23]
	v_mfma_f32_16x16x32_bf16 v[16:19], v[170:173], v[206:209], v[16:19]
	v_mfma_f32_16x16x32_bf16 v[4:7], v[148:151], v[214:217], v[4:7]
	v_mfma_f32_16x16x32_bf16 v[0:3], v[170:173], v[214:217], v[0:3]
	s_barrier
	s_setprio 0
	s_add_i32 s1, s1, 2
	s_add_u32 s4, s4, 0x100
	s_addc_u32 s5, s5, 0
	s_cmpk_gt_u32 s1, 0x53
	s_mov_b64 s[38:39], s[40:41]
	s_cbranch_scc0 .LBB0_876
	s_and_b64 vcc, exec, s[26:27]
	s_cbranch_vccz .LBB0_879
	s_barrier
